# G1 K-loop LDS-DMA issue spread through MFMAs + G2 gate-ratio epilogue: 32 serial MGA/MGB loads prefetched through a 12-quad register ring with counted vmcnt
# speedup vs baseline: 1.0158x; 1.0158x over previous
; #define WAIT_V0() asm volatile("s_waitcnt vmcnt(0)" ::: "memory")
; DI void gemm_core(const int tid, const u16* __restrict__ Wb, int ldw, const u16* __restrict__ Xb, int ldx, int K, f32x4 (&acc)[8][4], const bool pre = false) {
;     ...
;   auto stage = [&](int buf, int kt) {
; #pragma unroll
;     for (int i = 0; i < 4; ++i) {
;       __builtin_amdgcn_global_load_lds((const unsigned*)(Wb + offw[i] + kt * 64), (unsigned*)(shm + buf * STAGE_B + wid * 1024 + i * 8192), 16, 0, 0);
;       __builtin_amdgcn_global_load_lds((const unsigned*)(Xb + offx[i] + kt * 64), (unsigned*)(shm + buf * STAGE_B + TILE_B + wid * 1024 + i * 8192), 16, 0, 0);
;     }
;   };
;   const int nt = K >> 6;
;   if (!pre) stage(0, 0);
;   WAIT_V0(); __syncthreads();
;   for (int t = 0; t < nt; ++t) {
;     const int cur = t & 1;
;     if (t + 1 < nt) stage(cur ^ 1, t + 1);
; #pragma unroll
;     for (int ks = 0; ks < 2; ++ks) {
;       bf16x8 At[8], Bf[4];
;       const char* pb = shm + cur * STAGE_B + TILE_B + lds_byte(wc * 64 + fr, fq * 8) + ks * 1024;
;       const char* pa = shm + cur * STAGE_B + lds_byte(wr * 128 + fr, fq * 8) + ks * 1024;
; #pragma unroll
;       for (int n = 0; n < 4; ++n) Bf[n] = *(const bf16x8*)(pb + n * 2048);
; #pragma unroll
;       for (int m = 0; m < 8; ++m) At[m] = *(const bf16x8*)(pa + m * 2048);
; #pragma unroll
;       for (int m = 0; m < 8; ++m)
; #pragma unroll
;         for (int n = 0; n < 4; ++n)
;           acc[m][n] = __builtin_amdgcn_mfma_f32_16x16x32_bf16(At[m], Bf[n], acc[m][n], 0, 0, 0);
;       __builtin_amdgcn_sched_group_barrier(0x100, 5, 0);
; #pragma unroll
;       for (int m = 0; m < 8; ++m) {
;         __builtin_amdgcn_sched_group_barrier(0x008, 1, 0);
;         if (m < 7) __builtin_amdgcn_sched_group_barrier(0x100, 1, 0);
;         __builtin_amdgcn_sched_group_barrier(0x008, 3, 0);
;       }
;       __builtin_amdgcn_sched_barrier(0);
;     }
;     WAIT_V0(); __syncthreads();
.LBB0_219:
	s_and_b32 s21, s17, 0x10000
	s_xor_b32 s72, s21, 0x10000
	s_add_i32 s72, s1, s72
	v_lshl_add_u64 v[150:151], v[144:145], 0, s[30:31]
	s_mov_b32 m0, s72
	s_nop 0
	global_load_lds_dwordx4 v[150:151], off
	v_lshl_add_u64 v[150:151], v[142:143], 0, s[30:31]
	s_add_i32 m0, s72, 0x8000
	s_nop 0
	global_load_lds_dwordx4 v[150:151], off
	v_lshl_add_u64 v[150:151], v[140:141], 0, s[30:31]
	s_add_i32 m0, s72, 0x2000
	s_nop 0
	global_load_lds_dwordx4 v[150:151], off
	v_lshl_add_u64 v[150:151], v[138:139], 0, s[30:31]
	s_add_i32 m0, s72, 0xa000
	s_nop 0
	global_load_lds_dwordx4 v[150:151], off
	v_lshl_add_u64 v[150:151], v[136:137], 0, s[30:31]
	s_add_i32 m0, s72, 0x4000
	s_nop 0
	global_load_lds_dwordx4 v[150:151], off
	v_lshl_add_u64 v[150:151], v[134:135], 0, s[30:31]
	s_add_i32 m0, s72, 0xc000
	s_nop 0
	global_load_lds_dwordx4 v[150:151], off
	v_lshl_add_u64 v[150:151], v[132:133], 0, s[30:31]
	s_add_i32 m0, s72, 0x6000
	s_nop 0
	global_load_lds_dwordx4 v[150:151], off
	v_lshl_add_u64 v[150:151], v[130:131], 0, s[30:31]
	s_add_i32 m0, s72, 0xe000
	s_add_i32 s72, s15, s21
	global_load_lds_dwordx4 v[150:151], off
	v_add_u32_e32 v0, s72, v146
	ds_read_b128 v[150:153], v0
	s_or_b32 s21, s13, s21
	v_add_u32_e32 v174, s21, v146
	ds_read_b128 v[154:157], v174 offset:32768
	ds_read_b128 v[158:161], v174 offset:34816
	ds_read_b128 v[162:165], v174 offset:36864
	ds_read_b128 v[166:169], v174 offset:38912
	s_waitcnt lgkmcnt(0)
	v_mfma_f32_16x16x32_bf16 v[6:9], v[150:153], v[154:157], v[6:9]
	ds_read_b128 v[170:173], v0 offset:2048
	v_mfma_f32_16x16x32_bf16 v[14:17], v[150:153], v[158:161], v[14:17]
	v_mfma_f32_16x16x32_bf16 v[22:25], v[150:153], v[162:165], v[22:25]
	v_mfma_f32_16x16x32_bf16 v[30:33], v[150:153], v[166:169], v[30:33]
	s_waitcnt lgkmcnt(0)
	v_mfma_f32_16x16x32_bf16 v[18:21], v[170:173], v[154:157], v[18:21]
	ds_read_b128 v[150:153], v0 offset:4096
	v_mfma_f32_16x16x32_bf16 v[26:29], v[170:173], v[158:161], v[26:29]
	v_mfma_f32_16x16x32_bf16 v[38:41], v[170:173], v[162:165], v[38:41]
	v_mfma_f32_16x16x32_bf16 v[46:49], v[170:173], v[166:169], v[46:49]
	s_waitcnt lgkmcnt(0)
	v_mfma_f32_16x16x32_bf16 v[34:37], v[150:153], v[154:157], v[34:37]
	ds_read_b128 v[170:173], v0 offset:6144
	v_mfma_f32_16x16x32_bf16 v[42:45], v[150:153], v[158:161], v[42:45]
	v_mfma_f32_16x16x32_bf16 v[54:57], v[150:153], v[162:165], v[54:57]
	v_mfma_f32_16x16x32_bf16 v[62:65], v[150:153], v[166:169], v[62:65]
	s_waitcnt lgkmcnt(0)
	v_mfma_f32_16x16x32_bf16 v[50:53], v[170:173], v[154:157], v[50:53]
	ds_read_b128 v[150:153], v0 offset:8192
	v_mfma_f32_16x16x32_bf16 v[58:61], v[170:173], v[158:161], v[58:61]
	v_mfma_f32_16x16x32_bf16 v[70:73], v[170:173], v[162:165], v[70:73]
	v_mfma_f32_16x16x32_bf16 v[74:77], v[170:173], v[166:169], v[74:77]
	s_waitcnt lgkmcnt(0)
	v_mfma_f32_16x16x32_bf16 v[66:69], v[150:153], v[154:157], v[66:69]
	ds_read_b128 v[170:173], v0 offset:10240
	v_mfma_f32_16x16x32_bf16 v[10:13], v[150:153], v[158:161], v[10:13]
	v_mfma_f32_16x16x32_bf16 v[2:5], v[150:153], v[162:165], v[2:5]
	v_mfma_f32_16x16x32_bf16 v[78:81], v[150:153], v[166:169], v[78:81]
	s_waitcnt lgkmcnt(0)
	v_mfma_f32_16x16x32_bf16 v[82:85], v[170:173], v[154:157], v[82:85]
	ds_read_b128 v[150:153], v0 offset:12288
	v_mfma_f32_16x16x32_bf16 v[86:89], v[170:173], v[158:161], v[86:89]
	v_mfma_f32_16x16x32_bf16 v[94:97], v[170:173], v[162:165], v[94:97]
	v_mfma_f32_16x16x32_bf16 v[98:101], v[170:173], v[166:169], v[98:101]
	s_waitcnt lgkmcnt(0)
	v_mfma_f32_16x16x32_bf16 v[90:93], v[150:153], v[154:157], v[90:93]
	ds_read_b128 v[170:173], v0 offset:14336
	v_mfma_f32_16x16x32_bf16 v[102:105], v[150:153], v[158:161], v[102:105]
	v_mfma_f32_16x16x32_bf16 v[122:125], v[150:153], v[162:165], v[122:125]
	v_mfma_f32_16x16x32_bf16 v[110:113], v[150:153], v[166:169], v[110:113]
	s_waitcnt lgkmcnt(0)
	v_mfma_f32_16x16x32_bf16 v[106:109], v[170:173], v[154:157], v[106:109]
	v_mfma_f32_16x16x32_bf16 v[114:117], v[170:173], v[158:161], v[114:117]
	v_mfma_f32_16x16x32_bf16 v[126:129], v[170:173], v[162:165], v[126:129]
	v_mfma_f32_16x16x32_bf16 v[118:121], v[170:173], v[166:169], v[118:121]
	ds_read_b128 v[150:153], v0 offset:1024
	ds_read_b128 v[154:157], v174 offset:33792
	ds_read_b128 v[158:161], v174 offset:35840
	ds_read_b128 v[162:165], v174 offset:37888
	ds_read_b128 v[166:169], v174 offset:39936
	s_waitcnt lgkmcnt(0)
	v_mfma_f32_16x16x32_bf16 v[6:9], v[150:153], v[154:157], v[6:9]
	ds_read_b128 v[170:173], v0 offset:3072
	v_mfma_f32_16x16x32_bf16 v[14:17], v[150:153], v[158:161], v[14:17]
	v_mfma_f32_16x16x32_bf16 v[22:25], v[150:153], v[162:165], v[22:25]
	v_mfma_f32_16x16x32_bf16 v[30:33], v[150:153], v[166:169], v[30:33]
	s_waitcnt lgkmcnt(0)
	v_mfma_f32_16x16x32_bf16 v[18:21], v[170:173], v[154:157], v[18:21]
	ds_read_b128 v[150:153], v0 offset:5120
	v_mfma_f32_16x16x32_bf16 v[26:29], v[170:173], v[158:161], v[26:29]
	v_mfma_f32_16x16x32_bf16 v[38:41], v[170:173], v[162:165], v[38:41]
	v_mfma_f32_16x16x32_bf16 v[46:49], v[170:173], v[166:169], v[46:49]
	s_waitcnt lgkmcnt(0)
	v_mfma_f32_16x16x32_bf16 v[34:37], v[150:153], v[154:157], v[34:37]
	ds_read_b128 v[170:173], v0 offset:7168
	v_mfma_f32_16x16x32_bf16 v[42:45], v[150:153], v[158:161], v[42:45]
	v_mfma_f32_16x16x32_bf16 v[54:57], v[150:153], v[162:165], v[54:57]
	v_mfma_f32_16x16x32_bf16 v[62:65], v[150:153], v[166:169], v[62:65]
	s_waitcnt lgkmcnt(0)
	v_mfma_f32_16x16x32_bf16 v[50:53], v[170:173], v[154:157], v[50:53]
	ds_read_b128 v[150:153], v0 offset:9216
	v_mfma_f32_16x16x32_bf16 v[58:61], v[170:173], v[158:161], v[58:61]
	v_mfma_f32_16x16x32_bf16 v[70:73], v[170:173], v[162:165], v[70:73]
	v_mfma_f32_16x16x32_bf16 v[74:77], v[170:173], v[166:169], v[74:77]
	s_waitcnt lgkmcnt(0)
; #define WAIT_V0() asm volatile("s_waitcnt vmcnt(0)" ::: "memory")
; DI void gemm_core(const int tid, const u16* __restrict__ Wb, int ldw, const u16* __restrict__ Xb, int ldx, int K, f32x4 (&acc)[8][4], const bool pre = false) {
;     ...
;   for (int t = 0; t < nt; ++t) {
;     const int cur = t & 1;
;     if (t + 1 < nt) stage(cur ^ 1, t + 1);
; #pragma unroll
;     for (int ks = 0; ks < 2; ++ks) {
;       bf16x8 At[8], Bf[4];
;       const char* pb = shm + cur * STAGE_B + TILE_B + lds_byte(wc * 64 + fr, fq * 8) + ks * 1024;
;       const char* pa = shm + cur * STAGE_B + lds_byte(wr * 128 + fr, fq * 8) + ks * 1024;
; #pragma unroll
;       for (int n = 0; n < 4; ++n) Bf[n] = *(const bf16x8*)(pb + n * 2048);
; #pragma unroll
;       for (int m = 0; m < 8; ++m) At[m] = *(const bf16x8*)(pa + m * 2048);
; #pragma unroll
;       for (int m = 0; m < 8; ++m)
; #pragma unroll
;         for (int n = 0; n < 4; ++n)
;           acc[m][n] = __builtin_amdgcn_mfma_f32_16x16x32_bf16(At[m], Bf[n], acc[m][n], 0, 0, 0);
;       __builtin_amdgcn_sched_group_barrier(0x100, 5, 0);
; #pragma unroll
;       for (int m = 0; m < 8; ++m) {
;         __builtin_amdgcn_sched_group_barrier(0x008, 1, 0);
;         if (m < 7) __builtin_amdgcn_sched_group_barrier(0x100, 1, 0);
;         __builtin_amdgcn_sched_group_barrier(0x008, 3, 0);
;       }
;       __builtin_amdgcn_sched_barrier(0);
;     }
;     WAIT_V0(); __syncthreads();
	v_mfma_f32_16x16x32_bf16 v[66:69], v[150:153], v[154:157], v[66:69]
	ds_read_b128 v[170:173], v0 offset:11264
	v_mfma_f32_16x16x32_bf16 v[10:13], v[150:153], v[158:161], v[10:13]
	v_mfma_f32_16x16x32_bf16 v[2:5], v[150:153], v[162:165], v[2:5]
	v_mfma_f32_16x16x32_bf16 v[78:81], v[150:153], v[166:169], v[78:81]
	s_waitcnt lgkmcnt(0)
	v_mfma_f32_16x16x32_bf16 v[82:85], v[170:173], v[154:157], v[82:85]
	ds_read_b128 v[150:153], v0 offset:13312
	v_mfma_f32_16x16x32_bf16 v[86:89], v[170:173], v[158:161], v[86:89]
	v_mfma_f32_16x16x32_bf16 v[94:97], v[170:173], v[162:165], v[94:97]
	v_mfma_f32_16x16x32_bf16 v[98:101], v[170:173], v[166:169], v[98:101]
	s_waitcnt lgkmcnt(0)
	v_mfma_f32_16x16x32_bf16 v[90:93], v[150:153], v[154:157], v[90:93]
	ds_read_b128 v[170:173], v0 offset:15360
	v_mfma_f32_16x16x32_bf16 v[102:105], v[150:153], v[158:161], v[102:105]
	v_mfma_f32_16x16x32_bf16 v[122:125], v[150:153], v[162:165], v[122:125]
	v_mfma_f32_16x16x32_bf16 v[110:113], v[150:153], v[166:169], v[110:113]
	s_waitcnt lgkmcnt(0)
	v_mfma_f32_16x16x32_bf16 v[106:109], v[170:173], v[154:157], v[106:109]
	v_mfma_f32_16x16x32_bf16 v[114:117], v[170:173], v[158:161], v[114:117]
	v_mfma_f32_16x16x32_bf16 v[126:129], v[170:173], v[162:165], v[126:129]
	v_mfma_f32_16x16x32_bf16 v[118:121], v[170:173], v[166:169], v[118:121]
	s_add_i32 s17, s17, 0x10000
	s_waitcnt vmcnt(0)
	s_add_u32 s30, s30, 0x80
	s_addc_u32 s31, s31, 0
	s_cmpk_lg_i32 s30, 0x380
	s_waitcnt vmcnt(0)
	s_barrier
	s_cbranch_scc1 .LBB0_219
	v_add_u32_e32 v0, s15, v146
	v_add_u32_e32 v0, 0x10000, v0
	ds_read_b128 v[142:145], v0 offset:14336
	ds_read_b128 v[152:155], v0 offset:12288
	ds_read_b128 v[156:159], v0 offset:10240
	v_or_b32_e32 v150, 0x18000, v146
	v_add_u32_e32 v151, s13, v150
	ds_read_b128 v[160:163], v0 offset:8192
	ds_read_b128 v[164:167], v0 offset:6144
	ds_read_b128 v[168:171], v151 offset:4096
	s_waitcnt lgkmcnt(0)
	v_mfma_f32_16x16x32_bf16 v[130:133], v[142:145], v[168:171], v[126:129]
	v_mfma_f32_16x16x32_bf16 v[134:137], v[152:155], v[168:171], v[122:125]
	v_mfma_f32_16x16x32_bf16 v[176:179], v[156:159], v[168:171], v[94:97]
	s_nop 1
	ds_read_b128 v[122:125], v151 offset:2048
	s_waitcnt lgkmcnt(0)
	v_mfma_f32_16x16x32_bf16 v[10:13], v[160:163], v[122:125], v[10:13]
	ds_read_b128 v[126:129], v0 offset:4096
	s_waitcnt lgkmcnt(0)
	v_mfma_f32_16x16x32_bf16 v[54:57], v[126:129], v[168:171], v[54:57]
	ds_read_b128 v[94:97], v151
	s_waitcnt lgkmcnt(0)
	v_mfma_f32_16x16x32_bf16 v[34:37], v[126:129], v[94:97], v[34:37]
	v_mfma_f32_16x16x32_bf16 v[50:53], v[164:167], v[94:97], v[50:53]
	v_mfma_f32_16x16x32_bf16 v[172:175], v[142:145], v[122:125], v[114:117]
	v_mfma_f32_16x16x32_bf16 v[184:187], v[152:155], v[122:125], v[102:105]
	s_nop 1
	ds_read_b128 v[114:117], v151 offset:6144
	s_waitcnt lgkmcnt(0)
	v_mfma_f32_16x16x32_bf16 v[110:113], v[152:155], v[114:117], v[110:113]
	v_mfma_f32_16x16x32_bf16 v[138:141], v[142:145], v[114:117], v[118:121]
	v_mfma_f32_16x16x32_bf16 v[180:183], v[156:159], v[114:117], v[98:101]
	s_nop 1
	ds_read_b128 v[118:121], v0 offset:2048
	s_waitcnt lgkmcnt(0)
	v_mfma_f32_16x16x32_bf16 v[18:21], v[118:121], v[94:97], v[18:21]
	v_mfma_f32_16x16x32_bf16 v[142:145], v[142:145], v[94:97], v[106:109]
	v_mfma_f32_16x16x32_bf16 v[82:85], v[156:159], v[94:97], v[82:85]
	v_mfma_f32_16x16x32_bf16 v[152:155], v[152:155], v[94:97], v[90:93]
	ds_read_b128 v[98:101], v0
	s_waitcnt lgkmcnt(0)
	v_mfma_f32_16x16x32_bf16 v[6:9], v[98:101], v[94:97], v[6:9]
	v_mfma_f32_16x16x32_bf16 v[94:97], v[160:163], v[94:97], v[66:69]
	v_mfma_f32_16x16x32_bf16 v[86:89], v[156:159], v[122:125], v[86:89]
	v_mfma_f32_16x16x32_bf16 v[102:105], v[164:167], v[168:171], v[70:73]
	v_mfma_f32_16x16x32_bf16 v[42:45], v[126:129], v[122:125], v[42:45]
	v_mfma_f32_16x16x32_bf16 v[46:49], v[118:121], v[114:117], v[46:49]
	v_mfma_f32_16x16x32_bf16 v[38:41], v[118:121], v[168:171], v[38:41]
	v_mfma_f32_16x16x32_bf16 v[26:29], v[118:121], v[122:125], v[26:29]
	v_mfma_f32_16x16x32_bf16 v[106:109], v[160:163], v[114:117], v[78:81]
	v_mfma_f32_16x16x32_bf16 v[30:33], v[98:101], v[114:117], v[30:33]
	v_mfma_f32_16x16x32_bf16 v[78:81], v[126:129], v[114:117], v[62:65]
	v_mfma_f32_16x16x32_bf16 v[90:93], v[164:167], v[114:117], v[74:77]
	v_mfma_f32_16x16x32_bf16 v[22:25], v[98:101], v[168:171], v[22:25]
	v_mfma_f32_16x16x32_bf16 v[14:17], v[98:101], v[122:125], v[14:17]
	v_mfma_f32_16x16x32_bf16 v[114:117], v[164:167], v[122:125], v[58:61]
	v_mfma_f32_16x16x32_bf16 v[98:101], v[160:163], v[168:171], v[2:5]
	ds_read_b128 v[62:65], v0 offset:1024
	ds_read_b128 v[156:159], v151 offset:1024
	ds_read_b128 v[160:163], v151 offset:3072
	ds_read_b128 v[164:167], v151 offset:5120
	ds_read_b128 v[168:171], v151 offset:7168
	s_waitcnt lgkmcnt(3)
	v_mfma_f32_16x16x32_bf16 v[2:5], v[62:65], v[156:159], v[6:9]
	ds_read_b128 v[66:69], v0 offset:3072
	s_waitcnt lgkmcnt(3)
	v_mfma_f32_16x16x32_bf16 v[58:61], v[62:65], v[160:163], v[14:17]
	s_waitcnt lgkmcnt(2)
	v_mfma_f32_16x16x32_bf16 v[122:125], v[62:65], v[164:167], v[22:25]
	s_waitcnt lgkmcnt(1)
	v_mfma_f32_16x16x32_bf16 v[70:73], v[62:65], v[168:171], v[30:33]
	s_waitcnt lgkmcnt(0)
	v_mfma_f32_16x16x32_bf16 v[6:9], v[66:69], v[156:159], v[18:21]
	ds_read_b128 v[14:17], v0 offset:5120
	v_mfma_f32_16x16x32_bf16 v[62:65], v[66:69], v[160:163], v[26:29]
	v_mfma_f32_16x16x32_bf16 v[126:129], v[66:69], v[164:167], v[38:41]
	v_mfma_f32_16x16x32_bf16 v[66:69], v[66:69], v[168:171], v[46:49]
	s_waitcnt lgkmcnt(0)
	v_mfma_f32_16x16x32_bf16 v[18:21], v[14:17], v[156:159], v[34:37]
	ds_read_b128 v[26:29], v0 offset:7168
	v_mfma_f32_16x16x32_bf16 v[74:77], v[14:17], v[160:163], v[42:45]
	v_mfma_f32_16x16x32_bf16 v[118:121], v[14:17], v[164:167], v[54:57]
	v_mfma_f32_16x16x32_bf16 v[54:57], v[14:17], v[168:171], v[78:81]
	s_waitcnt lgkmcnt(0)
; DI uint4 ld_nt16(const void* q) { const ntu4 t = __builtin_nontemporal_load((const ntu4*)q); uint4 v; v.x = t[0]; v.y = t[1]; v.z = t[2]; v.w = t[3]; return v; }
; DI int uni(int v) { return __builtin_amdgcn_readfirstlane(v); }
; DI float frcp(float x) { return __builtin_amdgcn_rcpf(x); }
; DI void gemm_stage0(const int tid, const u16* __restrict__ Wb, int ldw, const u16* __restrict__ Xb, int ldx) {
;   const int wid = uni(tid >> 6), lane = tid & 63;
; #pragma unroll
;   for (int i = 0; i < 4; ++i) {
;     int R, C; stage_rc(wid * 1024 + i * 8192 + lane * 16, R, C);
;     __builtin_amdgcn_global_load_lds((const unsigned*)(Wb + R * ldw + C), (unsigned*)(shm + wid * 1024 + i * 8192), 16, 0, 0);
;     __builtin_amdgcn_global_load_lds((const unsigned*)(Xb + R * ldx + C), (unsigned*)(shm + TILE_B + wid * 1024 + i * 8192), 16, 0, 0);
;   }
; }
; template <int CT>
; DI void phase_g2(int c, int l) {
;     ...
;     for (int n = 0; n < 4; ++n) {
; #pragma unroll
;       for (int mp = 0; mp < 4; ++mp) {
;         const size_t fo = frag_off(pm, pn, wid, n, mp, lane);
;         float a8[8], b8[8];
;         unpack8(ld_nt16(WSU(MGA) + fo), a8); unpack8(ld_nt16(WSU(MGB) + fo), b8);
; #pragma unroll
;         for (int j = 0; j < 8; ++j) acc[mp * 2 + (j >> 2)][n][j & 3] *= (1.f + __expf(-b8[j])) * frcp(1.f + __expf(-a8[j]));
	v_mfma_f32_16x16x32_bf16 v[22:25], v[26:29], v[156:159], v[50:53]
	ds_read_b128 v[14:17], v0 offset:9216
	v_mfma_f32_16x16x32_bf16 v[78:81], v[26:29], v[160:163], v[114:117]
	v_mfma_f32_16x16x32_bf16 v[114:117], v[26:29], v[164:167], v[102:105]
	v_mfma_f32_16x16x32_bf16 v[50:53], v[26:29], v[168:171], v[90:93]
	s_waitcnt lgkmcnt(0)
	v_mfma_f32_16x16x32_bf16 v[26:29], v[14:17], v[156:159], v[94:97]
	ds_read_b128 v[34:37], v0 offset:11264
	v_mfma_f32_16x16x32_bf16 v[90:93], v[14:17], v[160:163], v[10:13]
	v_mfma_f32_16x16x32_bf16 v[102:105], v[14:17], v[164:167], v[98:101]
	v_mfma_f32_16x16x32_bf16 v[38:41], v[14:17], v[168:171], v[106:109]
	s_waitcnt lgkmcnt(0)
	v_mfma_f32_16x16x32_bf16 v[30:33], v[34:37], v[156:159], v[82:85]
	ds_read_b128 v[10:13], v0 offset:13312
	v_mfma_f32_16x16x32_bf16 v[94:97], v[34:37], v[160:163], v[86:89]
	v_mfma_f32_16x16x32_bf16 v[98:101], v[34:37], v[164:167], v[176:179]
	v_mfma_f32_16x16x32_bf16 v[34:37], v[34:37], v[168:171], v[180:183]
	s_waitcnt lgkmcnt(0)
	v_mfma_f32_16x16x32_bf16 v[42:45], v[10:13], v[156:159], v[152:155]
	s_nop 2
	ds_read_b128 v[152:155], v0 offset:15360
	v_mfma_f32_16x16x32_bf16 v[106:109], v[10:13], v[160:163], v[184:187]
	v_mfma_f32_16x16x32_bf16 v[86:89], v[10:13], v[164:167], v[134:137]
	v_mfma_f32_16x16x32_bf16 v[14:17], v[10:13], v[168:171], v[110:113]
	s_waitcnt lgkmcnt(0)
	v_mfma_f32_16x16x32_bf16 v[46:49], v[152:155], v[156:159], v[142:145]
	v_mfma_f32_16x16x32_bf16 v[110:113], v[152:155], v[160:163], v[172:175]
	v_mfma_f32_16x16x32_bf16 v[82:85], v[152:155], v[164:167], v[130:133]
	v_mfma_f32_16x16x32_bf16 v[10:13], v[152:155], v[168:171], v[138:141]
	s_add_u32 s26, s45, s26
	s_addc_u32 s27, s46, s27
	s_lshl_b64 s[28:29], s[28:29], 1
	s_add_u32 s28, s47, s28
	v_readfirstlane_b32 s1, v192
	s_addc_u32 s29, s50, s29
	s_lshr_b32 s17, s1, 1
	v_and_or_b32 v0, s17, 32, v147
	s_lshr_b32 s21, s1, 3
	v_lshlrev_b32_e32 v0, 1, v0
	s_and_b32 s21, s21, 0x7ffff0
	v_lshl_add_u64 v[130:131], s[26:27], 0, v[0:1]
	v_lshl_add_u64 v[132:133], s[28:29], 0, v[0:1]
	v_or_b32_e32 v0, s21, v196
	v_lshlrev_b32_e32 v134, 9, v0
	s_lshl_b32 s13, s1, 4
	v_ashrrev_i32_e32 v135, 31, v134
	s_and_b32 s15, s13, 0xfffffc00
	v_lshlrev_b64 v[134:135], 1, v[134:135]
	s_add_i32 s17, s15, 0x8000
	v_lshl_add_u64 v[136:137], v[130:131], 0, v[134:135]
	s_mov_b32 m0, s15
	s_waitcnt vmcnt(0)
	s_barrier
	global_load_lds_dwordx4 v[136:137], off
	s_mov_b32 m0, s17
	s_add_i32 s17, s13, 0x2000
	s_lshr_b32 s17, s17, 7
	s_and_b32 s17, s17, 0x7ffff0
	v_lshl_add_u64 v[134:135], v[132:133], 0, v[134:135]
	v_or_b32_e32 v0, s17, v196
	global_load_lds_dwordx4 v[134:135], off
	v_lshlrev_b32_e32 v134, 9, v0
	v_ashrrev_i32_e32 v135, 31, v134
	s_add_i32 s17, s13, 0x4000
	v_lshlrev_b64 v[134:135], 1, v[134:135]
	s_lshr_b32 s17, s17, 7
	v_lshl_add_u64 v[136:137], v[130:131], 0, v[134:135]
	s_add_i32 m0, s15, 0x2000
	s_and_b32 s17, s17, 0x7ffff0
	global_load_lds_dwordx4 v[136:137], off
	v_lshl_add_u64 v[134:135], v[132:133], 0, v[134:135]
	s_add_i32 m0, s15, 0xa000
	v_or_b32_e32 v0, s17, v196
	global_load_lds_dwordx4 v[134:135], off
	v_lshlrev_b32_e32 v134, 9, v0
	v_ashrrev_i32_e32 v135, 31, v134
	s_addk_i32 s13, 0x6000
	v_lshlrev_b64 v[134:135], 1, v[134:135]
	s_lshr_b32 s13, s13, 7
	v_lshl_add_u64 v[136:137], v[130:131], 0, v[134:135]
	s_add_i32 m0, s15, 0x4000
	s_and_b32 s13, s13, 0x7ffff0
	global_load_lds_dwordx4 v[136:137], off
	v_lshl_add_u64 v[134:135], v[132:133], 0, v[134:135]
	s_add_i32 m0, s15, 0xc000
	v_or_b32_e32 v0, s13, v196
	global_load_lds_dwordx4 v[134:135], off
	v_lshlrev_b32_e32 v134, 9, v0
	v_ashrrev_i32_e32 v135, 31, v134
	v_lshlrev_b64 v[134:135], 1, v[134:135]
	v_lshl_add_u64 v[130:131], v[130:131], 0, v[134:135]
	s_add_i32 m0, s15, 0x6000
	v_mov_b32_e32 v0, v210
	global_load_lds_dwordx4 v[130:131], off
	v_lshl_add_u64 v[130:131], v[132:133], 0, v[134:135]
	s_add_i32 m0, s15, 0xe000
	s_ashr_i32 s15, s14, 31
	global_load_lds_dwordx4 v[130:131], off
	s_lshl_b64 s[28:29], s[14:15], 3
	v_readfirstlane_b32 s13, v0
	s_ashr_i32 s17, s13, 6
	s_ashr_i32 s13, s12, 31
	s_lshl_b64 s[26:27], s[12:13], 5
	s_add_u32 s13, s28, s26
	s_addc_u32 s15, s29, s27
	s_ashr_i32 s21, s17, 31
	s_add_u32 s26, s13, s17
	s_addc_u32 s27, s15, s21
	v_lshlrev_b32_e32 v0, 4, v0
	s_lshl_b64 s[26:27], s[26:27], 14
	v_and_b32_e32 v0, 0x3f0, v0
	v_or_b32_e32 v130, s26, v0
	v_mov_b32_e32 v131, s27
	v_mov_b32_e32 v222, v130
	v_mov_b32_e32 v223, s27
	v_lshl_add_u64 v[228:229], s[6:7], 0, v[222:223]
	global_load_dwordx4 v[156:159], v[228:229], off nt
	v_lshl_add_u64 v[228:229], s[8:9], 0, v[222:223]
	global_load_dwordx4 v[160:163], v[228:229], off nt
	v_or_b32_e32 v222, 0x400, v130
	v_mov_b32_e32 v223, s27
	v_lshl_add_u64 v[228:229], s[6:7], 0, v[222:223]
	global_load_dwordx4 v[164:167], v[228:229], off nt
	v_lshl_add_u64 v[228:229], s[8:9], 0, v[222:223]
	global_load_dwordx4 v[168:171], v[228:229], off nt
	v_or_b32_e32 v222, 0x800, v130
	v_mov_b32_e32 v223, s27
	v_lshl_add_u64 v[228:229], s[6:7], 0, v[222:223]
	global_load_dwordx4 v[172:175], v[228:229], off nt
	v_lshl_add_u64 v[228:229], s[8:9], 0, v[222:223]
	global_load_dwordx4 v[232:235], v[228:229], off nt
	v_or_b32_e32 v222, 0xc00, v130
	v_mov_b32_e32 v223, s27
	v_lshl_add_u64 v[228:229], s[6:7], 0, v[222:223]
	global_load_dwordx4 v[236:239], v[228:229], off nt
	v_lshl_add_u64 v[228:229], s[8:9], 0, v[222:223]
	global_load_dwordx4 v[240:243], v[228:229], off nt
	v_or_b32_e32 v222, 0x1000, v130
	v_mov_b32_e32 v223, s27
	v_lshl_add_u64 v[228:229], s[6:7], 0, v[222:223]
	global_load_dwordx4 v[244:247], v[228:229], off nt
	v_lshl_add_u64 v[228:229], s[8:9], 0, v[222:223]
	global_load_dwordx4 v[248:251], v[228:229], off nt
	v_or_b32_e32 v222, 0x1400, v130
	v_mov_b32_e32 v223, s27
	v_lshl_add_u64 v[228:229], s[6:7], 0, v[222:223]
	global_load_dwordx4 v[216:219], v[228:229], off nt
	v_lshl_add_u64 v[228:229], s[8:9], 0, v[222:223]
	global_load_dwordx4 v[224:227], v[228:229], off nt
	s_ashr_i32 s21, s1, 6
	s_lshl_b32 s26, s21, 5
	s_lshl_b32 s1, s1, 7
	s_lshl_b32 s17, s21, 10
	s_and_b32 s26, s26, 32
	s_and_b32 s1, s1, 0x6000
	s_movk_i32 s89, 0x1000
	s_waitcnt vmcnt(11)
; DI uint4 ld_nt16(const void* q) { const ntu4 t = __builtin_nontemporal_load((const ntu4*)q); uint4 v; v.x = t[0]; v.y = t[1]; v.z = t[2]; v.w = t[3]; return v; }
; DI float frcp(float x) { return __builtin_amdgcn_rcpf(x); }
; template <int CT>
; DI void phase_g2(int c, int l) {
;     ...
;     for (int n = 0; n < 4; ++n) {
; #pragma unroll
;       for (int mp = 0; mp < 4; ++mp) {
;         const size_t fo = frag_off(pm, pn, wid, n, mp, lane);
;         float a8[8], b8[8];
;         unpack8(ld_nt16(WSU(MGA) + fo), a8); unpack8(ld_nt16(WSU(MGB) + fo), b8);
; #pragma unroll
;         for (int j = 0; j < 8; ++j) acc[mp * 2 + (j >> 2)][n][j & 3] *= (1.f + __expf(-b8[j])) * frcp(1.f + __expf(-a8[j]));
;       }
	v_lshlrev_b32_e32 v0, 16, v156
	v_and_b32_e32 v136, 0xffff0000, v156
	v_lshlrev_b32_e32 v137, 16, v157
	v_and_b32_e32 v139, 0xffff0000, v157
	v_lshlrev_b32_e32 v140, 16, v158
	v_and_b32_e32 v141, 0xffff0000, v158
	v_lshlrev_b32_e32 v142, 16, v159
	v_and_b32_e32 v143, 0xffff0000, v159
	v_mul_f32_e32 v0, 0xbfb8aa3b, v0
	v_exp_f32_e32 v0, v0
	s_waitcnt vmcnt(10)
	v_and_b32_e32 v144, 0xffff0000, v160
	v_add_f32_e32 v0, 1.0, v0
	v_lshlrev_b32_e32 v152, 16, v162
	v_and_b32_e32 v153, 0xffff0000, v162
	v_rcp_f32_e32 v134, v0
	v_mul_f32_e32 v0, 0xbfb8aa3b, v144
	v_lshlrev_b32_e32 v145, 16, v161
	v_and_b32_e32 v151, 0xffff0000, v161
	v_exp_f32_e32 v133, v0
	v_mul_f32_e32 v0, 0xbfb8aa3b, v136
	v_exp_f32_e32 v0, v0
	v_lshlrev_b32_e32 v154, 16, v163
	v_and_b32_e32 v155, 0xffff0000, v163
	v_lshlrev_b32_e32 v138, 16, v160
	v_add_f32_e32 v0, 1.0, v0
	v_rcp_f32_e32 v135, v0
	v_mul_f32_e32 v0, 0xbfb8aa3b, v145
	v_exp_f32_e32 v136, v0
	v_mul_f32_e32 v0, 0xbfb8aa3b, v137
	v_exp_f32_e32 v0, v0
	v_mul_f32_e32 v132, 0xbfb8aa3b, v138
	v_exp_f32_e32 v132, v132
	v_add_f32_e32 v0, 1.0, v0
	v_rcp_f32_e32 v138, v0
	v_mul_f32_e32 v0, 0xbfb8aa3b, v151
	v_exp_f32_e32 v137, v0
	v_mul_f32_e32 v0, 0xbfb8aa3b, v139
	v_exp_f32_e32 v0, v0
	v_pk_add_f32 v[132:133], v[132:133], 1.0 op_sel_hi:[1,0]
	v_pk_add_f32 v[136:137], v[136:137], 1.0 op_sel_hi:[1,0]
	v_pk_mul_f32 v[132:133], v[132:133], v[134:135]
	v_add_f32_e32 v0, 1.0, v0
	v_rcp_f32_e32 v139, v0
	v_mul_f32_e32 v0, 0xbfb8aa3b, v152
	v_pk_mul_f32 v[2:3], v[2:3], v[132:133]
	v_exp_f32_e32 v132, v0
	v_mul_f32_e32 v0, 0xbfb8aa3b, v140
	v_exp_f32_e32 v0, v0
	v_pk_mul_f32 v[134:135], v[136:137], v[138:139]
	v_add_f32_e32 v0, 1.0, v0
	v_pk_mul_f32 v[4:5], v[4:5], v[134:135]
	v_rcp_f32_e32 v134, v0
	v_mul_f32_e32 v0, 0xbfb8aa3b, v153
	v_exp_f32_e32 v133, v0
	v_mul_f32_e32 v0, 0xbfb8aa3b, v141
	v_exp_f32_e32 v0, v0
	v_pk_add_f32 v[132:133], v[132:133], 1.0 op_sel_hi:[1,0]
	v_add_f32_e32 v0, 1.0, v0
	v_rcp_f32_e32 v135, v0
	v_mul_f32_e32 v0, 0xbfb8aa3b, v154
	v_exp_f32_e32 v136, v0
	v_mul_f32_e32 v0, 0xbfb8aa3b, v142
	v_exp_f32_e32 v0, v0
	v_pk_mul_f32 v[132:133], v[132:133], v[134:135]
	v_add_f32_e32 v0, 1.0, v0
	v_rcp_f32_e32 v138, v0
	v_mul_f32_e32 v0, 0xbfb8aa3b, v155
	v_exp_f32_e32 v137, v0
	v_mul_f32_e32 v0, 0xbfb8aa3b, v143
	v_exp_f32_e32 v0, v0
	v_pk_mul_f32 v[6:7], v[6:7], v[132:133]
	v_pk_add_f32 v[136:137], v[136:137], 1.0 op_sel_hi:[1,0]
	v_add_f32_e32 v0, 1.0, v0
	v_rcp_f32_e32 v139, v0
	s_nop 0
	v_pk_mul_f32 v[134:135], v[136:137], v[138:139]
	v_or_b32_e32 v136, 0x400, v130
	v_mov_b32_e32 v137, s27
	v_pk_mul_f32 v[8:9], v[8:9], v[134:135]
	v_or_b32_e32 v222, 0x1800, v130
	v_mov_b32_e32 v223, s27
	v_lshl_add_u64 v[228:229], s[6:7], 0, v[222:223]
	global_load_dwordx4 v[156:159], v[228:229], off nt
	v_lshl_add_u64 v[228:229], s[8:9], 0, v[222:223]
	global_load_dwordx4 v[160:163], v[228:229], off nt
	s_waitcnt vmcnt(11)
	v_lshlrev_b32_e32 v0, 16, v164
	v_and_b32_e32 v138, 0xffff0000, v164
	v_lshlrev_b32_e32 v139, 16, v165
	v_and_b32_e32 v140, 0xffff0000, v165
	v_lshlrev_b32_e32 v141, 16, v166
	v_and_b32_e32 v142, 0xffff0000, v166
	v_lshlrev_b32_e32 v143, 16, v167
	v_and_b32_e32 v144, 0xffff0000, v167
	v_mul_f32_e32 v0, 0xbfb8aa3b, v0
	v_exp_f32_e32 v0, v0
	s_waitcnt vmcnt(10)
	v_and_b32_e32 v137, 0xffff0000, v168
	v_add_f32_e32 v0, 1.0, v0
	v_lshlrev_b32_e32 v152, 16, v170
	v_and_b32_e32 v153, 0xffff0000, v170
	v_rcp_f32_e32 v134, v0
	v_mul_f32_e32 v0, 0xbfb8aa3b, v137
	v_lshlrev_b32_e32 v145, 16, v169
	v_and_b32_e32 v151, 0xffff0000, v169
	v_exp_f32_e32 v133, v0
	v_mul_f32_e32 v0, 0xbfb8aa3b, v138
	v_exp_f32_e32 v0, v0
	v_lshlrev_b32_e32 v136, 16, v168
	v_lshlrev_b32_e32 v154, 16, v171
	v_and_b32_e32 v155, 0xffff0000, v171
	v_add_f32_e32 v0, 1.0, v0
	v_rcp_f32_e32 v135, v0
	v_mul_f32_e32 v0, 0xbfb8aa3b, v145
	v_mul_f32_e32 v132, 0xbfb8aa3b, v136
	v_exp_f32_e32 v136, v0
	v_mul_f32_e32 v0, 0xbfb8aa3b, v139
	v_exp_f32_e32 v0, v0
	v_exp_f32_e32 v132, v132
	v_add_f32_e32 v0, 1.0, v0
	v_rcp_f32_e32 v138, v0
	v_mul_f32_e32 v0, 0xbfb8aa3b, v151
	v_exp_f32_e32 v137, v0
	v_mul_f32_e32 v0, 0xbfb8aa3b, v140
	v_exp_f32_e32 v0, v0
	v_pk_add_f32 v[132:133], v[132:133], 1.0 op_sel_hi:[1,0]
	v_pk_add_f32 v[136:137], v[136:137], 1.0 op_sel_hi:[1,0]
	v_pk_mul_f32 v[132:133], v[132:133], v[134:135]
	v_add_f32_e32 v0, 1.0, v0
	v_rcp_f32_e32 v139, v0
	v_mul_f32_e32 v0, 0xbfb8aa3b, v152
	v_pk_mul_f32 v[18:19], v[18:19], v[132:133]
	v_exp_f32_e32 v132, v0
	v_mul_f32_e32 v0, 0xbfb8aa3b, v141
	v_exp_f32_e32 v0, v0
	v_pk_mul_f32 v[134:135], v[136:137], v[138:139]
	v_add_f32_e32 v0, 1.0, v0
	v_pk_mul_f32 v[20:21], v[20:21], v[134:135]
	v_rcp_f32_e32 v134, v0
	v_mul_f32_e32 v0, 0xbfb8aa3b, v153
	v_exp_f32_e32 v133, v0
	v_mul_f32_e32 v0, 0xbfb8aa3b, v142
	v_exp_f32_e32 v0, v0
	v_pk_add_f32 v[132:133], v[132:133], 1.0 op_sel_hi:[1,0]
	v_add_f32_e32 v0, 1.0, v0
	v_rcp_f32_e32 v135, v0
	v_mul_f32_e32 v0, 0xbfb8aa3b, v154
	v_exp_f32_e32 v136, v0
	v_mul_f32_e32 v0, 0xbfb8aa3b, v143
	v_exp_f32_e32 v0, v0
	v_pk_mul_f32 v[132:133], v[132:133], v[134:135]
	v_add_f32_e32 v0, 1.0, v0
	v_rcp_f32_e32 v138, v0
	v_mul_f32_e32 v0, 0xbfb8aa3b, v155
	v_exp_f32_e32 v137, v0
	v_mul_f32_e32 v0, 0xbfb8aa3b, v144
	v_exp_f32_e32 v0, v0
	v_pk_mul_f32 v[22:23], v[22:23], v[132:133]
	v_pk_add_f32 v[136:137], v[136:137], 1.0 op_sel_hi:[1,0]
	v_add_f32_e32 v0, 1.0, v0
	v_rcp_f32_e32 v139, v0
	s_nop 0
	v_pk_mul_f32 v[134:135], v[136:137], v[138:139]
	v_or_b32_e32 v136, 0x800, v130
	v_mov_b32_e32 v137, s27
	v_pk_mul_f32 v[24:25], v[24:25], v[134:135]
	v_or_b32_e32 v222, 0x1c00, v130
	v_mov_b32_e32 v223, s27
	v_lshl_add_u64 v[228:229], s[6:7], 0, v[222:223]
	global_load_dwordx4 v[164:167], v[228:229], off nt
	v_lshl_add_u64 v[228:229], s[8:9], 0, v[222:223]
	global_load_dwordx4 v[168:171], v[228:229], off nt
	s_waitcnt vmcnt(11)
; DI uint4 ld_nt16(const void* q) { const ntu4 t = __builtin_nontemporal_load((const ntu4*)q); uint4 v; v.x = t[0]; v.y = t[1]; v.z = t[2]; v.w = t[3]; return v; }
; DI float frcp(float x) { return __builtin_amdgcn_rcpf(x); }
; template <int CT>
; DI void phase_g2(int c, int l) {
;     ...
;     for (int n = 0; n < 4; ++n) {
; #pragma unroll
;       for (int mp = 0; mp < 4; ++mp) {
;         const size_t fo = frag_off(pm, pn, wid, n, mp, lane);
;         float a8[8], b8[8];
;         unpack8(ld_nt16(WSU(MGA) + fo), a8); unpack8(ld_nt16(WSU(MGB) + fo), b8);
; #pragma unroll
;         for (int j = 0; j < 8; ++j) acc[mp * 2 + (j >> 2)][n][j & 3] *= (1.f + __expf(-b8[j])) * frcp(1.f + __expf(-a8[j]));
;       }
	v_lshlrev_b32_e32 v0, 16, v172
	v_and_b32_e32 v138, 0xffff0000, v172
	v_lshlrev_b32_e32 v139, 16, v173
	v_and_b32_e32 v140, 0xffff0000, v173
	v_lshlrev_b32_e32 v141, 16, v174
	v_and_b32_e32 v142, 0xffff0000, v174
	v_lshlrev_b32_e32 v143, 16, v175
	v_and_b32_e32 v144, 0xffff0000, v175
	v_mul_f32_e32 v0, 0xbfb8aa3b, v0
	v_exp_f32_e32 v0, v0
	s_waitcnt vmcnt(10)
	v_and_b32_e32 v137, 0xffff0000, v232
	v_add_f32_e32 v0, 1.0, v0
	v_lshlrev_b32_e32 v152, 16, v234
	v_and_b32_e32 v153, 0xffff0000, v234
	v_rcp_f32_e32 v134, v0
	v_mul_f32_e32 v0, 0xbfb8aa3b, v137
	v_lshlrev_b32_e32 v145, 16, v233
	v_and_b32_e32 v151, 0xffff0000, v233
	v_exp_f32_e32 v133, v0
	v_mul_f32_e32 v0, 0xbfb8aa3b, v138
	v_exp_f32_e32 v0, v0
	v_lshlrev_b32_e32 v136, 16, v232
	v_lshlrev_b32_e32 v154, 16, v235
	v_and_b32_e32 v155, 0xffff0000, v235
	v_add_f32_e32 v0, 1.0, v0
	v_rcp_f32_e32 v135, v0
	v_mul_f32_e32 v0, 0xbfb8aa3b, v145
	v_mul_f32_e32 v132, 0xbfb8aa3b, v136
	v_exp_f32_e32 v136, v0
	v_mul_f32_e32 v0, 0xbfb8aa3b, v139
	v_exp_f32_e32 v0, v0
	v_exp_f32_e32 v132, v132
	v_add_f32_e32 v0, 1.0, v0
	v_rcp_f32_e32 v138, v0
	v_mul_f32_e32 v0, 0xbfb8aa3b, v151
	v_exp_f32_e32 v137, v0
	v_mul_f32_e32 v0, 0xbfb8aa3b, v140
	v_exp_f32_e32 v0, v0
	v_pk_add_f32 v[132:133], v[132:133], 1.0 op_sel_hi:[1,0]
	v_pk_add_f32 v[136:137], v[136:137], 1.0 op_sel_hi:[1,0]
	v_pk_mul_f32 v[132:133], v[132:133], v[134:135]
	v_add_f32_e32 v0, 1.0, v0
	v_rcp_f32_e32 v139, v0
	v_mul_f32_e32 v0, 0xbfb8aa3b, v152
	v_pk_mul_f32 v[26:27], v[26:27], v[132:133]
	v_exp_f32_e32 v132, v0
	v_mul_f32_e32 v0, 0xbfb8aa3b, v141
	v_exp_f32_e32 v0, v0
	v_pk_mul_f32 v[134:135], v[136:137], v[138:139]
	v_add_f32_e32 v0, 1.0, v0
	v_pk_mul_f32 v[28:29], v[28:29], v[134:135]
	v_rcp_f32_e32 v134, v0
	v_mul_f32_e32 v0, 0xbfb8aa3b, v153
	v_exp_f32_e32 v133, v0
	v_mul_f32_e32 v0, 0xbfb8aa3b, v142
	v_exp_f32_e32 v0, v0
	v_pk_add_f32 v[132:133], v[132:133], 1.0 op_sel_hi:[1,0]
	v_add_f32_e32 v0, 1.0, v0
	v_rcp_f32_e32 v135, v0
	v_mul_f32_e32 v0, 0xbfb8aa3b, v154
	v_exp_f32_e32 v136, v0
	v_mul_f32_e32 v0, 0xbfb8aa3b, v143
	v_exp_f32_e32 v0, v0
	v_pk_mul_f32 v[132:133], v[132:133], v[134:135]
	v_add_f32_e32 v0, 1.0, v0
	v_rcp_f32_e32 v138, v0
	v_mul_f32_e32 v0, 0xbfb8aa3b, v155
	v_exp_f32_e32 v137, v0
	v_mul_f32_e32 v0, 0xbfb8aa3b, v144
	v_exp_f32_e32 v0, v0
	v_pk_mul_f32 v[30:31], v[30:31], v[132:133]
	v_pk_add_f32 v[136:137], v[136:137], 1.0 op_sel_hi:[1,0]
	v_add_f32_e32 v0, 1.0, v0
	v_rcp_f32_e32 v139, v0
	s_nop 0
	v_pk_mul_f32 v[134:135], v[136:137], v[138:139]
	v_or_b32_e32 v136, 0xc00, v130
	v_mov_b32_e32 v137, s27
	v_pk_mul_f32 v[32:33], v[32:33], v[134:135]
	v_or_b32_e32 v222, 0x2000, v130
	v_mov_b32_e32 v223, s27
	v_lshl_add_u64 v[228:229], s[6:7], 0, v[222:223]
	global_load_dwordx4 v[172:175], v[228:229], off nt
	v_lshl_add_u64 v[228:229], s[8:9], 0, v[222:223]
	global_load_dwordx4 v[232:235], v[228:229], off nt
	s_waitcnt vmcnt(11)
	v_lshlrev_b32_e32 v0, 16, v236
	v_and_b32_e32 v138, 0xffff0000, v236
	v_lshlrev_b32_e32 v139, 16, v237
	v_and_b32_e32 v140, 0xffff0000, v237
	v_lshlrev_b32_e32 v141, 16, v238
	v_and_b32_e32 v142, 0xffff0000, v238
	v_lshlrev_b32_e32 v143, 16, v239
	v_and_b32_e32 v144, 0xffff0000, v239
	v_mul_f32_e32 v0, 0xbfb8aa3b, v0
	v_exp_f32_e32 v0, v0
	s_waitcnt vmcnt(10)
	v_and_b32_e32 v137, 0xffff0000, v240
	v_add_f32_e32 v0, 1.0, v0
	v_lshlrev_b32_e32 v152, 16, v242
	v_and_b32_e32 v153, 0xffff0000, v242
	v_rcp_f32_e32 v134, v0
	v_mul_f32_e32 v0, 0xbfb8aa3b, v137
	v_lshlrev_b32_e32 v145, 16, v241
	v_and_b32_e32 v151, 0xffff0000, v241
	v_exp_f32_e32 v133, v0
	v_mul_f32_e32 v0, 0xbfb8aa3b, v138
	v_exp_f32_e32 v0, v0
	v_lshlrev_b32_e32 v136, 16, v240
	v_lshlrev_b32_e32 v154, 16, v243
	v_and_b32_e32 v155, 0xffff0000, v243
	v_add_f32_e32 v0, 1.0, v0
	v_rcp_f32_e32 v135, v0
	v_mul_f32_e32 v0, 0xbfb8aa3b, v145
	v_mul_f32_e32 v132, 0xbfb8aa3b, v136
	v_exp_f32_e32 v136, v0
	v_mul_f32_e32 v0, 0xbfb8aa3b, v139
	v_exp_f32_e32 v0, v0
	v_exp_f32_e32 v132, v132
	v_add_f32_e32 v0, 1.0, v0
	v_rcp_f32_e32 v138, v0
	v_mul_f32_e32 v0, 0xbfb8aa3b, v151
	v_exp_f32_e32 v137, v0
	v_mul_f32_e32 v0, 0xbfb8aa3b, v140
	v_exp_f32_e32 v0, v0
	v_pk_add_f32 v[132:133], v[132:133], 1.0 op_sel_hi:[1,0]
	v_pk_add_f32 v[136:137], v[136:137], 1.0 op_sel_hi:[1,0]
	v_pk_mul_f32 v[132:133], v[132:133], v[134:135]
	v_add_f32_e32 v0, 1.0, v0
	v_rcp_f32_e32 v139, v0
	v_mul_f32_e32 v0, 0xbfb8aa3b, v152
	v_pk_mul_f32 v[42:43], v[42:43], v[132:133]
	v_exp_f32_e32 v132, v0
	v_mul_f32_e32 v0, 0xbfb8aa3b, v141
	v_exp_f32_e32 v0, v0
	v_pk_mul_f32 v[134:135], v[136:137], v[138:139]
	v_add_f32_e32 v0, 1.0, v0
	v_pk_mul_f32 v[44:45], v[44:45], v[134:135]
	v_rcp_f32_e32 v134, v0
	v_mul_f32_e32 v0, 0xbfb8aa3b, v153
	v_exp_f32_e32 v133, v0
	v_mul_f32_e32 v0, 0xbfb8aa3b, v142
	v_exp_f32_e32 v0, v0
	v_pk_add_f32 v[132:133], v[132:133], 1.0 op_sel_hi:[1,0]
	v_add_f32_e32 v0, 1.0, v0
	v_rcp_f32_e32 v135, v0
	v_mul_f32_e32 v0, 0xbfb8aa3b, v154
	v_exp_f32_e32 v136, v0
	v_mul_f32_e32 v0, 0xbfb8aa3b, v143
	v_exp_f32_e32 v0, v0
	v_pk_mul_f32 v[132:133], v[132:133], v[134:135]
	v_add_f32_e32 v0, 1.0, v0
	v_rcp_f32_e32 v138, v0
	v_mul_f32_e32 v0, 0xbfb8aa3b, v155
	v_exp_f32_e32 v137, v0
	v_mul_f32_e32 v0, 0xbfb8aa3b, v144
	v_exp_f32_e32 v0, v0
	v_pk_mul_f32 v[46:47], v[46:47], v[132:133]
	v_pk_add_f32 v[136:137], v[136:137], 1.0 op_sel_hi:[1,0]
	v_add_f32_e32 v0, 1.0, v0
	v_rcp_f32_e32 v139, v0
	s_nop 0
	v_pk_mul_f32 v[134:135], v[136:137], v[138:139]
	v_or_b32_e32 v136, 0x1000, v130
	v_mov_b32_e32 v137, s27
	v_pk_mul_f32 v[48:49], v[48:49], v[134:135]
	v_or_b32_e32 v222, 0x2400, v130
	v_mov_b32_e32 v223, s27
	v_lshl_add_u64 v[228:229], s[6:7], 0, v[222:223]
	global_load_dwordx4 v[236:239], v[228:229], off nt
	v_lshl_add_u64 v[228:229], s[8:9], 0, v[222:223]
	global_load_dwordx4 v[240:243], v[228:229], off nt
	s_waitcnt vmcnt(11)
; DI uint4 ld_nt16(const void* q) { const ntu4 t = __builtin_nontemporal_load((const ntu4*)q); uint4 v; v.x = t[0]; v.y = t[1]; v.z = t[2]; v.w = t[3]; return v; }
; DI float frcp(float x) { return __builtin_amdgcn_rcpf(x); }
; template <int CT>
; DI void phase_g2(int c, int l) {
;     ...
;     for (int n = 0; n < 4; ++n) {
; #pragma unroll
;       for (int mp = 0; mp < 4; ++mp) {
;         const size_t fo = frag_off(pm, pn, wid, n, mp, lane);
;         float a8[8], b8[8];
;         unpack8(ld_nt16(WSU(MGA) + fo), a8); unpack8(ld_nt16(WSU(MGB) + fo), b8);
; #pragma unroll
;         for (int j = 0; j < 8; ++j) acc[mp * 2 + (j >> 2)][n][j & 3] *= (1.f + __expf(-b8[j])) * frcp(1.f + __expf(-a8[j]));
;       }
	v_lshlrev_b32_e32 v0, 16, v244
	v_and_b32_e32 v138, 0xffff0000, v244
	v_lshlrev_b32_e32 v139, 16, v245
	v_and_b32_e32 v140, 0xffff0000, v245
	v_lshlrev_b32_e32 v141, 16, v246
	v_and_b32_e32 v142, 0xffff0000, v246
	v_lshlrev_b32_e32 v143, 16, v247
	v_and_b32_e32 v144, 0xffff0000, v247
	v_mul_f32_e32 v0, 0xbfb8aa3b, v0
	v_exp_f32_e32 v0, v0
	s_waitcnt vmcnt(10)
	v_and_b32_e32 v137, 0xffff0000, v248
	v_add_f32_e32 v0, 1.0, v0
	v_lshlrev_b32_e32 v152, 16, v250
	v_and_b32_e32 v153, 0xffff0000, v250
	v_rcp_f32_e32 v134, v0
	v_mul_f32_e32 v0, 0xbfb8aa3b, v137
	v_lshlrev_b32_e32 v145, 16, v249
	v_and_b32_e32 v151, 0xffff0000, v249
	v_exp_f32_e32 v133, v0
	v_mul_f32_e32 v0, 0xbfb8aa3b, v138
	v_exp_f32_e32 v0, v0
	v_lshlrev_b32_e32 v136, 16, v248
	v_lshlrev_b32_e32 v154, 16, v251
	v_and_b32_e32 v155, 0xffff0000, v251
	v_add_f32_e32 v0, 1.0, v0
	v_rcp_f32_e32 v135, v0
	v_mul_f32_e32 v0, 0xbfb8aa3b, v145
	v_mul_f32_e32 v132, 0xbfb8aa3b, v136
	v_exp_f32_e32 v136, v0
	v_mul_f32_e32 v0, 0xbfb8aa3b, v139
	v_exp_f32_e32 v0, v0
	v_exp_f32_e32 v132, v132
	v_add_f32_e32 v0, 1.0, v0
	v_rcp_f32_e32 v138, v0
	v_mul_f32_e32 v0, 0xbfb8aa3b, v151
	v_exp_f32_e32 v137, v0
	v_mul_f32_e32 v0, 0xbfb8aa3b, v140
	v_exp_f32_e32 v0, v0
	v_pk_add_f32 v[132:133], v[132:133], 1.0 op_sel_hi:[1,0]
	v_pk_add_f32 v[136:137], v[136:137], 1.0 op_sel_hi:[1,0]
	v_pk_mul_f32 v[132:133], v[132:133], v[134:135]
	v_add_f32_e32 v0, 1.0, v0
	v_rcp_f32_e32 v139, v0
	v_mul_f32_e32 v0, 0xbfb8aa3b, v152
	v_pk_mul_f32 v[58:59], v[58:59], v[132:133]
	v_exp_f32_e32 v132, v0
	v_mul_f32_e32 v0, 0xbfb8aa3b, v141
	v_exp_f32_e32 v0, v0
	v_pk_mul_f32 v[134:135], v[136:137], v[138:139]
	v_add_f32_e32 v0, 1.0, v0
	v_pk_mul_f32 v[60:61], v[60:61], v[134:135]
	v_rcp_f32_e32 v134, v0
	v_mul_f32_e32 v0, 0xbfb8aa3b, v153
	v_exp_f32_e32 v133, v0
	v_mul_f32_e32 v0, 0xbfb8aa3b, v142
	v_exp_f32_e32 v0, v0
	v_pk_add_f32 v[132:133], v[132:133], 1.0 op_sel_hi:[1,0]
	v_add_f32_e32 v0, 1.0, v0
	v_rcp_f32_e32 v135, v0
	v_mul_f32_e32 v0, 0xbfb8aa3b, v154
	v_exp_f32_e32 v136, v0
	v_mul_f32_e32 v0, 0xbfb8aa3b, v143
	v_exp_f32_e32 v0, v0
	v_pk_mul_f32 v[132:133], v[132:133], v[134:135]
	v_add_f32_e32 v0, 1.0, v0
	v_rcp_f32_e32 v138, v0
	v_mul_f32_e32 v0, 0xbfb8aa3b, v155
	v_exp_f32_e32 v137, v0
	v_mul_f32_e32 v0, 0xbfb8aa3b, v144
	v_exp_f32_e32 v0, v0
	v_pk_mul_f32 v[62:63], v[62:63], v[132:133]
	v_pk_add_f32 v[136:137], v[136:137], 1.0 op_sel_hi:[1,0]
	v_add_f32_e32 v0, 1.0, v0
	v_rcp_f32_e32 v139, v0
	s_nop 0
	v_pk_mul_f32 v[134:135], v[136:137], v[138:139]
	v_or_b32_e32 v136, 0x1400, v130
	v_mov_b32_e32 v137, s27
	v_pk_mul_f32 v[64:65], v[64:65], v[134:135]
	v_or_b32_e32 v222, 0x2800, v130
	v_mov_b32_e32 v223, s27
	v_lshl_add_u64 v[228:229], s[6:7], 0, v[222:223]
	global_load_dwordx4 v[244:247], v[228:229], off nt
	v_lshl_add_u64 v[228:229], s[8:9], 0, v[222:223]
	global_load_dwordx4 v[248:251], v[228:229], off nt
	s_waitcnt vmcnt(11)
	v_lshlrev_b32_e32 v0, 16, v216
	v_and_b32_e32 v138, 0xffff0000, v216
	v_lshlrev_b32_e32 v139, 16, v217
	v_and_b32_e32 v140, 0xffff0000, v217
	v_lshlrev_b32_e32 v141, 16, v218
	v_and_b32_e32 v142, 0xffff0000, v218
	v_lshlrev_b32_e32 v143, 16, v219
	v_and_b32_e32 v144, 0xffff0000, v219
	v_mul_f32_e32 v0, 0xbfb8aa3b, v0
	v_exp_f32_e32 v0, v0
	s_waitcnt vmcnt(10)
	v_and_b32_e32 v137, 0xffff0000, v224
	v_add_f32_e32 v0, 1.0, v0
	v_lshlrev_b32_e32 v152, 16, v226
	v_and_b32_e32 v153, 0xffff0000, v226
	v_rcp_f32_e32 v134, v0
	v_mul_f32_e32 v0, 0xbfb8aa3b, v137
	v_lshlrev_b32_e32 v145, 16, v225
	v_and_b32_e32 v151, 0xffff0000, v225
	v_exp_f32_e32 v133, v0
	v_mul_f32_e32 v0, 0xbfb8aa3b, v138
	v_exp_f32_e32 v0, v0
	v_lshlrev_b32_e32 v136, 16, v224
	v_lshlrev_b32_e32 v154, 16, v227
	v_and_b32_e32 v155, 0xffff0000, v227
	v_add_f32_e32 v0, 1.0, v0
	v_rcp_f32_e32 v135, v0
	v_mul_f32_e32 v0, 0xbfb8aa3b, v145
	v_mul_f32_e32 v132, 0xbfb8aa3b, v136
	v_exp_f32_e32 v136, v0
	v_mul_f32_e32 v0, 0xbfb8aa3b, v139
	v_exp_f32_e32 v0, v0
	v_exp_f32_e32 v132, v132
	v_add_f32_e32 v0, 1.0, v0
	v_rcp_f32_e32 v138, v0
	v_mul_f32_e32 v0, 0xbfb8aa3b, v151
	v_exp_f32_e32 v137, v0
	v_mul_f32_e32 v0, 0xbfb8aa3b, v140
	v_exp_f32_e32 v0, v0
	v_pk_add_f32 v[132:133], v[132:133], 1.0 op_sel_hi:[1,0]
	v_pk_add_f32 v[136:137], v[136:137], 1.0 op_sel_hi:[1,0]
	v_pk_mul_f32 v[132:133], v[132:133], v[134:135]
	v_add_f32_e32 v0, 1.0, v0
	v_rcp_f32_e32 v139, v0
	v_mul_f32_e32 v0, 0xbfb8aa3b, v152
	v_pk_mul_f32 v[74:75], v[74:75], v[132:133]
	v_exp_f32_e32 v132, v0
	v_mul_f32_e32 v0, 0xbfb8aa3b, v141
	v_exp_f32_e32 v0, v0
	v_pk_mul_f32 v[134:135], v[136:137], v[138:139]
	v_add_f32_e32 v0, 1.0, v0
	v_pk_mul_f32 v[76:77], v[76:77], v[134:135]
	v_rcp_f32_e32 v134, v0
	v_mul_f32_e32 v0, 0xbfb8aa3b, v153
	v_exp_f32_e32 v133, v0
	v_mul_f32_e32 v0, 0xbfb8aa3b, v142
	v_exp_f32_e32 v0, v0
	v_pk_add_f32 v[132:133], v[132:133], 1.0 op_sel_hi:[1,0]
	v_add_f32_e32 v0, 1.0, v0
	v_rcp_f32_e32 v135, v0
	v_mul_f32_e32 v0, 0xbfb8aa3b, v154
	v_exp_f32_e32 v136, v0
	v_mul_f32_e32 v0, 0xbfb8aa3b, v143
	v_exp_f32_e32 v0, v0
	v_pk_mul_f32 v[132:133], v[132:133], v[134:135]
	v_add_f32_e32 v0, 1.0, v0
	v_rcp_f32_e32 v138, v0
	v_mul_f32_e32 v0, 0xbfb8aa3b, v155
	v_exp_f32_e32 v137, v0
	v_mul_f32_e32 v0, 0xbfb8aa3b, v144
	v_exp_f32_e32 v0, v0
	v_pk_mul_f32 v[78:79], v[78:79], v[132:133]
	v_pk_add_f32 v[136:137], v[136:137], 1.0 op_sel_hi:[1,0]
	v_add_f32_e32 v0, 1.0, v0
	v_rcp_f32_e32 v139, v0
	s_nop 0
	v_pk_mul_f32 v[134:135], v[136:137], v[138:139]
	v_or_b32_e32 v136, 0x1800, v130
	v_mov_b32_e32 v137, s27
	v_pk_mul_f32 v[80:81], v[80:81], v[134:135]
	v_or_b32_e32 v222, 0x2c00, v130
	v_mov_b32_e32 v223, s27
	v_lshl_add_u64 v[228:229], s[6:7], 0, v[222:223]
	global_load_dwordx4 v[216:219], v[228:229], off nt
	v_lshl_add_u64 v[228:229], s[8:9], 0, v[222:223]
	global_load_dwordx4 v[224:227], v[228:229], off nt
	s_waitcnt vmcnt(11)
; DI uint4 ld_nt16(const void* q) { const ntu4 t = __builtin_nontemporal_load((const ntu4*)q); uint4 v; v.x = t[0]; v.y = t[1]; v.z = t[2]; v.w = t[3]; return v; }
; DI float frcp(float x) { return __builtin_amdgcn_rcpf(x); }
; template <int CT>
; DI void phase_g2(int c, int l) {
;     ...
;     for (int n = 0; n < 4; ++n) {
; #pragma unroll
;       for (int mp = 0; mp < 4; ++mp) {
;         const size_t fo = frag_off(pm, pn, wid, n, mp, lane);
;         float a8[8], b8[8];
;         unpack8(ld_nt16(WSU(MGA) + fo), a8); unpack8(ld_nt16(WSU(MGB) + fo), b8);
; #pragma unroll
;         for (int j = 0; j < 8; ++j) acc[mp * 2 + (j >> 2)][n][j & 3] *= (1.f + __expf(-b8[j])) * frcp(1.f + __expf(-a8[j]));
;       }
	v_lshlrev_b32_e32 v0, 16, v156
	v_and_b32_e32 v138, 0xffff0000, v156
	v_lshlrev_b32_e32 v139, 16, v157
	v_and_b32_e32 v140, 0xffff0000, v157
	v_lshlrev_b32_e32 v141, 16, v158
	v_and_b32_e32 v142, 0xffff0000, v158
	v_lshlrev_b32_e32 v143, 16, v159
	v_and_b32_e32 v144, 0xffff0000, v159
	v_mul_f32_e32 v0, 0xbfb8aa3b, v0
	v_exp_f32_e32 v0, v0
	s_waitcnt vmcnt(10)
	v_and_b32_e32 v137, 0xffff0000, v160
	v_add_f32_e32 v0, 1.0, v0
	v_lshlrev_b32_e32 v152, 16, v162
	v_and_b32_e32 v153, 0xffff0000, v162
	v_rcp_f32_e32 v134, v0
	v_mul_f32_e32 v0, 0xbfb8aa3b, v137
	v_lshlrev_b32_e32 v145, 16, v161
	v_and_b32_e32 v151, 0xffff0000, v161
	v_exp_f32_e32 v133, v0
	v_mul_f32_e32 v0, 0xbfb8aa3b, v138
	v_exp_f32_e32 v0, v0
	v_lshlrev_b32_e32 v136, 16, v160
	v_lshlrev_b32_e32 v154, 16, v163
	v_and_b32_e32 v155, 0xffff0000, v163
	v_add_f32_e32 v0, 1.0, v0
	v_rcp_f32_e32 v135, v0
	v_mul_f32_e32 v0, 0xbfb8aa3b, v145
	v_mul_f32_e32 v132, 0xbfb8aa3b, v136
	v_exp_f32_e32 v136, v0
	v_mul_f32_e32 v0, 0xbfb8aa3b, v139
	v_exp_f32_e32 v0, v0
	v_exp_f32_e32 v132, v132
	v_add_f32_e32 v0, 1.0, v0
	v_rcp_f32_e32 v138, v0
	v_mul_f32_e32 v0, 0xbfb8aa3b, v151
	v_exp_f32_e32 v137, v0
	v_mul_f32_e32 v0, 0xbfb8aa3b, v140
	v_exp_f32_e32 v0, v0
	v_pk_add_f32 v[132:133], v[132:133], 1.0 op_sel_hi:[1,0]
	v_pk_add_f32 v[136:137], v[136:137], 1.0 op_sel_hi:[1,0]
	v_pk_mul_f32 v[132:133], v[132:133], v[134:135]
	v_add_f32_e32 v0, 1.0, v0
	v_rcp_f32_e32 v139, v0
	v_mul_f32_e32 v0, 0xbfb8aa3b, v152
	v_pk_mul_f32 v[90:91], v[90:91], v[132:133]
	v_exp_f32_e32 v132, v0
	v_mul_f32_e32 v0, 0xbfb8aa3b, v141
	v_exp_f32_e32 v0, v0
	v_pk_mul_f32 v[134:135], v[136:137], v[138:139]
	v_add_f32_e32 v0, 1.0, v0
	v_pk_mul_f32 v[92:93], v[92:93], v[134:135]
	v_rcp_f32_e32 v134, v0
	v_mul_f32_e32 v0, 0xbfb8aa3b, v153
	v_exp_f32_e32 v133, v0
	v_mul_f32_e32 v0, 0xbfb8aa3b, v142
	v_exp_f32_e32 v0, v0
	v_pk_add_f32 v[132:133], v[132:133], 1.0 op_sel_hi:[1,0]
	v_add_f32_e32 v0, 1.0, v0
	v_rcp_f32_e32 v135, v0
	v_mul_f32_e32 v0, 0xbfb8aa3b, v154
	v_exp_f32_e32 v136, v0
	v_mul_f32_e32 v0, 0xbfb8aa3b, v143
	v_exp_f32_e32 v0, v0
	v_pk_mul_f32 v[132:133], v[132:133], v[134:135]
	v_add_f32_e32 v0, 1.0, v0
	v_rcp_f32_e32 v138, v0
	v_mul_f32_e32 v0, 0xbfb8aa3b, v155
	v_exp_f32_e32 v137, v0
	v_mul_f32_e32 v0, 0xbfb8aa3b, v144
	v_exp_f32_e32 v0, v0
	v_pk_mul_f32 v[94:95], v[94:95], v[132:133]
	v_pk_add_f32 v[136:137], v[136:137], 1.0 op_sel_hi:[1,0]
	v_add_f32_e32 v0, 1.0, v0
	v_rcp_f32_e32 v139, v0
	s_nop 0
	v_pk_mul_f32 v[134:135], v[136:137], v[138:139]
	v_or_b32_e32 v136, 0x1c00, v130
	v_mov_b32_e32 v137, s27
	v_pk_mul_f32 v[96:97], v[96:97], v[134:135]
	v_or_b32_e32 v222, 0x3000, v130
	v_mov_b32_e32 v223, s27
	v_lshl_add_u64 v[228:229], s[6:7], 0, v[222:223]
	global_load_dwordx4 v[156:159], v[228:229], off nt
	v_lshl_add_u64 v[228:229], s[8:9], 0, v[222:223]
	global_load_dwordx4 v[160:163], v[228:229], off nt
	s_waitcnt vmcnt(11)
	v_lshlrev_b32_e32 v0, 16, v164
	v_and_b32_e32 v138, 0xffff0000, v164
	v_lshlrev_b32_e32 v139, 16, v165
	v_and_b32_e32 v140, 0xffff0000, v165
	v_lshlrev_b32_e32 v141, 16, v166
	v_and_b32_e32 v142, 0xffff0000, v166
	v_lshlrev_b32_e32 v143, 16, v167
	v_and_b32_e32 v144, 0xffff0000, v167
	v_mul_f32_e32 v0, 0xbfb8aa3b, v0
	v_exp_f32_e32 v0, v0
	s_waitcnt vmcnt(10)
	v_and_b32_e32 v137, 0xffff0000, v168
	v_add_f32_e32 v0, 1.0, v0
	v_lshlrev_b32_e32 v152, 16, v170
	v_and_b32_e32 v153, 0xffff0000, v170
	v_rcp_f32_e32 v134, v0
	v_mul_f32_e32 v0, 0xbfb8aa3b, v137
	v_lshlrev_b32_e32 v145, 16, v169
	v_and_b32_e32 v151, 0xffff0000, v169
	v_exp_f32_e32 v133, v0
	v_mul_f32_e32 v0, 0xbfb8aa3b, v138
	v_exp_f32_e32 v0, v0
	v_lshlrev_b32_e32 v136, 16, v168
	v_lshlrev_b32_e32 v154, 16, v171
	v_and_b32_e32 v155, 0xffff0000, v171
	v_add_f32_e32 v0, 1.0, v0
	v_rcp_f32_e32 v135, v0
	v_mul_f32_e32 v0, 0xbfb8aa3b, v145
	v_mul_f32_e32 v132, 0xbfb8aa3b, v136
	v_exp_f32_e32 v136, v0
	v_mul_f32_e32 v0, 0xbfb8aa3b, v139
	v_exp_f32_e32 v0, v0
	v_exp_f32_e32 v132, v132
	v_add_f32_e32 v0, 1.0, v0
	v_rcp_f32_e32 v138, v0
	v_mul_f32_e32 v0, 0xbfb8aa3b, v151
	v_exp_f32_e32 v137, v0
	v_mul_f32_e32 v0, 0xbfb8aa3b, v140
	v_exp_f32_e32 v0, v0
	v_pk_add_f32 v[132:133], v[132:133], 1.0 op_sel_hi:[1,0]
	v_pk_add_f32 v[136:137], v[136:137], 1.0 op_sel_hi:[1,0]
	v_pk_mul_f32 v[132:133], v[132:133], v[134:135]
	v_add_f32_e32 v0, 1.0, v0
	v_rcp_f32_e32 v139, v0
	v_mul_f32_e32 v0, 0xbfb8aa3b, v152
	v_pk_mul_f32 v[106:107], v[106:107], v[132:133]
	v_exp_f32_e32 v132, v0
	v_mul_f32_e32 v0, 0xbfb8aa3b, v141
	v_exp_f32_e32 v0, v0
	v_pk_mul_f32 v[134:135], v[136:137], v[138:139]
	v_add_f32_e32 v0, 1.0, v0
	v_pk_mul_f32 v[108:109], v[108:109], v[134:135]
	v_rcp_f32_e32 v134, v0
	v_mul_f32_e32 v0, 0xbfb8aa3b, v153
	v_exp_f32_e32 v133, v0
	v_mul_f32_e32 v0, 0xbfb8aa3b, v142
	v_exp_f32_e32 v0, v0
	v_pk_add_f32 v[132:133], v[132:133], 1.0 op_sel_hi:[1,0]
	v_add_f32_e32 v0, 1.0, v0
	v_rcp_f32_e32 v135, v0
	v_mul_f32_e32 v0, 0xbfb8aa3b, v154
	v_exp_f32_e32 v136, v0
	v_mul_f32_e32 v0, 0xbfb8aa3b, v143
	v_exp_f32_e32 v0, v0
	v_pk_mul_f32 v[132:133], v[132:133], v[134:135]
	v_add_f32_e32 v0, 1.0, v0
	v_rcp_f32_e32 v138, v0
	v_mul_f32_e32 v0, 0xbfb8aa3b, v155
	v_exp_f32_e32 v137, v0
	v_mul_f32_e32 v0, 0xbfb8aa3b, v144
	v_exp_f32_e32 v0, v0
	v_pk_mul_f32 v[110:111], v[110:111], v[132:133]
	v_pk_add_f32 v[136:137], v[136:137], 1.0 op_sel_hi:[1,0]
	v_add_f32_e32 v0, 1.0, v0
	v_rcp_f32_e32 v139, v0
	s_nop 0
	v_pk_mul_f32 v[134:135], v[136:137], v[138:139]
	v_or_b32_e32 v136, 0x2000, v130
	v_mov_b32_e32 v137, s27
	v_pk_mul_f32 v[112:113], v[112:113], v[134:135]
	v_or_b32_e32 v222, 0x3400, v130
	v_mov_b32_e32 v223, s27
	v_lshl_add_u64 v[228:229], s[6:7], 0, v[222:223]
	global_load_dwordx4 v[164:167], v[228:229], off nt
	v_lshl_add_u64 v[228:229], s[8:9], 0, v[222:223]
	global_load_dwordx4 v[168:171], v[228:229], off nt
	s_waitcnt vmcnt(11)
; DI uint4 ld_nt16(const void* q) { const ntu4 t = __builtin_nontemporal_load((const ntu4*)q); uint4 v; v.x = t[0]; v.y = t[1]; v.z = t[2]; v.w = t[3]; return v; }
; DI float frcp(float x) { return __builtin_amdgcn_rcpf(x); }
; template <int CT>
; DI void phase_g2(int c, int l) {
;     ...
;     for (int n = 0; n < 4; ++n) {
; #pragma unroll
;       for (int mp = 0; mp < 4; ++mp) {
;         const size_t fo = frag_off(pm, pn, wid, n, mp, lane);
;         float a8[8], b8[8];
;         unpack8(ld_nt16(WSU(MGA) + fo), a8); unpack8(ld_nt16(WSU(MGB) + fo), b8);
; #pragma unroll
;         for (int j = 0; j < 8; ++j) acc[mp * 2 + (j >> 2)][n][j & 3] *= (1.f + __expf(-b8[j])) * frcp(1.f + __expf(-a8[j]));
;       }
	v_lshlrev_b32_e32 v0, 16, v172
	v_and_b32_e32 v138, 0xffff0000, v172
	v_lshlrev_b32_e32 v139, 16, v173
	v_and_b32_e32 v140, 0xffff0000, v173
	v_lshlrev_b32_e32 v141, 16, v174
	v_and_b32_e32 v142, 0xffff0000, v174
	v_lshlrev_b32_e32 v143, 16, v175
	v_and_b32_e32 v144, 0xffff0000, v175
	v_mul_f32_e32 v0, 0xbfb8aa3b, v0
	v_exp_f32_e32 v0, v0
	s_waitcnt vmcnt(10)
	v_and_b32_e32 v137, 0xffff0000, v232
	v_add_f32_e32 v0, 1.0, v0
	v_lshlrev_b32_e32 v152, 16, v234
	v_and_b32_e32 v153, 0xffff0000, v234
	v_rcp_f32_e32 v134, v0
	v_mul_f32_e32 v0, 0xbfb8aa3b, v137
	v_lshlrev_b32_e32 v145, 16, v233
	v_and_b32_e32 v151, 0xffff0000, v233
	v_exp_f32_e32 v133, v0
	v_mul_f32_e32 v0, 0xbfb8aa3b, v138
	v_exp_f32_e32 v0, v0
	v_lshlrev_b32_e32 v136, 16, v232
	v_lshlrev_b32_e32 v154, 16, v235
	v_and_b32_e32 v155, 0xffff0000, v235
	v_add_f32_e32 v0, 1.0, v0
	v_rcp_f32_e32 v135, v0
	v_mul_f32_e32 v0, 0xbfb8aa3b, v145
	v_mul_f32_e32 v132, 0xbfb8aa3b, v136
	v_exp_f32_e32 v136, v0
	v_mul_f32_e32 v0, 0xbfb8aa3b, v139
	v_exp_f32_e32 v0, v0
	v_exp_f32_e32 v132, v132
	v_add_f32_e32 v0, 1.0, v0
	v_rcp_f32_e32 v138, v0
	v_mul_f32_e32 v0, 0xbfb8aa3b, v151
	v_exp_f32_e32 v137, v0
	v_mul_f32_e32 v0, 0xbfb8aa3b, v140
	v_exp_f32_e32 v0, v0
	v_pk_add_f32 v[132:133], v[132:133], 1.0 op_sel_hi:[1,0]
	v_pk_add_f32 v[136:137], v[136:137], 1.0 op_sel_hi:[1,0]
	v_pk_mul_f32 v[132:133], v[132:133], v[134:135]
	v_add_f32_e32 v0, 1.0, v0
	v_rcp_f32_e32 v139, v0
	v_mul_f32_e32 v0, 0xbfb8aa3b, v152
	v_pk_mul_f32 v[122:123], v[122:123], v[132:133]
	v_exp_f32_e32 v132, v0
	v_mul_f32_e32 v0, 0xbfb8aa3b, v141
	v_exp_f32_e32 v0, v0
	v_pk_mul_f32 v[134:135], v[136:137], v[138:139]
	v_add_f32_e32 v0, 1.0, v0
	v_pk_mul_f32 v[124:125], v[124:125], v[134:135]
	v_rcp_f32_e32 v134, v0
	v_mul_f32_e32 v0, 0xbfb8aa3b, v153
	v_exp_f32_e32 v133, v0
	v_mul_f32_e32 v0, 0xbfb8aa3b, v142
	v_exp_f32_e32 v0, v0
	v_pk_add_f32 v[132:133], v[132:133], 1.0 op_sel_hi:[1,0]
	v_add_f32_e32 v0, 1.0, v0
	v_rcp_f32_e32 v135, v0
	v_mul_f32_e32 v0, 0xbfb8aa3b, v154
	v_exp_f32_e32 v136, v0
	v_mul_f32_e32 v0, 0xbfb8aa3b, v143
	v_exp_f32_e32 v0, v0
	v_pk_mul_f32 v[132:133], v[132:133], v[134:135]
	v_add_f32_e32 v0, 1.0, v0
	v_rcp_f32_e32 v138, v0
	v_mul_f32_e32 v0, 0xbfb8aa3b, v155
	v_exp_f32_e32 v137, v0
	v_mul_f32_e32 v0, 0xbfb8aa3b, v144
	v_exp_f32_e32 v0, v0
	v_pk_mul_f32 v[126:127], v[126:127], v[132:133]
	v_pk_add_f32 v[136:137], v[136:137], 1.0 op_sel_hi:[1,0]
	v_add_f32_e32 v0, 1.0, v0
	v_rcp_f32_e32 v139, v0
	s_nop 0
	v_pk_mul_f32 v[134:135], v[136:137], v[138:139]
	v_or_b32_e32 v136, 0x2400, v130
	v_mov_b32_e32 v137, s27
	v_pk_mul_f32 v[128:129], v[128:129], v[134:135]
	v_or_b32_e32 v222, 0x3800, v130
	v_mov_b32_e32 v223, s27
	v_lshl_add_u64 v[228:229], s[6:7], 0, v[222:223]
	global_load_dwordx4 v[172:175], v[228:229], off nt
	v_lshl_add_u64 v[228:229], s[8:9], 0, v[222:223]
	global_load_dwordx4 v[232:235], v[228:229], off nt
	s_waitcnt vmcnt(11)
	v_lshlrev_b32_e32 v0, 16, v236
	v_and_b32_e32 v138, 0xffff0000, v236
	v_lshlrev_b32_e32 v139, 16, v237
	v_and_b32_e32 v140, 0xffff0000, v237
	v_lshlrev_b32_e32 v141, 16, v238
	v_and_b32_e32 v142, 0xffff0000, v238
	v_lshlrev_b32_e32 v143, 16, v239
	v_and_b32_e32 v144, 0xffff0000, v239
	v_mul_f32_e32 v0, 0xbfb8aa3b, v0
	v_exp_f32_e32 v0, v0
	s_waitcnt vmcnt(10)
	v_and_b32_e32 v137, 0xffff0000, v240
	v_add_f32_e32 v0, 1.0, v0
	v_lshlrev_b32_e32 v152, 16, v242
	v_and_b32_e32 v153, 0xffff0000, v242
	v_rcp_f32_e32 v134, v0
	v_mul_f32_e32 v0, 0xbfb8aa3b, v137
	v_lshlrev_b32_e32 v145, 16, v241
	v_and_b32_e32 v151, 0xffff0000, v241
	v_exp_f32_e32 v133, v0
	v_mul_f32_e32 v0, 0xbfb8aa3b, v138
	v_exp_f32_e32 v0, v0
	v_lshlrev_b32_e32 v136, 16, v240
	v_lshlrev_b32_e32 v154, 16, v243
	v_and_b32_e32 v155, 0xffff0000, v243
	v_add_f32_e32 v0, 1.0, v0
	v_rcp_f32_e32 v135, v0
	v_mul_f32_e32 v0, 0xbfb8aa3b, v145
	v_mul_f32_e32 v132, 0xbfb8aa3b, v136
	v_exp_f32_e32 v136, v0
	v_mul_f32_e32 v0, 0xbfb8aa3b, v139
	v_exp_f32_e32 v0, v0
	v_exp_f32_e32 v132, v132
	v_add_f32_e32 v0, 1.0, v0
	v_rcp_f32_e32 v138, v0
	v_mul_f32_e32 v0, 0xbfb8aa3b, v151
	v_exp_f32_e32 v137, v0
	v_mul_f32_e32 v0, 0xbfb8aa3b, v140
	v_exp_f32_e32 v0, v0
	v_pk_add_f32 v[132:133], v[132:133], 1.0 op_sel_hi:[1,0]
	v_pk_add_f32 v[136:137], v[136:137], 1.0 op_sel_hi:[1,0]
	v_pk_mul_f32 v[132:133], v[132:133], v[134:135]
	v_add_f32_e32 v0, 1.0, v0
	v_rcp_f32_e32 v139, v0
	v_mul_f32_e32 v0, 0xbfb8aa3b, v152
	v_pk_mul_f32 v[118:119], v[118:119], v[132:133]
	v_exp_f32_e32 v132, v0
	v_mul_f32_e32 v0, 0xbfb8aa3b, v141
	v_exp_f32_e32 v0, v0
	v_pk_mul_f32 v[134:135], v[136:137], v[138:139]
	v_add_f32_e32 v0, 1.0, v0
	v_pk_mul_f32 v[120:121], v[120:121], v[134:135]
	v_rcp_f32_e32 v134, v0
	v_mul_f32_e32 v0, 0xbfb8aa3b, v153
	v_exp_f32_e32 v133, v0
	v_mul_f32_e32 v0, 0xbfb8aa3b, v142
	v_exp_f32_e32 v0, v0
	v_pk_add_f32 v[132:133], v[132:133], 1.0 op_sel_hi:[1,0]
	v_add_f32_e32 v0, 1.0, v0
	v_rcp_f32_e32 v135, v0
	v_mul_f32_e32 v0, 0xbfb8aa3b, v154
	v_exp_f32_e32 v136, v0
	v_mul_f32_e32 v0, 0xbfb8aa3b, v143
	v_exp_f32_e32 v0, v0
	v_pk_mul_f32 v[132:133], v[132:133], v[134:135]
	v_add_f32_e32 v0, 1.0, v0
	v_rcp_f32_e32 v138, v0
	v_mul_f32_e32 v0, 0xbfb8aa3b, v155
	v_exp_f32_e32 v137, v0
	v_mul_f32_e32 v0, 0xbfb8aa3b, v144
	v_exp_f32_e32 v0, v0
	v_pk_mul_f32 v[114:115], v[114:115], v[132:133]
	v_pk_add_f32 v[136:137], v[136:137], 1.0 op_sel_hi:[1,0]
	v_add_f32_e32 v0, 1.0, v0
	v_rcp_f32_e32 v139, v0
	s_nop 0
	v_pk_mul_f32 v[134:135], v[136:137], v[138:139]
	v_or_b32_e32 v136, 0x2800, v130
	v_mov_b32_e32 v137, s27
	v_pk_mul_f32 v[116:117], v[116:117], v[134:135]
	v_or_b32_e32 v222, 0x3c00, v130
	v_mov_b32_e32 v223, s27
	v_lshl_add_u64 v[228:229], s[6:7], 0, v[222:223]
	global_load_dwordx4 v[236:239], v[228:229], off nt
	v_lshl_add_u64 v[228:229], s[8:9], 0, v[222:223]
	global_load_dwordx4 v[240:243], v[228:229], off nt
	s_waitcnt vmcnt(11)
; DI uint4 ld_nt16(const void* q) { const ntu4 t = __builtin_nontemporal_load((const ntu4*)q); uint4 v; v.x = t[0]; v.y = t[1]; v.z = t[2]; v.w = t[3]; return v; }
; DI float frcp(float x) { return __builtin_amdgcn_rcpf(x); }
; template <int CT>
; DI void phase_g2(int c, int l) {
;     ...
;     for (int n = 0; n < 4; ++n) {
; #pragma unroll
;       for (int mp = 0; mp < 4; ++mp) {
;         const size_t fo = frag_off(pm, pn, wid, n, mp, lane);
;         float a8[8], b8[8];
;         unpack8(ld_nt16(WSU(MGA) + fo), a8); unpack8(ld_nt16(WSU(MGB) + fo), b8);
; #pragma unroll
;         for (int j = 0; j < 8; ++j) acc[mp * 2 + (j >> 2)][n][j & 3] *= (1.f + __expf(-b8[j])) * frcp(1.f + __expf(-a8[j]));
;       }
	v_lshlrev_b32_e32 v0, 16, v244
	v_and_b32_e32 v138, 0xffff0000, v244
	v_lshlrev_b32_e32 v139, 16, v245
	v_and_b32_e32 v140, 0xffff0000, v245
	v_lshlrev_b32_e32 v141, 16, v246
	v_and_b32_e32 v142, 0xffff0000, v246
	v_lshlrev_b32_e32 v143, 16, v247
	v_and_b32_e32 v144, 0xffff0000, v247
	v_mul_f32_e32 v0, 0xbfb8aa3b, v0
	v_exp_f32_e32 v0, v0
	s_waitcnt vmcnt(10)
	v_and_b32_e32 v137, 0xffff0000, v248
	v_add_f32_e32 v0, 1.0, v0
	v_lshlrev_b32_e32 v152, 16, v250
	v_and_b32_e32 v153, 0xffff0000, v250
	v_rcp_f32_e32 v134, v0
	v_mul_f32_e32 v0, 0xbfb8aa3b, v137
	v_lshlrev_b32_e32 v145, 16, v249
	v_and_b32_e32 v151, 0xffff0000, v249
	v_exp_f32_e32 v133, v0
	v_mul_f32_e32 v0, 0xbfb8aa3b, v138
	v_exp_f32_e32 v0, v0
	v_lshlrev_b32_e32 v136, 16, v248
	v_lshlrev_b32_e32 v154, 16, v251
	v_and_b32_e32 v155, 0xffff0000, v251
	v_add_f32_e32 v0, 1.0, v0
	v_rcp_f32_e32 v135, v0
	v_mul_f32_e32 v0, 0xbfb8aa3b, v145
	v_mul_f32_e32 v132, 0xbfb8aa3b, v136
	v_exp_f32_e32 v136, v0
	v_mul_f32_e32 v0, 0xbfb8aa3b, v139
	v_exp_f32_e32 v0, v0
	v_exp_f32_e32 v132, v132
	v_add_f32_e32 v0, 1.0, v0
	v_rcp_f32_e32 v138, v0
	v_mul_f32_e32 v0, 0xbfb8aa3b, v151
	v_exp_f32_e32 v137, v0
	v_mul_f32_e32 v0, 0xbfb8aa3b, v140
	v_exp_f32_e32 v0, v0
	v_pk_add_f32 v[132:133], v[132:133], 1.0 op_sel_hi:[1,0]
	v_pk_add_f32 v[136:137], v[136:137], 1.0 op_sel_hi:[1,0]
	v_pk_mul_f32 v[132:133], v[132:133], v[134:135]
	v_add_f32_e32 v0, 1.0, v0
	v_rcp_f32_e32 v139, v0
	v_mul_f32_e32 v0, 0xbfb8aa3b, v152
	v_pk_mul_f32 v[102:103], v[102:103], v[132:133]
	v_exp_f32_e32 v132, v0
	v_mul_f32_e32 v0, 0xbfb8aa3b, v141
	v_exp_f32_e32 v0, v0
	v_pk_mul_f32 v[134:135], v[136:137], v[138:139]
	v_add_f32_e32 v0, 1.0, v0
	v_pk_mul_f32 v[104:105], v[104:105], v[134:135]
	v_rcp_f32_e32 v134, v0
	v_mul_f32_e32 v0, 0xbfb8aa3b, v153
	v_exp_f32_e32 v133, v0
	v_mul_f32_e32 v0, 0xbfb8aa3b, v142
	v_exp_f32_e32 v0, v0
	v_pk_add_f32 v[132:133], v[132:133], 1.0 op_sel_hi:[1,0]
	v_add_f32_e32 v0, 1.0, v0
	v_rcp_f32_e32 v135, v0
	v_mul_f32_e32 v0, 0xbfb8aa3b, v154
	v_exp_f32_e32 v136, v0
	v_mul_f32_e32 v0, 0xbfb8aa3b, v143
	v_exp_f32_e32 v0, v0
	v_pk_mul_f32 v[132:133], v[132:133], v[134:135]
	v_add_f32_e32 v0, 1.0, v0
	v_rcp_f32_e32 v138, v0
	v_mul_f32_e32 v0, 0xbfb8aa3b, v155
	v_exp_f32_e32 v137, v0
	v_mul_f32_e32 v0, 0xbfb8aa3b, v144
	v_exp_f32_e32 v0, v0
	v_pk_mul_f32 v[98:99], v[98:99], v[132:133]
	v_pk_add_f32 v[136:137], v[136:137], 1.0 op_sel_hi:[1,0]
	v_add_f32_e32 v0, 1.0, v0
	v_rcp_f32_e32 v139, v0
	s_nop 0
	v_pk_mul_f32 v[134:135], v[136:137], v[138:139]
	v_or_b32_e32 v136, 0x2c00, v130
	v_mov_b32_e32 v137, s27
	v_pk_mul_f32 v[100:101], v[100:101], v[134:135]
	s_waitcnt vmcnt(9)
	v_lshlrev_b32_e32 v0, 16, v216
	v_and_b32_e32 v138, 0xffff0000, v216
	v_lshlrev_b32_e32 v139, 16, v217
	v_and_b32_e32 v140, 0xffff0000, v217
	v_lshlrev_b32_e32 v141, 16, v218
	v_and_b32_e32 v142, 0xffff0000, v218
	v_lshlrev_b32_e32 v143, 16, v219
	v_and_b32_e32 v144, 0xffff0000, v219
	v_mul_f32_e32 v0, 0xbfb8aa3b, v0
	v_exp_f32_e32 v0, v0
	s_waitcnt vmcnt(8)
	v_and_b32_e32 v137, 0xffff0000, v224
	v_add_f32_e32 v0, 1.0, v0
	v_lshlrev_b32_e32 v152, 16, v226
	v_and_b32_e32 v153, 0xffff0000, v226
	v_rcp_f32_e32 v134, v0
	v_mul_f32_e32 v0, 0xbfb8aa3b, v137
	v_lshlrev_b32_e32 v145, 16, v225
	v_and_b32_e32 v151, 0xffff0000, v225
	v_exp_f32_e32 v133, v0
	v_mul_f32_e32 v0, 0xbfb8aa3b, v138
	v_exp_f32_e32 v0, v0
	v_lshlrev_b32_e32 v136, 16, v224
	v_lshlrev_b32_e32 v154, 16, v227
	v_and_b32_e32 v155, 0xffff0000, v227
	v_add_f32_e32 v0, 1.0, v0
	v_rcp_f32_e32 v135, v0
	v_mul_f32_e32 v0, 0xbfb8aa3b, v145
	v_mul_f32_e32 v132, 0xbfb8aa3b, v136
	v_exp_f32_e32 v136, v0
	v_mul_f32_e32 v0, 0xbfb8aa3b, v139
	v_exp_f32_e32 v0, v0
	v_exp_f32_e32 v132, v132
	v_add_f32_e32 v0, 1.0, v0
	v_rcp_f32_e32 v138, v0
	v_mul_f32_e32 v0, 0xbfb8aa3b, v151
	v_exp_f32_e32 v137, v0
	v_mul_f32_e32 v0, 0xbfb8aa3b, v140
	v_exp_f32_e32 v0, v0
	v_pk_add_f32 v[132:133], v[132:133], 1.0 op_sel_hi:[1,0]
	v_pk_add_f32 v[136:137], v[136:137], 1.0 op_sel_hi:[1,0]
	v_pk_mul_f32 v[132:133], v[132:133], v[134:135]
	v_add_f32_e32 v0, 1.0, v0
	v_rcp_f32_e32 v139, v0
	v_mul_f32_e32 v0, 0xbfb8aa3b, v152
	v_pk_mul_f32 v[86:87], v[86:87], v[132:133]
	v_exp_f32_e32 v132, v0
	v_mul_f32_e32 v0, 0xbfb8aa3b, v141
	v_exp_f32_e32 v0, v0
	v_pk_mul_f32 v[134:135], v[136:137], v[138:139]
	v_add_f32_e32 v0, 1.0, v0
	v_pk_mul_f32 v[88:89], v[88:89], v[134:135]
	v_rcp_f32_e32 v134, v0
	v_mul_f32_e32 v0, 0xbfb8aa3b, v153
	v_exp_f32_e32 v133, v0
	v_mul_f32_e32 v0, 0xbfb8aa3b, v142
	v_exp_f32_e32 v0, v0
	v_pk_add_f32 v[132:133], v[132:133], 1.0 op_sel_hi:[1,0]
	v_add_f32_e32 v0, 1.0, v0
	v_rcp_f32_e32 v135, v0
	v_mul_f32_e32 v0, 0xbfb8aa3b, v154
	v_exp_f32_e32 v136, v0
	v_mul_f32_e32 v0, 0xbfb8aa3b, v143
	v_exp_f32_e32 v0, v0
	v_pk_mul_f32 v[132:133], v[132:133], v[134:135]
	v_add_f32_e32 v0, 1.0, v0
	v_rcp_f32_e32 v138, v0
	v_mul_f32_e32 v0, 0xbfb8aa3b, v155
	v_exp_f32_e32 v137, v0
	v_mul_f32_e32 v0, 0xbfb8aa3b, v144
	v_exp_f32_e32 v0, v0
	v_pk_mul_f32 v[82:83], v[82:83], v[132:133]
	v_pk_add_f32 v[136:137], v[136:137], 1.0 op_sel_hi:[1,0]
	v_add_f32_e32 v0, 1.0, v0
	v_rcp_f32_e32 v139, v0
	s_nop 0
	v_pk_mul_f32 v[134:135], v[136:137], v[138:139]
	v_or_b32_e32 v136, 0x3000, v130
	v_mov_b32_e32 v137, s27
	v_pk_mul_f32 v[84:85], v[84:85], v[134:135]
	s_waitcnt vmcnt(7)
	v_lshlrev_b32_e32 v0, 16, v156
	v_and_b32_e32 v138, 0xffff0000, v156
	v_lshlrev_b32_e32 v139, 16, v157
	v_and_b32_e32 v140, 0xffff0000, v157
	v_lshlrev_b32_e32 v141, 16, v158
	v_and_b32_e32 v142, 0xffff0000, v158
	v_lshlrev_b32_e32 v143, 16, v159
	v_and_b32_e32 v144, 0xffff0000, v159
	v_mul_f32_e32 v0, 0xbfb8aa3b, v0
	v_exp_f32_e32 v0, v0
	s_waitcnt vmcnt(6)
; DI uint4 ld_nt16(const void* q) { const ntu4 t = __builtin_nontemporal_load((const ntu4*)q); uint4 v; v.x = t[0]; v.y = t[1]; v.z = t[2]; v.w = t[3]; return v; }
; DI float frcp(float x) { return __builtin_amdgcn_rcpf(x); }
; template <int CT>
; DI void phase_g2(int c, int l) {
;     ...
;     for (int n = 0; n < 4; ++n) {
; #pragma unroll
;       for (int mp = 0; mp < 4; ++mp) {
;         const size_t fo = frag_off(pm, pn, wid, n, mp, lane);
;         float a8[8], b8[8];
;         unpack8(ld_nt16(WSU(MGA) + fo), a8); unpack8(ld_nt16(WSU(MGB) + fo), b8);
; #pragma unroll
;         for (int j = 0; j < 8; ++j) acc[mp * 2 + (j >> 2)][n][j & 3] *= (1.f + __expf(-b8[j])) * frcp(1.f + __expf(-a8[j]));
;       }
	v_and_b32_e32 v137, 0xffff0000, v160
	v_add_f32_e32 v0, 1.0, v0
	v_lshlrev_b32_e32 v152, 16, v162
	v_and_b32_e32 v153, 0xffff0000, v162
	v_rcp_f32_e32 v134, v0
	v_mul_f32_e32 v0, 0xbfb8aa3b, v137
	v_lshlrev_b32_e32 v145, 16, v161
	v_and_b32_e32 v151, 0xffff0000, v161
	v_exp_f32_e32 v133, v0
	v_mul_f32_e32 v0, 0xbfb8aa3b, v138
	v_exp_f32_e32 v0, v0
	v_lshlrev_b32_e32 v136, 16, v160
	v_lshlrev_b32_e32 v154, 16, v163
	v_and_b32_e32 v155, 0xffff0000, v163
	v_add_f32_e32 v0, 1.0, v0
	v_rcp_f32_e32 v135, v0
	v_mul_f32_e32 v0, 0xbfb8aa3b, v145
	v_mul_f32_e32 v132, 0xbfb8aa3b, v136
	v_exp_f32_e32 v136, v0
	v_mul_f32_e32 v0, 0xbfb8aa3b, v139
	v_exp_f32_e32 v0, v0
	v_exp_f32_e32 v132, v132
	v_add_f32_e32 v0, 1.0, v0
	v_rcp_f32_e32 v138, v0
	v_mul_f32_e32 v0, 0xbfb8aa3b, v151
	v_exp_f32_e32 v137, v0
	v_mul_f32_e32 v0, 0xbfb8aa3b, v140
	v_exp_f32_e32 v0, v0
	v_pk_add_f32 v[132:133], v[132:133], 1.0 op_sel_hi:[1,0]
	v_pk_add_f32 v[136:137], v[136:137], 1.0 op_sel_hi:[1,0]
	v_pk_mul_f32 v[132:133], v[132:133], v[134:135]
	v_add_f32_e32 v0, 1.0, v0
	v_rcp_f32_e32 v139, v0
	v_mul_f32_e32 v0, 0xbfb8aa3b, v152
	v_pk_mul_f32 v[70:71], v[70:71], v[132:133]
	v_exp_f32_e32 v132, v0
	v_mul_f32_e32 v0, 0xbfb8aa3b, v141
	v_exp_f32_e32 v0, v0
	v_pk_mul_f32 v[134:135], v[136:137], v[138:139]
	v_add_f32_e32 v0, 1.0, v0
	v_pk_mul_f32 v[72:73], v[72:73], v[134:135]
	v_rcp_f32_e32 v134, v0
	v_mul_f32_e32 v0, 0xbfb8aa3b, v153
	v_exp_f32_e32 v133, v0
	v_mul_f32_e32 v0, 0xbfb8aa3b, v142
	v_exp_f32_e32 v0, v0
	v_pk_add_f32 v[132:133], v[132:133], 1.0 op_sel_hi:[1,0]
	v_add_f32_e32 v0, 1.0, v0
	v_rcp_f32_e32 v135, v0
	v_mul_f32_e32 v0, 0xbfb8aa3b, v154
	v_exp_f32_e32 v136, v0
	v_mul_f32_e32 v0, 0xbfb8aa3b, v143
	v_exp_f32_e32 v0, v0
	v_pk_mul_f32 v[132:133], v[132:133], v[134:135]
	v_add_f32_e32 v0, 1.0, v0
	v_rcp_f32_e32 v138, v0
	v_mul_f32_e32 v0, 0xbfb8aa3b, v155
	v_exp_f32_e32 v137, v0
	v_mul_f32_e32 v0, 0xbfb8aa3b, v144
	v_exp_f32_e32 v0, v0
	v_pk_mul_f32 v[66:67], v[66:67], v[132:133]
	v_pk_add_f32 v[136:137], v[136:137], 1.0 op_sel_hi:[1,0]
	v_add_f32_e32 v0, 1.0, v0
	v_rcp_f32_e32 v139, v0
	s_nop 0
	v_pk_mul_f32 v[134:135], v[136:137], v[138:139]
	v_or_b32_e32 v136, 0x3400, v130
	v_mov_b32_e32 v137, s27
	v_pk_mul_f32 v[68:69], v[68:69], v[134:135]
	s_waitcnt vmcnt(5)
	v_lshlrev_b32_e32 v0, 16, v164
	v_and_b32_e32 v138, 0xffff0000, v164
	v_lshlrev_b32_e32 v139, 16, v165
	v_and_b32_e32 v140, 0xffff0000, v165
	v_lshlrev_b32_e32 v141, 16, v166
	v_and_b32_e32 v142, 0xffff0000, v166
	v_lshlrev_b32_e32 v143, 16, v167
	v_and_b32_e32 v144, 0xffff0000, v167
	v_mul_f32_e32 v0, 0xbfb8aa3b, v0
	v_exp_f32_e32 v0, v0
	s_waitcnt vmcnt(4)
	v_and_b32_e32 v137, 0xffff0000, v168
	v_add_f32_e32 v0, 1.0, v0
	v_lshlrev_b32_e32 v152, 16, v170
	v_and_b32_e32 v153, 0xffff0000, v170
	v_rcp_f32_e32 v134, v0
	v_mul_f32_e32 v0, 0xbfb8aa3b, v137
	v_lshlrev_b32_e32 v145, 16, v169
	v_and_b32_e32 v151, 0xffff0000, v169
	v_exp_f32_e32 v133, v0
	v_mul_f32_e32 v0, 0xbfb8aa3b, v138
	v_exp_f32_e32 v0, v0
	v_lshlrev_b32_e32 v136, 16, v168
	v_lshlrev_b32_e32 v154, 16, v171
	v_and_b32_e32 v155, 0xffff0000, v171
	v_add_f32_e32 v0, 1.0, v0
	v_rcp_f32_e32 v135, v0
	v_mul_f32_e32 v0, 0xbfb8aa3b, v145
	v_mul_f32_e32 v132, 0xbfb8aa3b, v136
	v_exp_f32_e32 v136, v0
	v_mul_f32_e32 v0, 0xbfb8aa3b, v139
	v_exp_f32_e32 v0, v0
	v_exp_f32_e32 v132, v132
	v_add_f32_e32 v0, 1.0, v0
	v_rcp_f32_e32 v138, v0
	v_mul_f32_e32 v0, 0xbfb8aa3b, v151
	v_exp_f32_e32 v137, v0
	v_mul_f32_e32 v0, 0xbfb8aa3b, v140
	v_exp_f32_e32 v0, v0
	v_pk_add_f32 v[132:133], v[132:133], 1.0 op_sel_hi:[1,0]
	v_pk_add_f32 v[136:137], v[136:137], 1.0 op_sel_hi:[1,0]
	v_pk_mul_f32 v[132:133], v[132:133], v[134:135]
	v_add_f32_e32 v0, 1.0, v0
	v_rcp_f32_e32 v139, v0
	v_mul_f32_e32 v0, 0xbfb8aa3b, v152
	v_pk_mul_f32 v[54:55], v[54:55], v[132:133]
	v_exp_f32_e32 v132, v0
	v_mul_f32_e32 v0, 0xbfb8aa3b, v141
	v_exp_f32_e32 v0, v0
	v_pk_mul_f32 v[134:135], v[136:137], v[138:139]
	v_add_f32_e32 v0, 1.0, v0
	v_pk_mul_f32 v[56:57], v[56:57], v[134:135]
	v_rcp_f32_e32 v134, v0
	v_mul_f32_e32 v0, 0xbfb8aa3b, v153
	v_exp_f32_e32 v133, v0
	v_mul_f32_e32 v0, 0xbfb8aa3b, v142
	v_exp_f32_e32 v0, v0
	v_pk_add_f32 v[132:133], v[132:133], 1.0 op_sel_hi:[1,0]
	v_add_f32_e32 v0, 1.0, v0
	v_rcp_f32_e32 v135, v0
	v_mul_f32_e32 v0, 0xbfb8aa3b, v154
	v_exp_f32_e32 v136, v0
	v_mul_f32_e32 v0, 0xbfb8aa3b, v143
	v_exp_f32_e32 v0, v0
	v_pk_mul_f32 v[132:133], v[132:133], v[134:135]
	v_add_f32_e32 v0, 1.0, v0
	v_rcp_f32_e32 v138, v0
	v_mul_f32_e32 v0, 0xbfb8aa3b, v155
	v_exp_f32_e32 v137, v0
	v_mul_f32_e32 v0, 0xbfb8aa3b, v144
	v_exp_f32_e32 v0, v0
	v_pk_mul_f32 v[50:51], v[50:51], v[132:133]
	v_pk_add_f32 v[136:137], v[136:137], 1.0 op_sel_hi:[1,0]
	v_add_f32_e32 v0, 1.0, v0
	v_rcp_f32_e32 v139, v0
	s_nop 0
	v_pk_mul_f32 v[134:135], v[136:137], v[138:139]
	v_or_b32_e32 v136, 0x3800, v130
	v_mov_b32_e32 v137, s27
	v_pk_mul_f32 v[52:53], v[52:53], v[134:135]
	v_or_b32_e32 v130, 0x3c00, v130
	s_lshl_b32 s27, s21, 12
	s_add_i32 s28, s27, 0x18000
	s_and_b32 s21, s27, 0xffffc000
	s_and_b32 s28, s28, 0xffffe000
	s_add_u32 s22, s67, s22
	s_addc_u32 s23, s81, s23
	s_add_u32 s24, s84, s24
	s_addc_u32 s25, s85, s25
	s_waitcnt vmcnt(3)
	v_lshlrev_b32_e32 v0, 16, v172
	v_and_b32_e32 v138, 0xffff0000, v172
	v_lshlrev_b32_e32 v139, 16, v173
	v_and_b32_e32 v140, 0xffff0000, v173
	v_lshlrev_b32_e32 v141, 16, v174
	v_and_b32_e32 v142, 0xffff0000, v174
	v_lshlrev_b32_e32 v143, 16, v175
	v_and_b32_e32 v144, 0xffff0000, v175
	v_mul_f32_e32 v0, 0xbfb8aa3b, v0
	v_exp_f32_e32 v0, v0
	s_waitcnt vmcnt(2)
; DI uint4 ld_nt16(const void* q) { const ntu4 t = __builtin_nontemporal_load((const ntu4*)q); uint4 v; v.x = t[0]; v.y = t[1]; v.z = t[2]; v.w = t[3]; return v; }
; DI int uni(int v) { return __builtin_amdgcn_readfirstlane(v); }
; DI float frcp(float x) { return __builtin_amdgcn_rcpf(x); }
; #define WAIT_V0() asm volatile("s_waitcnt vmcnt(0)" ::: "memory")
; DI void gemm_core(const int tid, const u16* __restrict__ Wb, int ldw, const u16* __restrict__ Xb, int ldx, int K, f32x4 (&acc)[8][4], const bool pre = false) {
;   const int wid = uni(tid >> 6), lane = tid & 63, wr = wid >> 2, wc = wid & 3, fr = lane & 15, fq = lane >> 4;
;   int offw[4], offx[4];
; #pragma unroll
;   for (int i = 0; i < 4; ++i) {
;     int R, C; stage_rc(wid * 1024 + i * 8192 + lane * 16, R, C);
;     offw[i] = R * ldw + C; offx[i] = R * ldx + C;
;   }
;   auto stage = [&](int buf, int kt) {
; #pragma unroll
;     for (int i = 0; i < 4; ++i) {
;       __builtin_amdgcn_global_load_lds((const unsigned*)(Wb + offw[i] + kt * 64), (unsigned*)(shm + buf * STAGE_B + wid * 1024 + i * 8192), 16, 0, 0);
;       __builtin_amdgcn_global_load_lds((const unsigned*)(Xb + offx[i] + kt * 64), (unsigned*)(shm + buf * STAGE_B + TILE_B + wid * 1024 + i * 8192), 16, 0, 0);
;     }
;   };
;   const int nt = K >> 6;
;   if (!pre) stage(0, 0);
;   WAIT_V0(); __syncthreads();
; template <int CT>
; DI void phase_g2(int c, int l) {
;     ...
;         const size_t fo = frag_off(pm, pn, wid, n, mp, lane);
;         float a8[8], b8[8];
;         unpack8(ld_nt16(WSU(MGA) + fo), a8); unpack8(ld_nt16(WSU(MGB) + fo), b8);
; #pragma unroll
;         for (int j = 0; j < 8; ++j) acc[mp * 2 + (j >> 2)][n][j & 3] *= (1.f + __expf(-b8[j])) * frcp(1.f + __expf(-a8[j]));
;       }
	v_and_b32_e32 v137, 0xffff0000, v232
	v_add_f32_e32 v0, 1.0, v0
	v_lshlrev_b32_e32 v152, 16, v234
	v_and_b32_e32 v153, 0xffff0000, v234
	v_rcp_f32_e32 v134, v0
	v_mul_f32_e32 v0, 0xbfb8aa3b, v137
	v_lshlrev_b32_e32 v145, 16, v233
	v_and_b32_e32 v151, 0xffff0000, v233
	v_exp_f32_e32 v133, v0
	v_mul_f32_e32 v0, 0xbfb8aa3b, v138
	v_exp_f32_e32 v0, v0
	v_lshlrev_b32_e32 v136, 16, v232
	v_lshlrev_b32_e32 v154, 16, v235
	v_and_b32_e32 v155, 0xffff0000, v235
	v_add_f32_e32 v0, 1.0, v0
	v_rcp_f32_e32 v135, v0
	v_mul_f32_e32 v0, 0xbfb8aa3b, v145
	v_mul_f32_e32 v132, 0xbfb8aa3b, v136
	v_exp_f32_e32 v136, v0
	v_mul_f32_e32 v0, 0xbfb8aa3b, v139
	v_exp_f32_e32 v0, v0
	v_exp_f32_e32 v132, v132
	v_add_f32_e32 v0, 1.0, v0
	v_rcp_f32_e32 v138, v0
	v_mul_f32_e32 v0, 0xbfb8aa3b, v151
	v_exp_f32_e32 v137, v0
	v_mul_f32_e32 v0, 0xbfb8aa3b, v140
	v_exp_f32_e32 v0, v0
	v_pk_add_f32 v[132:133], v[132:133], 1.0 op_sel_hi:[1,0]
	v_pk_add_f32 v[136:137], v[136:137], 1.0 op_sel_hi:[1,0]
	v_pk_mul_f32 v[132:133], v[132:133], v[134:135]
	v_add_f32_e32 v0, 1.0, v0
	v_rcp_f32_e32 v139, v0
	v_mul_f32_e32 v0, 0xbfb8aa3b, v152
	v_pk_mul_f32 v[38:39], v[38:39], v[132:133]
	v_exp_f32_e32 v132, v0
	v_mul_f32_e32 v0, 0xbfb8aa3b, v141
	v_exp_f32_e32 v0, v0
	v_pk_mul_f32 v[134:135], v[136:137], v[138:139]
	v_add_f32_e32 v0, 1.0, v0
	v_pk_mul_f32 v[40:41], v[40:41], v[134:135]
	v_rcp_f32_e32 v134, v0
	v_mul_f32_e32 v0, 0xbfb8aa3b, v153
	v_exp_f32_e32 v133, v0
	v_mul_f32_e32 v0, 0xbfb8aa3b, v142
	v_exp_f32_e32 v0, v0
	v_pk_add_f32 v[132:133], v[132:133], 1.0 op_sel_hi:[1,0]
	v_add_f32_e32 v0, 1.0, v0
	v_rcp_f32_e32 v135, v0
	v_mul_f32_e32 v0, 0xbfb8aa3b, v154
	v_exp_f32_e32 v136, v0
	v_mul_f32_e32 v0, 0xbfb8aa3b, v143
	v_exp_f32_e32 v0, v0
	v_pk_mul_f32 v[132:133], v[132:133], v[134:135]
	v_add_f32_e32 v0, 1.0, v0
	v_rcp_f32_e32 v138, v0
	v_mul_f32_e32 v0, 0xbfb8aa3b, v155
	v_exp_f32_e32 v137, v0
	v_mul_f32_e32 v0, 0xbfb8aa3b, v144
	v_exp_f32_e32 v0, v0
	v_pk_mul_f32 v[34:35], v[34:35], v[132:133]
	v_pk_add_f32 v[136:137], v[136:137], 1.0 op_sel_hi:[1,0]
	v_add_f32_e32 v0, 1.0, v0
	v_rcp_f32_e32 v139, v0
	v_pk_mul_f32 v[134:135], v[136:137], v[138:139]
	s_nop 0
	v_pk_mul_f32 v[36:37], v[36:37], v[134:135]
	s_waitcnt vmcnt(1)
	v_lshlrev_b32_e32 v0, 16, v236
	v_and_b32_e32 v136, 0xffff0000, v236
	v_lshlrev_b32_e32 v137, 16, v237
	v_and_b32_e32 v138, 0xffff0000, v237
	v_mul_f32_e32 v0, 0xbfb8aa3b, v0
	v_exp_f32_e32 v0, v0
	v_lshlrev_b32_e32 v141, 16, v239
	v_and_b32_e32 v142, 0xffff0000, v239
	v_lshlrev_b32_e32 v139, 16, v238
	v_add_f32_e32 v0, 1.0, v0
	v_and_b32_e32 v140, 0xffff0000, v238
	s_waitcnt vmcnt(0)
	s_waitcnt lgkmcnt(0)
	s_barrier
	s_waitcnt vmcnt(0)
	v_and_b32_e32 v135, 0xffff0000, v240
	v_lshlrev_b32_e32 v145, 16, v242
	v_and_b32_e32 v151, 0xffff0000, v242
	v_rcp_f32_e32 v132, v0
	v_mul_f32_e32 v0, 0xbfb8aa3b, v135
	v_lshlrev_b32_e32 v143, 16, v241
	v_and_b32_e32 v144, 0xffff0000, v241
	v_exp_f32_e32 v131, v0
	v_mul_f32_e32 v0, 0xbfb8aa3b, v136
	v_exp_f32_e32 v0, v0
	v_lshlrev_b32_e32 v134, 16, v240
	v_lshlrev_b32_e32 v152, 16, v243
	v_and_b32_e32 v153, 0xffff0000, v243
	v_add_f32_e32 v0, 1.0, v0
	v_rcp_f32_e32 v133, v0
	v_mul_f32_e32 v0, 0xbfb8aa3b, v143
	v_mul_f32_e32 v130, 0xbfb8aa3b, v134
	v_exp_f32_e32 v134, v0
	v_mul_f32_e32 v0, 0xbfb8aa3b, v137
	v_exp_f32_e32 v0, v0
	v_exp_f32_e32 v130, v130
	v_add_f32_e32 v0, 1.0, v0
	v_rcp_f32_e32 v136, v0
	v_mul_f32_e32 v0, 0xbfb8aa3b, v144
	v_exp_f32_e32 v135, v0
	v_mul_f32_e32 v0, 0xbfb8aa3b, v138
	v_exp_f32_e32 v0, v0
	v_pk_add_f32 v[130:131], v[130:131], 1.0 op_sel_hi:[1,0]
	v_pk_add_f32 v[134:135], v[134:135], 1.0 op_sel_hi:[1,0]
	v_pk_mul_f32 v[130:131], v[130:131], v[132:133]
	v_add_f32_e32 v0, 1.0, v0
	v_rcp_f32_e32 v137, v0
	v_mul_f32_e32 v0, 0xbfb8aa3b, v145
	v_pk_mul_f32 v[14:15], v[14:15], v[130:131]
	v_exp_f32_e32 v130, v0
	v_mul_f32_e32 v0, 0xbfb8aa3b, v139
	v_exp_f32_e32 v0, v0
	v_pk_mul_f32 v[132:133], v[134:135], v[136:137]
	v_add_f32_e32 v0, 1.0, v0
	v_pk_mul_f32 v[16:17], v[16:17], v[132:133]
	v_rcp_f32_e32 v132, v0
	v_mul_f32_e32 v0, 0xbfb8aa3b, v151
	v_exp_f32_e32 v131, v0
	v_mul_f32_e32 v0, 0xbfb8aa3b, v140
	v_exp_f32_e32 v0, v0
	v_pk_add_f32 v[130:131], v[130:131], 1.0 op_sel_hi:[1,0]
	v_add_f32_e32 v0, 1.0, v0
	v_rcp_f32_e32 v133, v0
	v_mul_f32_e32 v0, 0xbfb8aa3b, v152
	v_exp_f32_e32 v134, v0
	v_mul_f32_e32 v0, 0xbfb8aa3b, v141
	v_exp_f32_e32 v0, v0
	v_pk_mul_f32 v[130:131], v[130:131], v[132:133]
	v_add_f32_e32 v0, 1.0, v0
	v_rcp_f32_e32 v136, v0
	v_mul_f32_e32 v0, 0xbfb8aa3b, v153
	v_exp_f32_e32 v135, v0
	v_mul_f32_e32 v0, 0xbfb8aa3b, v142
	v_exp_f32_e32 v0, v0
	v_pk_mul_f32 v[10:11], v[10:11], v[130:131]
	v_or_b32_e32 v130, s28, v147
	s_add_i32 s28, s27, 0x10000
	v_add_f32_e32 v0, 1.0, v0
	v_rcp_f32_e32 v137, v0
	v_pk_add_f32 v[134:135], v[134:135], 1.0 op_sel_hi:[1,0]
	s_and_b32 s28, s28, 0xffffe000
	v_add3_u32 v130, v130, v149, s26
	v_pk_mul_f32 v[132:133], v[134:135], v[136:137]
	v_or_b32_e32 v134, s28, v147
	s_add_i32 s28, s27, 0x8000
	s_and_b32 s28, s28, 0xffffe000
	s_and_b32 s27, s27, 0xffffe000
	v_or_b32_e32 v138, s28, v147
	v_or_b32_e32 v142, s27, v147
	v_add3_u32 v134, v134, v149, s26
	v_add3_u32 v138, v138, v149, s26
	v_add3_u32 v142, v142, v149, s26
	v_lshlrev_b32_e32 v0, 2, v148
	v_ashrrev_i32_e32 v131, 31, v130
	v_ashrrev_i32_e32 v135, 31, v134
	v_ashrrev_i32_e32 v139, 31, v138
	v_ashrrev_i32_e32 v143, 31, v142
	v_pk_mul_f32 v[12:13], v[12:13], v[132:133]
	v_and_b32_e32 v0, 32, v0
	v_lshlrev_b64 v[132:133], 1, v[130:131]
	v_lshlrev_b64 v[136:137], 1, v[134:135]
	v_lshlrev_b64 v[140:141], 1, v[138:139]
	v_lshlrev_b64 v[144:145], 1, v[142:143]
	v_bitop3_b32 v0, v194, v0, v193 bitop3:0x36
	v_lshl_add_u64 v[130:131], s[22:23], 0, v[132:133]
	v_lshl_add_u64 v[132:133], s[24:25], 0, v[132:133]
	v_lshl_add_u64 v[134:135], s[22:23], 0, v[136:137]
	v_lshl_add_u64 v[136:137], s[24:25], 0, v[136:137]
	v_lshl_add_u64 v[138:139], s[22:23], 0, v[140:141]
	v_lshl_add_u64 v[140:141], s[24:25], 0, v[140:141]
	v_lshl_add_u64 v[142:143], s[22:23], 0, v[144:145]
	v_lshl_add_u64 v[144:145], s[24:25], 0, v[144:145]
	s_mov_b32 s24, 0
	s_mov_b64 s[22:23], 0

; DI int uni(int v) { return __builtin_amdgcn_readfirstlane(v); }
; #define WAIT_V0() asm volatile("s_waitcnt vmcnt(0)" ::: "memory")
; DI void gemm_core_q(const int tid, const u8* __restrict__ Wb, const u8* __restrict__ Xb, f32x4 (&acc)[8][4]) {
;   const int wid = uni(tid >> 6), lane = tid & 63, wr = wid >> 2, wc = wid & 3, fr = lane & 15, fq = lane >> 4;
;   int off[4];
; #pragma unroll
;   for (int i = 0; i < 4; ++i) off[i] = stage_off_q(wid * 1024 + i * 8192 + lane * 16);
;   auto stage = [&](int buf, int kt) {
; #pragma unroll
;     for (int i = 0; i < 4; ++i) {
;       __builtin_amdgcn_global_load_lds((const unsigned*)(Wb + off[i] + kt * 128), (unsigned*)(shm + buf * STAGE_B + wid * 1024 + i * 8192), 16, 0, 0);
;       __builtin_amdgcn_global_load_lds((const unsigned*)(Xb + off[i] + kt * 128), (unsigned*)(shm + buf * STAGE_B + TILE_B + wid * 1024 + i * 8192), 16, 0, 0);
;     }
;   };
;   stage(0, 0); WAIT_V0(); __syncthreads();
;   for (int t = 0; t < 8; ++t) {
;     const int cur = t & 1;
;     if (t + 1 < 8) stage(cur ^ 1, t + 1);
;     i32x8 At[8], Bf[4];
;     const int qb = lds_byte_q(wc * 64 + fr, fq * 2), qa = lds_byte_q(wr * 128 + fr, fq * 2);
;     const char* pb = shm + cur * STAGE_B + TILE_B + qb;
;     const char* pb2 = shm + cur * STAGE_B + TILE_B + (qb ^ 16);
;     const char* pa = shm + cur * STAGE_B + qa;
;     const char* pa2 = shm + cur * STAGE_B + (qa ^ 16);
; #pragma unroll
;     for (int n = 0; n < 4; ++n) {
;       const i32x4 lo = *(const i32x4*)(pb + n * 2048);
;       const i32x4 hi = *(const i32x4*)(pb2 + n * 2048);
;       Bf[n] = __builtin_shufflevector(lo, hi, 0, 1, 2, 3, 4, 5, 6, 7);
;     }
; #pragma unroll
;     for (int m = 0; m < 8; ++m) {
;       const i32x4 lo = *(const i32x4*)(pa + m * 2048);
;       const i32x4 hi = *(const i32x4*)(pa2 + m * 2048);
;       At[m] = __builtin_shufflevector(lo, hi, 0, 1, 2, 3, 4, 5, 6, 7);
;     }
.LBB0_496:
	s_ashr_i32 s25, s24, 31
	s_lshl_b64 s[4:5], s[24:25], 10
	s_add_u32 s4, s35, s4
	s_addc_u32 s5, s36, s5
	s_ashr_i32 s21, s20, 31
	s_lshl_b64 s[6:7], s[20:21], 10
	s_add_u32 s6, s45, s6
	v_readfirstlane_b32 s8, v18
	v_lshrrev_b32_e32 v2, 2, v18
	s_addc_u32 s7, s46, s7
	s_ashr_i32 s9, s8, 6
	v_bfe_u32 v4, v2, 2, 2
	v_bfe_u32 v2, v2, 3, 1
	s_lshl_b32 s26, s9, 10
	v_xor_b32_e32 v2, v2, v4
	s_lshl_b32 s23, s9, 3
	v_lshlrev_b32_e32 v0, 4, v18
	v_bfe_u32 v3, v18, 2, 4
	v_lshlrev_b32_e32 v2, 4, v2
	s_and_b32 s23, s23, 0x3ffff0
	s_add_i32 s29, s26, 0x2000
	v_bitop3_b32 v0, v2, v0, 48 bitop3:0x78
	v_or_b32_e32 v2, s23, v3
	s_lshr_b32 s23, s29, 7
	v_and_or_b32 v0, s8, 64, v0
	s_and_b32 s23, s23, 0x3ffff0
	s_add_i32 s28, s26, 0x4000
	v_lshl_or_b32 v4, v2, 10, v0
	v_or_b32_e32 v2, s23, v3
	s_lshr_b32 s23, s28, 7
	s_and_b32 s23, s23, 0x3ffff0
	s_add_i32 s27, s26, 0x6000
	v_lshl_or_b32 v8, v2, 10, v0
	v_or_b32_e32 v2, s23, v3
	s_lshr_b32 s23, s27, 7
	s_and_b32 s23, s23, 0x3ffff0
	v_lshl_or_b32 v12, v2, 10, v0
	v_or_b32_e32 v2, s23, v3
	v_ashrrev_i32_e32 v5, 31, v4
	v_lshl_or_b32 v16, v2, 10, v0
	v_lshl_add_u64 v[2:3], s[4:5], 0, v[4:5]
	s_mov_b32 m0, s26
	s_add_i32 s54, s26, 0x8000
	global_load_lds_dwordx4 v[2:3], off
	v_lshl_add_u64 v[4:5], s[6:7], 0, v[4:5]
	s_mov_b32 m0, s54
	v_ashrrev_i32_e32 v9, 31, v8
	global_load_lds_dwordx4 v[4:5], off
	v_lshl_add_u64 v[6:7], s[4:5], 0, v[8:9]
	s_mov_b32 m0, s29
	s_add_i32 s72, s26, 0xa000
	v_ashrrev_i32_e32 v13, 31, v12
	v_ashrrev_i32_e32 v17, 31, v16
	global_load_lds_dwordx4 v[6:7], off
	v_lshl_add_u64 v[8:9], s[6:7], 0, v[8:9]
	s_mov_b32 m0, s72
	v_lshl_add_u64 v[10:11], s[4:5], 0, v[12:13]
	v_lshl_add_u64 v[14:15], s[4:5], 0, v[16:17]
	s_lshr_b32 s4, s8, 3
	v_bfe_u32 v20, v18, 5, 1
	v_and_b32_e32 v0, 15, v18
	global_load_lds_dwordx4 v[8:9], off
	s_mov_b32 m0, s28
	s_add_i32 s73, s26, 0xc000
	v_lshrrev_b32_e32 v19, 3, v18
	v_and_or_b32 v21, s4, 24, v20
	v_bfe_u32 v22, v18, 2, 2
	v_bfe_u32 v18, v18, 3, 1
	s_lshl_b32 s4, s9, 2
	global_load_lds_dwordx4 v[10:11], off
	v_lshl_add_u64 v[12:13], s[6:7], 0, v[12:13]
	s_mov_b32 m0, s73
	v_and_b32_e32 v19, 2, v19
	v_xor_b32_e32 v18, v18, v22
	s_and_b32 s4, s4, 0x3ffff0
	global_load_lds_dwordx4 v[12:13], off
	s_mov_b32 m0, s27
	s_add_i32 s74, s26, 0xe000
	v_lshlrev_b32_e32 v0, 6, v0
	v_xor_b32_e32 v18, v18, v19
	v_or_b32_e32 v20, s4, v20
	global_load_lds_dwordx4 v[14:15], off
	v_lshl_add_u64 v[16:17], s[6:7], 0, v[16:17]
	s_mov_b32 m0, s74
	v_lshl_or_b32 v21, v21, 10, v0
	v_lshlrev_b32_e32 v18, 4, v18
	v_lshl_or_b32 v22, v20, 10, v0
	s_add_i32 s9, s26, 0x10000
	global_load_lds_dwordx4 v[16:17], off
	v_or_b32_e32 v19, v21, v18
	v_or_b32_e32 v0, v22, v18
	v_bitop3_b32 v20, v21, 16, v18 bitop3:0x36
	v_bitop3_b32 v18, v22, 16, v18 bitop3:0x36
	s_add_i32 s4, s26, 0x18000
	s_waitcnt vmcnt(0)
	s_waitcnt vmcnt(0) lgkmcnt(0)
	s_barrier
	s_add_i32 s5, s26, 0x12000
	s_add_i32 s6, s26, 0x1a000
	s_add_i32 s7, s26, 0x14000
	s_add_i32 s8, s26, 0x1c000
	s_add_i32 s23, s26, 0x16000
	s_add_i32 s25, s26, 0x1e000
	ds_read_b128 v[22:25], v0
	ds_read_b128 v[26:29], v18
	ds_read_b128 v[30:33], v19 offset:32768
	ds_read_b128 v[34:37], v20 offset:32768
	ds_read_b128 v[38:41], v19 offset:34816
	ds_read_b128 v[42:45], v20 offset:34816
	ds_read_b128 v[46:49], v19 offset:36864
	ds_read_b128 v[50:53], v20 offset:36864
	ds_read_b128 v[54:57], v19 offset:38912
	ds_read_b128 v[58:61], v20 offset:38912
	v_lshl_add_u64 v[2:3], v[2:3], 0, s[64:65]
	s_mov_b32 m0, s9
	s_nop 0
	global_load_lds_dwordx4 v[2:3], off
	s_waitcnt lgkmcnt(0)
	v_mfma_scale_f32_16x16x128_f8f6f4 v[74:77], v[22:29], v[30:37], 0, v212, v212 op_sel_hi:[0,0,0]
	ds_read_b128 v[62:65], v0 offset:2048
	ds_read_b128 v[66:69], v18 offset:2048
	v_lshl_add_u64 v[4:5], v[4:5], 0, s[64:65]
	s_mov_b32 m0, s4
	s_nop 0
	global_load_lds_dwordx4 v[4:5], off
	v_mfma_scale_f32_16x16x128_f8f6f4 v[82:85], v[22:29], v[38:45], 0, v212, v212 op_sel_hi:[0,0,0]
	v_mfma_scale_f32_16x16x128_f8f6f4 v[86:89], v[22:29], v[46:53], 0, v212, v212 op_sel_hi:[0,0,0]
	v_lshl_add_u64 v[6:7], v[6:7], 0, s[64:65]
	s_mov_b32 m0, s5
	s_nop 0
	global_load_lds_dwordx4 v[6:7], off
	v_mfma_scale_f32_16x16x128_f8f6f4 v[90:93], v[22:29], v[54:61], 0, v212, v212 op_sel_hi:[0,0,0]
	s_waitcnt lgkmcnt(0)
	v_mfma_scale_f32_16x16x128_f8f6f4 v[94:97], v[62:69], v[30:37], 0, v212, v212 op_sel_hi:[0,0,0]
	ds_read_b128 v[22:25], v0 offset:4096
	ds_read_b128 v[26:29], v18 offset:4096
	v_lshl_add_u64 v[8:9], v[8:9], 0, s[64:65]
	s_mov_b32 m0, s6
	s_nop 0
	global_load_lds_dwordx4 v[8:9], off
	v_mfma_scale_f32_16x16x128_f8f6f4 v[98:101], v[62:69], v[38:45], 0, v212, v212 op_sel_hi:[0,0,0]
	v_mfma_scale_f32_16x16x128_f8f6f4 v[102:105], v[62:69], v[46:53], 0, v212, v212 op_sel_hi:[0,0,0]
	v_lshl_add_u64 v[10:11], v[10:11], 0, s[64:65]
	s_mov_b32 m0, s7
	s_nop 0
	global_load_lds_dwordx4 v[10:11], off
	v_mfma_scale_f32_16x16x128_f8f6f4 v[106:109], v[62:69], v[54:61], 0, v212, v212 op_sel_hi:[0,0,0]
	s_waitcnt lgkmcnt(0)
	v_mfma_scale_f32_16x16x128_f8f6f4 v[110:113], v[22:29], v[30:37], 0, v212, v212 op_sel_hi:[0,0,0]
	ds_read_b128 v[62:65], v0 offset:6144
	ds_read_b128 v[66:69], v18 offset:6144
	v_lshl_add_u64 v[12:13], v[12:13], 0, s[64:65]
	s_mov_b32 m0, s8
	s_nop 0
	global_load_lds_dwordx4 v[12:13], off
	v_mfma_scale_f32_16x16x128_f8f6f4 v[114:117], v[22:29], v[38:45], 0, v212, v212 op_sel_hi:[0,0,0]
	v_mfma_scale_f32_16x16x128_f8f6f4 v[118:121], v[22:29], v[46:53], 0, v212, v212 op_sel_hi:[0,0,0]
	v_lshl_add_u64 v[14:15], v[14:15], 0, s[64:65]
	s_mov_b32 m0, s23
	s_nop 0
	global_load_lds_dwordx4 v[14:15], off
	v_mfma_scale_f32_16x16x128_f8f6f4 v[122:125], v[22:29], v[54:61], 0, v212, v212 op_sel_hi:[0,0,0]
	s_waitcnt lgkmcnt(0)
; #define WAIT_V0() asm volatile("s_waitcnt vmcnt(0)" ::: "memory")
; DI void gemm_core_q(const int tid, const u8* __restrict__ Wb, const u8* __restrict__ Xb, f32x4 (&acc)[8][4]) {
;     ...
;   auto stage = [&](int buf, int kt) {
; #pragma unroll
;     for (int i = 0; i < 4; ++i) {
;       __builtin_amdgcn_global_load_lds((const unsigned*)(Wb + off[i] + kt * 128), (unsigned*)(shm + buf * STAGE_B + wid * 1024 + i * 8192), 16, 0, 0);
;       __builtin_amdgcn_global_load_lds((const unsigned*)(Xb + off[i] + kt * 128), (unsigned*)(shm + buf * STAGE_B + TILE_B + wid * 1024 + i * 8192), 16, 0, 0);
;     }
;   };
;   stage(0, 0); WAIT_V0(); __syncthreads();
;   for (int t = 0; t < 8; ++t) {
;     const int cur = t & 1;
;     if (t + 1 < 8) stage(cur ^ 1, t + 1);
;     i32x8 At[8], Bf[4];
;     const int qb = lds_byte_q(wc * 64 + fr, fq * 2), qa = lds_byte_q(wr * 128 + fr, fq * 2);
;     const char* pb = shm + cur * STAGE_B + TILE_B + qb;
;     const char* pb2 = shm + cur * STAGE_B + TILE_B + (qb ^ 16);
;     const char* pa = shm + cur * STAGE_B + qa;
;     const char* pa2 = shm + cur * STAGE_B + (qa ^ 16);
; #pragma unroll
;     for (int n = 0; n < 4; ++n) {
;       const i32x4 lo = *(const i32x4*)(pb + n * 2048);
;       const i32x4 hi = *(const i32x4*)(pb2 + n * 2048);
;       Bf[n] = __builtin_shufflevector(lo, hi, 0, 1, 2, 3, 4, 5, 6, 7);
;     }
; #pragma unroll
;     for (int m = 0; m < 8; ++m) {
;       const i32x4 lo = *(const i32x4*)(pa + m * 2048);
;       const i32x4 hi = *(const i32x4*)(pa2 + m * 2048);
;       At[m] = __builtin_shufflevector(lo, hi, 0, 1, 2, 3, 4, 5, 6, 7);
;     }
; #pragma unroll
;     for (int m = 0; m < 8; ++m)
; #pragma unroll
;       for (int n = 0; n < 4; ++n)
;         acc[m][n] = __builtin_amdgcn_mfma_scale_f32_16x16x128_f8f6f4(At[m], Bf[n], acc[m][n], 0, 0, 0, 0x7F7F7F7F, 0, 0x7F7F7F7F);
;     __builtin_amdgcn_sched_group_barrier(0x100, 10, 0);
; #pragma unroll
;     for (int m = 0; m < 8; ++m) {
;       __builtin_amdgcn_sched_group_barrier(0x008, 1, 0);
;       if (m < 7) __builtin_amdgcn_sched_group_barrier(0x100, 2, 0);
;       __builtin_amdgcn_sched_group_barrier(0x008, 3, 0);
;     }
;     __builtin_amdgcn_sched_barrier(0);
;     WAIT_V0(); __syncthreads();
	v_mfma_scale_f32_16x16x128_f8f6f4 v[126:129], v[62:69], v[30:37], 0, v212, v212 op_sel_hi:[0,0,0]
	ds_read_b128 v[22:25], v0 offset:8192
	ds_read_b128 v[26:29], v18 offset:8192
	v_lshl_add_u64 v[16:17], v[16:17], 0, s[64:65]
	s_mov_b32 m0, s25
	s_nop 0
	global_load_lds_dwordx4 v[16:17], off
	v_mfma_scale_f32_16x16x128_f8f6f4 v[130:133], v[62:69], v[38:45], 0, v212, v212 op_sel_hi:[0,0,0]
	v_mfma_scale_f32_16x16x128_f8f6f4 v[134:137], v[62:69], v[46:53], 0, v212, v212 op_sel_hi:[0,0,0]
	v_mfma_scale_f32_16x16x128_f8f6f4 v[138:141], v[62:69], v[54:61], 0, v212, v212 op_sel_hi:[0,0,0]
	s_waitcnt lgkmcnt(0)
	v_mfma_scale_f32_16x16x128_f8f6f4 v[142:145], v[22:29], v[30:37], 0, v212, v212 op_sel_hi:[0,0,0]
	ds_read_b128 v[62:65], v0 offset:10240
	ds_read_b128 v[66:69], v18 offset:10240
	v_mfma_scale_f32_16x16x128_f8f6f4 v[146:149], v[22:29], v[38:45], 0, v212, v212 op_sel_hi:[0,0,0]
	v_mfma_scale_f32_16x16x128_f8f6f4 v[150:153], v[22:29], v[46:53], 0, v212, v212 op_sel_hi:[0,0,0]
	v_mfma_scale_f32_16x16x128_f8f6f4 v[154:157], v[22:29], v[54:61], 0, v212, v212 op_sel_hi:[0,0,0]
	s_waitcnt lgkmcnt(0)
	v_mfma_scale_f32_16x16x128_f8f6f4 v[158:161], v[62:69], v[30:37], 0, v212, v212 op_sel_hi:[0,0,0]
	ds_read_b128 v[22:25], v0 offset:12288
	ds_read_b128 v[26:29], v18 offset:12288
	v_mfma_scale_f32_16x16x128_f8f6f4 v[162:165], v[62:69], v[38:45], 0, v212, v212 op_sel_hi:[0,0,0]
	v_mfma_scale_f32_16x16x128_f8f6f4 v[166:169], v[62:69], v[46:53], 0, v212, v212 op_sel_hi:[0,0,0]
	v_mfma_scale_f32_16x16x128_f8f6f4 v[170:173], v[62:69], v[54:61], 0, v212, v212 op_sel_hi:[0,0,0]
	s_waitcnt lgkmcnt(0)
	v_mfma_scale_f32_16x16x128_f8f6f4 v[174:177], v[22:29], v[30:37], 0, v212, v212 op_sel_hi:[0,0,0]
	ds_read_b128 v[62:65], v0 offset:14336
	ds_read_b128 v[66:69], v18 offset:14336
	v_mfma_scale_f32_16x16x128_f8f6f4 v[178:181], v[22:29], v[38:45], 0, v212, v212 op_sel_hi:[0,0,0]
	v_mfma_scale_f32_16x16x128_f8f6f4 v[182:185], v[22:29], v[46:53], 0, v212, v212 op_sel_hi:[0,0,0]
	v_mfma_scale_f32_16x16x128_f8f6f4 v[22:25], v[22:29], v[54:61], 0, v212, v212 op_sel_hi:[0,0,0]
	s_waitcnt lgkmcnt(0)
	v_mfma_scale_f32_16x16x128_f8f6f4 v[186:189], v[62:69], v[30:37], 0, v212, v212 op_sel_hi:[0,0,0]
	v_mfma_scale_f32_16x16x128_f8f6f4 v[190:193], v[62:69], v[38:45], 0, v212, v212 op_sel_hi:[0,0,0]
	v_mfma_scale_f32_16x16x128_f8f6f4 v[194:197], v[62:69], v[46:53], 0, v212, v212 op_sel_hi:[0,0,0]
	v_mfma_scale_f32_16x16x128_f8f6f4 v[198:201], v[62:69], v[54:61], 0, v212, v212 op_sel_hi:[0,0,0]
	s_waitcnt vmcnt(0)
	s_waitcnt vmcnt(0)
	s_barrier
	v_add_u32_e32 v38, 0x10000, v0
	v_add_u32_e32 v41, 0x10000, v18
	v_or_b32_e32 v39, 0x18000, v19
	v_add_u32_e32 v40, 0x18000, v20
	v_or_b32_e32 v21, 0x19000, v19
	ds_read_b128 v[42:45], v38
	ds_read_b128 v[46:49], v41
	ds_read_b128 v[28:31], v39
	ds_read_b128 v[32:35], v40
	v_or_b32_e32 v26, 0x18800, v19
	v_or_b32_e32 v27, 0x19800, v19
	ds_read_b128 v[50:53], v26
	ds_read_b128 v[54:57], v40 offset:2048
	ds_read_b128 v[58:61], v21
	ds_read_b128 v[62:65], v40 offset:4096
	ds_read_b128 v[66:69], v27
	ds_read_b128 v[70:73], v40 offset:6144
	v_lshl_add_u64 v[2:3], v[2:3], 0, s[64:65]
	s_mov_b32 m0, s26
	s_nop 0
	global_load_lds_dwordx4 v[2:3], off
	s_waitcnt lgkmcnt(0)
	v_mfma_scale_f32_16x16x128_f8f6f4 v[202:205], v[42:49], v[28:35], v[74:77], v212, v212 op_sel_hi:[0,0,0]
	ds_read_b128 v[78:81], v41 offset:2048
	s_nop 5
	ds_read_b128 v[74:77], v38 offset:2048
	v_lshl_add_u64 v[4:5], v[4:5], 0, s[64:65]
	s_mov_b32 m0, s54
	s_nop 0
	global_load_lds_dwordx4 v[4:5], off
	v_mfma_scale_f32_16x16x128_f8f6f4 v[82:85], v[42:49], v[50:57], v[82:85], v212, v212 op_sel_hi:[0,0,0]
	v_mfma_scale_f32_16x16x128_f8f6f4 v[86:89], v[42:49], v[58:65], v[86:89], v212, v212 op_sel_hi:[0,0,0]
	v_lshl_add_u64 v[6:7], v[6:7], 0, s[64:65]
	s_mov_b32 m0, s29
	s_nop 0
	global_load_lds_dwordx4 v[6:7], off
	v_mfma_scale_f32_16x16x128_f8f6f4 v[90:93], v[42:49], v[66:73], v[90:93], v212, v212 op_sel_hi:[0,0,0]
	s_waitcnt lgkmcnt(0)
	v_mfma_scale_f32_16x16x128_f8f6f4 v[94:97], v[74:81], v[28:35], v[94:97], v212, v212 op_sel_hi:[0,0,0]
	ds_read_b128 v[42:45], v38 offset:4096
	ds_read_b128 v[46:49], v41 offset:4096
	v_lshl_add_u64 v[8:9], v[8:9], 0, s[64:65]
	s_mov_b32 m0, s72
	s_nop 0
	global_load_lds_dwordx4 v[8:9], off
	v_mfma_scale_f32_16x16x128_f8f6f4 v[98:101], v[74:81], v[50:57], v[98:101], v212, v212 op_sel_hi:[0,0,0]
	v_mfma_scale_f32_16x16x128_f8f6f4 v[102:105], v[74:81], v[58:65], v[102:105], v212, v212 op_sel_hi:[0,0,0]
	v_lshl_add_u64 v[10:11], v[10:11], 0, s[64:65]
	s_mov_b32 m0, s28
	s_nop 0
	global_load_lds_dwordx4 v[10:11], off
	v_mfma_scale_f32_16x16x128_f8f6f4 v[106:109], v[74:81], v[66:73], v[106:109], v212, v212 op_sel_hi:[0,0,0]
	s_waitcnt lgkmcnt(0)
	v_mfma_scale_f32_16x16x128_f8f6f4 v[110:113], v[42:49], v[28:35], v[110:113], v212, v212 op_sel_hi:[0,0,0]
	ds_read_b128 v[74:77], v38 offset:6144
	ds_read_b128 v[78:81], v41 offset:6144
	v_lshl_add_u64 v[12:13], v[12:13], 0, s[64:65]
	s_mov_b32 m0, s73
	s_nop 0
	global_load_lds_dwordx4 v[12:13], off
	v_mfma_scale_f32_16x16x128_f8f6f4 v[114:117], v[42:49], v[50:57], v[114:117], v212, v212 op_sel_hi:[0,0,0]
	v_mfma_scale_f32_16x16x128_f8f6f4 v[118:121], v[42:49], v[58:65], v[118:121], v212, v212 op_sel_hi:[0,0,0]
	v_lshl_add_u64 v[14:15], v[14:15], 0, s[64:65]
	s_mov_b32 m0, s27
	s_nop 0
	global_load_lds_dwordx4 v[14:15], off
	v_mfma_scale_f32_16x16x128_f8f6f4 v[122:125], v[42:49], v[66:73], v[122:125], v212, v212 op_sel_hi:[0,0,0]
	s_waitcnt lgkmcnt(0)
; #define WAIT_V0() asm volatile("s_waitcnt vmcnt(0)" ::: "memory")
; DI void gemm_core_q(const int tid, const u8* __restrict__ Wb, const u8* __restrict__ Xb, f32x4 (&acc)[8][4]) {
;     ...
;   auto stage = [&](int buf, int kt) {
; #pragma unroll
;     for (int i = 0; i < 4; ++i) {
;       __builtin_amdgcn_global_load_lds((const unsigned*)(Wb + off[i] + kt * 128), (unsigned*)(shm + buf * STAGE_B + wid * 1024 + i * 8192), 16, 0, 0);
;       __builtin_amdgcn_global_load_lds((const unsigned*)(Xb + off[i] + kt * 128), (unsigned*)(shm + buf * STAGE_B + TILE_B + wid * 1024 + i * 8192), 16, 0, 0);
;     }
;   };
;   stage(0, 0); WAIT_V0(); __syncthreads();
;   for (int t = 0; t < 8; ++t) {
;     const int cur = t & 1;
;     if (t + 1 < 8) stage(cur ^ 1, t + 1);
;     i32x8 At[8], Bf[4];
;     const int qb = lds_byte_q(wc * 64 + fr, fq * 2), qa = lds_byte_q(wr * 128 + fr, fq * 2);
;     const char* pb = shm + cur * STAGE_B + TILE_B + qb;
;     const char* pb2 = shm + cur * STAGE_B + TILE_B + (qb ^ 16);
;     const char* pa = shm + cur * STAGE_B + qa;
;     const char* pa2 = shm + cur * STAGE_B + (qa ^ 16);
; #pragma unroll
;     for (int n = 0; n < 4; ++n) {
;       const i32x4 lo = *(const i32x4*)(pb + n * 2048);
;       const i32x4 hi = *(const i32x4*)(pb2 + n * 2048);
;       Bf[n] = __builtin_shufflevector(lo, hi, 0, 1, 2, 3, 4, 5, 6, 7);
;     }
; #pragma unroll
;     for (int m = 0; m < 8; ++m) {
;       const i32x4 lo = *(const i32x4*)(pa + m * 2048);
;       const i32x4 hi = *(const i32x4*)(pa2 + m * 2048);
;       At[m] = __builtin_shufflevector(lo, hi, 0, 1, 2, 3, 4, 5, 6, 7);
;     }
; #pragma unroll
;     for (int m = 0; m < 8; ++m)
; #pragma unroll
;       for (int n = 0; n < 4; ++n)
;         acc[m][n] = __builtin_amdgcn_mfma_scale_f32_16x16x128_f8f6f4(At[m], Bf[n], acc[m][n], 0, 0, 0, 0x7F7F7F7F, 0, 0x7F7F7F7F);
;     __builtin_amdgcn_sched_group_barrier(0x100, 10, 0);
; #pragma unroll
;     for (int m = 0; m < 8; ++m) {
;       __builtin_amdgcn_sched_group_barrier(0x008, 1, 0);
;       if (m < 7) __builtin_amdgcn_sched_group_barrier(0x100, 2, 0);
;       __builtin_amdgcn_sched_group_barrier(0x008, 3, 0);
;     }
;     __builtin_amdgcn_sched_barrier(0);
;     WAIT_V0(); __syncthreads();
	v_mfma_scale_f32_16x16x128_f8f6f4 v[126:129], v[74:81], v[28:35], v[126:129], v212, v212 op_sel_hi:[0,0,0]
	ds_read_b128 v[42:45], v38 offset:8192
	ds_read_b128 v[46:49], v41 offset:8192
	v_lshl_add_u64 v[16:17], v[16:17], 0, s[64:65]
	s_mov_b32 m0, s74
	s_nop 0
	global_load_lds_dwordx4 v[16:17], off
	v_mfma_scale_f32_16x16x128_f8f6f4 v[130:133], v[74:81], v[50:57], v[130:133], v212, v212 op_sel_hi:[0,0,0]
	v_mfma_scale_f32_16x16x128_f8f6f4 v[134:137], v[74:81], v[58:65], v[134:137], v212, v212 op_sel_hi:[0,0,0]
	v_mfma_scale_f32_16x16x128_f8f6f4 v[138:141], v[74:81], v[66:73], v[138:141], v212, v212 op_sel_hi:[0,0,0]
	s_waitcnt lgkmcnt(0)
	v_mfma_scale_f32_16x16x128_f8f6f4 v[142:145], v[42:49], v[28:35], v[142:145], v212, v212 op_sel_hi:[0,0,0]
	ds_read_b128 v[74:77], v38 offset:10240
	ds_read_b128 v[78:81], v41 offset:10240
	v_mfma_scale_f32_16x16x128_f8f6f4 v[146:149], v[42:49], v[50:57], v[146:149], v212, v212 op_sel_hi:[0,0,0]
	v_mfma_scale_f32_16x16x128_f8f6f4 v[150:153], v[42:49], v[58:65], v[150:153], v212, v212 op_sel_hi:[0,0,0]
	v_mfma_scale_f32_16x16x128_f8f6f4 v[154:157], v[42:49], v[66:73], v[154:157], v212, v212 op_sel_hi:[0,0,0]
	s_waitcnt lgkmcnt(0)
	v_mfma_scale_f32_16x16x128_f8f6f4 v[158:161], v[74:81], v[28:35], v[158:161], v212, v212 op_sel_hi:[0,0,0]
	ds_read_b128 v[42:45], v38 offset:12288
	ds_read_b128 v[46:49], v41 offset:12288
	v_mfma_scale_f32_16x16x128_f8f6f4 v[162:165], v[74:81], v[50:57], v[162:165], v212, v212 op_sel_hi:[0,0,0]
	v_mfma_scale_f32_16x16x128_f8f6f4 v[166:169], v[74:81], v[58:65], v[166:169], v212, v212 op_sel_hi:[0,0,0]
	v_mfma_scale_f32_16x16x128_f8f6f4 v[170:173], v[74:81], v[66:73], v[170:173], v212, v212 op_sel_hi:[0,0,0]
	s_waitcnt lgkmcnt(0)
	v_mfma_scale_f32_16x16x128_f8f6f4 v[174:177], v[42:49], v[28:35], v[174:177], v212, v212 op_sel_hi:[0,0,0]
	ds_read_b128 v[74:77], v38 offset:14336
	ds_read_b128 v[78:81], v41 offset:14336
	v_mfma_scale_f32_16x16x128_f8f6f4 v[22:25], v[42:49], v[66:73], v[22:25], v212, v212 op_sel_hi:[0,0,0]
	v_mfma_scale_f32_16x16x128_f8f6f4 v[178:181], v[42:49], v[50:57], v[178:181], v212, v212 op_sel_hi:[0,0,0]
	v_mfma_scale_f32_16x16x128_f8f6f4 v[182:185], v[42:49], v[58:65], v[182:185], v212, v212 op_sel_hi:[0,0,0]
	s_waitcnt lgkmcnt(0)
	v_mfma_scale_f32_16x16x128_f8f6f4 v[186:189], v[74:81], v[28:35], v[186:189], v212, v212 op_sel_hi:[0,0,0]
	v_mfma_scale_f32_16x16x128_f8f6f4 v[190:193], v[74:81], v[50:57], v[190:193], v212, v212 op_sel_hi:[0,0,0]
	v_mfma_scale_f32_16x16x128_f8f6f4 v[194:197], v[74:81], v[58:65], v[194:197], v212, v212 op_sel_hi:[0,0,0]
	v_mfma_scale_f32_16x16x128_f8f6f4 v[198:201], v[74:81], v[66:73], v[198:201], v212, v212 op_sel_hi:[0,0,0]
	s_waitcnt vmcnt(0)
	s_waitcnt vmcnt(0)
	s_barrier
	ds_read_b128 v[28:31], v0
	ds_read_b128 v[32:35], v18
	ds_read_b128 v[42:45], v19 offset:32768
	ds_read_b128 v[46:49], v20 offset:32768
	ds_read_b128 v[50:53], v19 offset:34816
	ds_read_b128 v[54:57], v20 offset:34816
	ds_read_b128 v[58:61], v19 offset:36864
	ds_read_b128 v[62:65], v20 offset:36864
	ds_read_b128 v[66:69], v19 offset:38912
	ds_read_b128 v[70:73], v20 offset:38912
	v_lshl_add_u64 v[2:3], v[2:3], 0, s[64:65]
	s_mov_b32 m0, s9
	s_nop 0
	global_load_lds_dwordx4 v[2:3], off
	s_waitcnt lgkmcnt(0)
	v_mfma_scale_f32_16x16x128_f8f6f4 v[202:205], v[28:35], v[42:49], v[202:205], v212, v212 op_sel_hi:[0,0,0]
	ds_read_b128 v[74:77], v0 offset:2048
	ds_read_b128 v[78:81], v18 offset:2048
	v_lshl_add_u64 v[4:5], v[4:5], 0, s[64:65]
	s_mov_b32 m0, s4
	s_nop 0
	global_load_lds_dwordx4 v[4:5], off
	v_mfma_scale_f32_16x16x128_f8f6f4 v[82:85], v[28:35], v[50:57], v[82:85], v212, v212 op_sel_hi:[0,0,0]
	v_mfma_scale_f32_16x16x128_f8f6f4 v[86:89], v[28:35], v[58:65], v[86:89], v212, v212 op_sel_hi:[0,0,0]
	v_lshl_add_u64 v[6:7], v[6:7], 0, s[64:65]
	s_mov_b32 m0, s5
	s_nop 0
	global_load_lds_dwordx4 v[6:7], off
	v_mfma_scale_f32_16x16x128_f8f6f4 v[90:93], v[28:35], v[66:73], v[90:93], v212, v212 op_sel_hi:[0,0,0]
	s_waitcnt lgkmcnt(0)
	v_mfma_scale_f32_16x16x128_f8f6f4 v[94:97], v[74:81], v[42:49], v[94:97], v212, v212 op_sel_hi:[0,0,0]
	ds_read_b128 v[28:31], v0 offset:4096
	ds_read_b128 v[32:35], v18 offset:4096
	v_lshl_add_u64 v[8:9], v[8:9], 0, s[64:65]
	s_mov_b32 m0, s6
	s_nop 0
	global_load_lds_dwordx4 v[8:9], off
	v_mfma_scale_f32_16x16x128_f8f6f4 v[98:101], v[74:81], v[50:57], v[98:101], v212, v212 op_sel_hi:[0,0,0]
	v_mfma_scale_f32_16x16x128_f8f6f4 v[102:105], v[74:81], v[58:65], v[102:105], v212, v212 op_sel_hi:[0,0,0]
	v_lshl_add_u64 v[10:11], v[10:11], 0, s[64:65]
	s_mov_b32 m0, s7
	s_nop 0
	global_load_lds_dwordx4 v[10:11], off
	v_mfma_scale_f32_16x16x128_f8f6f4 v[106:109], v[74:81], v[66:73], v[106:109], v212, v212 op_sel_hi:[0,0,0]
	s_waitcnt lgkmcnt(0)
	v_mfma_scale_f32_16x16x128_f8f6f4 v[110:113], v[28:35], v[42:49], v[110:113], v212, v212 op_sel_hi:[0,0,0]
	ds_read_b128 v[74:77], v0 offset:6144
	ds_read_b128 v[78:81], v18 offset:6144
	v_lshl_add_u64 v[12:13], v[12:13], 0, s[64:65]
	s_mov_b32 m0, s8
	s_nop 0
	global_load_lds_dwordx4 v[12:13], off
	v_mfma_scale_f32_16x16x128_f8f6f4 v[114:117], v[28:35], v[50:57], v[114:117], v212, v212 op_sel_hi:[0,0,0]
	v_mfma_scale_f32_16x16x128_f8f6f4 v[118:121], v[28:35], v[58:65], v[118:121], v212, v212 op_sel_hi:[0,0,0]
	v_lshl_add_u64 v[14:15], v[14:15], 0, s[64:65]
	s_mov_b32 m0, s23
	s_nop 0
	global_load_lds_dwordx4 v[14:15], off
	v_mfma_scale_f32_16x16x128_f8f6f4 v[122:125], v[28:35], v[66:73], v[122:125], v212, v212 op_sel_hi:[0,0,0]
	s_waitcnt lgkmcnt(0)
; #define WAIT_V0() asm volatile("s_waitcnt vmcnt(0)" ::: "memory")
; DI void gemm_core_q(const int tid, const u8* __restrict__ Wb, const u8* __restrict__ Xb, f32x4 (&acc)[8][4]) {
;     ...
;   auto stage = [&](int buf, int kt) {
; #pragma unroll
;     for (int i = 0; i < 4; ++i) {
;       __builtin_amdgcn_global_load_lds((const unsigned*)(Wb + off[i] + kt * 128), (unsigned*)(shm + buf * STAGE_B + wid * 1024 + i * 8192), 16, 0, 0);
;       __builtin_amdgcn_global_load_lds((const unsigned*)(Xb + off[i] + kt * 128), (unsigned*)(shm + buf * STAGE_B + TILE_B + wid * 1024 + i * 8192), 16, 0, 0);
;     }
;   };
;   stage(0, 0); WAIT_V0(); __syncthreads();
;   for (int t = 0; t < 8; ++t) {
;     const int cur = t & 1;
;     if (t + 1 < 8) stage(cur ^ 1, t + 1);
;     i32x8 At[8], Bf[4];
;     const int qb = lds_byte_q(wc * 64 + fr, fq * 2), qa = lds_byte_q(wr * 128 + fr, fq * 2);
;     const char* pb = shm + cur * STAGE_B + TILE_B + qb;
;     const char* pb2 = shm + cur * STAGE_B + TILE_B + (qb ^ 16);
;     const char* pa = shm + cur * STAGE_B + qa;
;     const char* pa2 = shm + cur * STAGE_B + (qa ^ 16);
; #pragma unroll
;     for (int n = 0; n < 4; ++n) {
;       const i32x4 lo = *(const i32x4*)(pb + n * 2048);
;       const i32x4 hi = *(const i32x4*)(pb2 + n * 2048);
;       Bf[n] = __builtin_shufflevector(lo, hi, 0, 1, 2, 3, 4, 5, 6, 7);
;     }
; #pragma unroll
;     for (int m = 0; m < 8; ++m) {
;       const i32x4 lo = *(const i32x4*)(pa + m * 2048);
;       const i32x4 hi = *(const i32x4*)(pa2 + m * 2048);
;       At[m] = __builtin_shufflevector(lo, hi, 0, 1, 2, 3, 4, 5, 6, 7);
;     }
; #pragma unroll
;     for (int m = 0; m < 8; ++m)
; #pragma unroll
;       for (int n = 0; n < 4; ++n)
;         acc[m][n] = __builtin_amdgcn_mfma_scale_f32_16x16x128_f8f6f4(At[m], Bf[n], acc[m][n], 0, 0, 0, 0x7F7F7F7F, 0, 0x7F7F7F7F);
;     __builtin_amdgcn_sched_group_barrier(0x100, 10, 0);
; #pragma unroll
;     for (int m = 0; m < 8; ++m) {
;       __builtin_amdgcn_sched_group_barrier(0x008, 1, 0);
;       if (m < 7) __builtin_amdgcn_sched_group_barrier(0x100, 2, 0);
;       __builtin_amdgcn_sched_group_barrier(0x008, 3, 0);
;     }
;     __builtin_amdgcn_sched_barrier(0);
;     WAIT_V0(); __syncthreads();
	v_mfma_scale_f32_16x16x128_f8f6f4 v[126:129], v[74:81], v[42:49], v[126:129], v212, v212 op_sel_hi:[0,0,0]
	ds_read_b128 v[28:31], v0 offset:8192
	ds_read_b128 v[32:35], v18 offset:8192
	v_lshl_add_u64 v[16:17], v[16:17], 0, s[64:65]
	s_mov_b32 m0, s25
	s_nop 0
	global_load_lds_dwordx4 v[16:17], off
	v_mfma_scale_f32_16x16x128_f8f6f4 v[130:133], v[74:81], v[50:57], v[130:133], v212, v212 op_sel_hi:[0,0,0]
	v_mfma_scale_f32_16x16x128_f8f6f4 v[134:137], v[74:81], v[58:65], v[134:137], v212, v212 op_sel_hi:[0,0,0]
	v_mfma_scale_f32_16x16x128_f8f6f4 v[138:141], v[74:81], v[66:73], v[138:141], v212, v212 op_sel_hi:[0,0,0]
	s_waitcnt lgkmcnt(0)
	v_mfma_scale_f32_16x16x128_f8f6f4 v[142:145], v[28:35], v[42:49], v[142:145], v212, v212 op_sel_hi:[0,0,0]
	ds_read_b128 v[74:77], v0 offset:10240
	ds_read_b128 v[78:81], v18 offset:10240
	v_mfma_scale_f32_16x16x128_f8f6f4 v[146:149], v[28:35], v[50:57], v[146:149], v212, v212 op_sel_hi:[0,0,0]
	v_mfma_scale_f32_16x16x128_f8f6f4 v[150:153], v[28:35], v[58:65], v[150:153], v212, v212 op_sel_hi:[0,0,0]
	v_mfma_scale_f32_16x16x128_f8f6f4 v[154:157], v[28:35], v[66:73], v[154:157], v212, v212 op_sel_hi:[0,0,0]
	s_waitcnt lgkmcnt(0)
	v_mfma_scale_f32_16x16x128_f8f6f4 v[158:161], v[74:81], v[42:49], v[158:161], v212, v212 op_sel_hi:[0,0,0]
	ds_read_b128 v[28:31], v0 offset:12288
	ds_read_b128 v[32:35], v18 offset:12288
	v_mfma_scale_f32_16x16x128_f8f6f4 v[162:165], v[74:81], v[50:57], v[162:165], v212, v212 op_sel_hi:[0,0,0]
	v_mfma_scale_f32_16x16x128_f8f6f4 v[166:169], v[74:81], v[58:65], v[166:169], v212, v212 op_sel_hi:[0,0,0]
	v_mfma_scale_f32_16x16x128_f8f6f4 v[170:173], v[74:81], v[66:73], v[170:173], v212, v212 op_sel_hi:[0,0,0]
	s_waitcnt lgkmcnt(0)
	v_mfma_scale_f32_16x16x128_f8f6f4 v[174:177], v[28:35], v[42:49], v[174:177], v212, v212 op_sel_hi:[0,0,0]
	ds_read_b128 v[74:77], v0 offset:14336
	ds_read_b128 v[78:81], v18 offset:14336
	v_mfma_scale_f32_16x16x128_f8f6f4 v[22:25], v[28:35], v[66:73], v[22:25], v212, v212 op_sel_hi:[0,0,0]
	v_mfma_scale_f32_16x16x128_f8f6f4 v[178:181], v[28:35], v[50:57], v[178:181], v212, v212 op_sel_hi:[0,0,0]
	v_mfma_scale_f32_16x16x128_f8f6f4 v[182:185], v[28:35], v[58:65], v[182:185], v212, v212 op_sel_hi:[0,0,0]
	s_waitcnt lgkmcnt(0)
	v_mfma_scale_f32_16x16x128_f8f6f4 v[186:189], v[74:81], v[42:49], v[186:189], v212, v212 op_sel_hi:[0,0,0]
	v_mfma_scale_f32_16x16x128_f8f6f4 v[190:193], v[74:81], v[50:57], v[190:193], v212, v212 op_sel_hi:[0,0,0]
	v_mfma_scale_f32_16x16x128_f8f6f4 v[194:197], v[74:81], v[58:65], v[194:197], v212, v212 op_sel_hi:[0,0,0]
	v_mfma_scale_f32_16x16x128_f8f6f4 v[198:201], v[74:81], v[66:73], v[198:201], v212, v212 op_sel_hi:[0,0,0]
	s_waitcnt vmcnt(0)
	s_waitcnt vmcnt(0)
	s_barrier
	ds_read_b128 v[28:31], v38
	ds_read_b128 v[32:35], v41
	ds_read_b128 v[42:45], v39
	ds_read_b128 v[46:49], v40
	ds_read_b128 v[50:53], v26
	ds_read_b128 v[54:57], v40 offset:2048
	ds_read_b128 v[58:61], v21
	ds_read_b128 v[62:65], v40 offset:4096
	ds_read_b128 v[66:69], v27
	ds_read_b128 v[70:73], v40 offset:6144
	v_lshl_add_u64 v[2:3], v[2:3], 0, s[64:65]
	s_mov_b32 m0, s26
	s_nop 0
	global_load_lds_dwordx4 v[2:3], off
	s_waitcnt lgkmcnt(0)
	v_mfma_scale_f32_16x16x128_f8f6f4 v[202:205], v[28:35], v[42:49], v[202:205], v212, v212 op_sel_hi:[0,0,0]
	ds_read_b128 v[74:77], v38 offset:2048
	ds_read_b128 v[78:81], v41 offset:2048
	v_lshl_add_u64 v[4:5], v[4:5], 0, s[64:65]
	s_mov_b32 m0, s54
	s_nop 0
	global_load_lds_dwordx4 v[4:5], off
	v_mfma_scale_f32_16x16x128_f8f6f4 v[82:85], v[28:35], v[50:57], v[82:85], v212, v212 op_sel_hi:[0,0,0]
	v_mfma_scale_f32_16x16x128_f8f6f4 v[86:89], v[28:35], v[58:65], v[86:89], v212, v212 op_sel_hi:[0,0,0]
	v_lshl_add_u64 v[6:7], v[6:7], 0, s[64:65]
	s_mov_b32 m0, s29
	s_nop 0
	global_load_lds_dwordx4 v[6:7], off
	v_mfma_scale_f32_16x16x128_f8f6f4 v[90:93], v[28:35], v[66:73], v[90:93], v212, v212 op_sel_hi:[0,0,0]
	s_waitcnt lgkmcnt(0)
	v_mfma_scale_f32_16x16x128_f8f6f4 v[94:97], v[74:81], v[42:49], v[94:97], v212, v212 op_sel_hi:[0,0,0]
	ds_read_b128 v[28:31], v38 offset:4096
	ds_read_b128 v[32:35], v41 offset:4096
	v_lshl_add_u64 v[8:9], v[8:9], 0, s[64:65]
	s_mov_b32 m0, s72
	s_nop 0
	global_load_lds_dwordx4 v[8:9], off
	v_mfma_scale_f32_16x16x128_f8f6f4 v[98:101], v[74:81], v[50:57], v[98:101], v212, v212 op_sel_hi:[0,0,0]
	v_mfma_scale_f32_16x16x128_f8f6f4 v[102:105], v[74:81], v[58:65], v[102:105], v212, v212 op_sel_hi:[0,0,0]
	v_lshl_add_u64 v[10:11], v[10:11], 0, s[64:65]
	s_mov_b32 m0, s28
	s_nop 0
	global_load_lds_dwordx4 v[10:11], off
	v_mfma_scale_f32_16x16x128_f8f6f4 v[106:109], v[74:81], v[66:73], v[106:109], v212, v212 op_sel_hi:[0,0,0]
	s_waitcnt lgkmcnt(0)
	v_mfma_scale_f32_16x16x128_f8f6f4 v[110:113], v[28:35], v[42:49], v[110:113], v212, v212 op_sel_hi:[0,0,0]
	ds_read_b128 v[74:77], v38 offset:6144
	ds_read_b128 v[78:81], v41 offset:6144
	v_lshl_add_u64 v[12:13], v[12:13], 0, s[64:65]
	s_mov_b32 m0, s73
	s_nop 0
	global_load_lds_dwordx4 v[12:13], off
	v_mfma_scale_f32_16x16x128_f8f6f4 v[114:117], v[28:35], v[50:57], v[114:117], v212, v212 op_sel_hi:[0,0,0]
	v_mfma_scale_f32_16x16x128_f8f6f4 v[118:121], v[28:35], v[58:65], v[118:121], v212, v212 op_sel_hi:[0,0,0]
	v_lshl_add_u64 v[14:15], v[14:15], 0, s[64:65]
	s_mov_b32 m0, s27
	s_nop 0
	global_load_lds_dwordx4 v[14:15], off
	v_mfma_scale_f32_16x16x128_f8f6f4 v[122:125], v[28:35], v[66:73], v[122:125], v212, v212 op_sel_hi:[0,0,0]
	s_waitcnt lgkmcnt(0)
; #define WAIT_V0() asm volatile("s_waitcnt vmcnt(0)" ::: "memory")
; DI void gemm_core_q(const int tid, const u8* __restrict__ Wb, const u8* __restrict__ Xb, f32x4 (&acc)[8][4]) {
;     ...
;   auto stage = [&](int buf, int kt) {
; #pragma unroll
;     for (int i = 0; i < 4; ++i) {
;       __builtin_amdgcn_global_load_lds((const unsigned*)(Wb + off[i] + kt * 128), (unsigned*)(shm + buf * STAGE_B + wid * 1024 + i * 8192), 16, 0, 0);
;       __builtin_amdgcn_global_load_lds((const unsigned*)(Xb + off[i] + kt * 128), (unsigned*)(shm + buf * STAGE_B + TILE_B + wid * 1024 + i * 8192), 16, 0, 0);
;     }
;   };
;   stage(0, 0); WAIT_V0(); __syncthreads();
;   for (int t = 0; t < 8; ++t) {
;     const int cur = t & 1;
;     if (t + 1 < 8) stage(cur ^ 1, t + 1);
;     i32x8 At[8], Bf[4];
;     const int qb = lds_byte_q(wc * 64 + fr, fq * 2), qa = lds_byte_q(wr * 128 + fr, fq * 2);
;     const char* pb = shm + cur * STAGE_B + TILE_B + qb;
;     const char* pb2 = shm + cur * STAGE_B + TILE_B + (qb ^ 16);
;     const char* pa = shm + cur * STAGE_B + qa;
;     const char* pa2 = shm + cur * STAGE_B + (qa ^ 16);
; #pragma unroll
;     for (int n = 0; n < 4; ++n) {
;       const i32x4 lo = *(const i32x4*)(pb + n * 2048);
;       const i32x4 hi = *(const i32x4*)(pb2 + n * 2048);
;       Bf[n] = __builtin_shufflevector(lo, hi, 0, 1, 2, 3, 4, 5, 6, 7);
;     }
; #pragma unroll
;     for (int m = 0; m < 8; ++m) {
;       const i32x4 lo = *(const i32x4*)(pa + m * 2048);
;       const i32x4 hi = *(const i32x4*)(pa2 + m * 2048);
;       At[m] = __builtin_shufflevector(lo, hi, 0, 1, 2, 3, 4, 5, 6, 7);
;     }
; #pragma unroll
;     for (int m = 0; m < 8; ++m)
; #pragma unroll
;       for (int n = 0; n < 4; ++n)
;         acc[m][n] = __builtin_amdgcn_mfma_scale_f32_16x16x128_f8f6f4(At[m], Bf[n], acc[m][n], 0, 0, 0, 0x7F7F7F7F, 0, 0x7F7F7F7F);
;     __builtin_amdgcn_sched_group_barrier(0x100, 10, 0);
; #pragma unroll
;     for (int m = 0; m < 8; ++m) {
;       __builtin_amdgcn_sched_group_barrier(0x008, 1, 0);
;       if (m < 7) __builtin_amdgcn_sched_group_barrier(0x100, 2, 0);
;       __builtin_amdgcn_sched_group_barrier(0x008, 3, 0);
;     }
;     __builtin_amdgcn_sched_barrier(0);
;     WAIT_V0(); __syncthreads();
	v_mfma_scale_f32_16x16x128_f8f6f4 v[126:129], v[74:81], v[42:49], v[126:129], v212, v212 op_sel_hi:[0,0,0]
	ds_read_b128 v[28:31], v38 offset:8192
	ds_read_b128 v[32:35], v41 offset:8192
	v_lshl_add_u64 v[16:17], v[16:17], 0, s[64:65]
	s_mov_b32 m0, s74
	s_nop 0
	global_load_lds_dwordx4 v[16:17], off
	v_mfma_scale_f32_16x16x128_f8f6f4 v[130:133], v[74:81], v[50:57], v[130:133], v212, v212 op_sel_hi:[0,0,0]
	v_mfma_scale_f32_16x16x128_f8f6f4 v[134:137], v[74:81], v[58:65], v[134:137], v212, v212 op_sel_hi:[0,0,0]
	v_mfma_scale_f32_16x16x128_f8f6f4 v[138:141], v[74:81], v[66:73], v[138:141], v212, v212 op_sel_hi:[0,0,0]
	s_waitcnt lgkmcnt(0)
	v_mfma_scale_f32_16x16x128_f8f6f4 v[142:145], v[28:35], v[42:49], v[142:145], v212, v212 op_sel_hi:[0,0,0]
	ds_read_b128 v[74:77], v38 offset:10240
	ds_read_b128 v[78:81], v41 offset:10240
	v_mfma_scale_f32_16x16x128_f8f6f4 v[146:149], v[28:35], v[50:57], v[146:149], v212, v212 op_sel_hi:[0,0,0]
	v_mfma_scale_f32_16x16x128_f8f6f4 v[150:153], v[28:35], v[58:65], v[150:153], v212, v212 op_sel_hi:[0,0,0]
	v_mfma_scale_f32_16x16x128_f8f6f4 v[154:157], v[28:35], v[66:73], v[154:157], v212, v212 op_sel_hi:[0,0,0]
	s_waitcnt lgkmcnt(0)
	v_mfma_scale_f32_16x16x128_f8f6f4 v[158:161], v[74:81], v[42:49], v[158:161], v212, v212 op_sel_hi:[0,0,0]
	ds_read_b128 v[28:31], v38 offset:12288
	ds_read_b128 v[32:35], v41 offset:12288
	v_mfma_scale_f32_16x16x128_f8f6f4 v[162:165], v[74:81], v[50:57], v[162:165], v212, v212 op_sel_hi:[0,0,0]
	v_mfma_scale_f32_16x16x128_f8f6f4 v[166:169], v[74:81], v[58:65], v[166:169], v212, v212 op_sel_hi:[0,0,0]
	v_mfma_scale_f32_16x16x128_f8f6f4 v[170:173], v[74:81], v[66:73], v[170:173], v212, v212 op_sel_hi:[0,0,0]
	s_waitcnt lgkmcnt(0)
	v_mfma_scale_f32_16x16x128_f8f6f4 v[174:177], v[28:35], v[42:49], v[174:177], v212, v212 op_sel_hi:[0,0,0]
	ds_read_b128 v[74:77], v38 offset:14336
	ds_read_b128 v[78:81], v41 offset:14336
	v_mfma_scale_f32_16x16x128_f8f6f4 v[22:25], v[28:35], v[66:73], v[22:25], v212, v212 op_sel_hi:[0,0,0]
	v_mfma_scale_f32_16x16x128_f8f6f4 v[178:181], v[28:35], v[50:57], v[178:181], v212, v212 op_sel_hi:[0,0,0]
	v_mfma_scale_f32_16x16x128_f8f6f4 v[182:185], v[28:35], v[58:65], v[182:185], v212, v212 op_sel_hi:[0,0,0]
	s_waitcnt lgkmcnt(0)
	v_mfma_scale_f32_16x16x128_f8f6f4 v[186:189], v[74:81], v[42:49], v[186:189], v212, v212 op_sel_hi:[0,0,0]
	v_mfma_scale_f32_16x16x128_f8f6f4 v[190:193], v[74:81], v[50:57], v[190:193], v212, v212 op_sel_hi:[0,0,0]
	v_mfma_scale_f32_16x16x128_f8f6f4 v[194:197], v[74:81], v[58:65], v[194:197], v212, v212 op_sel_hi:[0,0,0]
	v_mfma_scale_f32_16x16x128_f8f6f4 v[198:201], v[74:81], v[66:73], v[198:201], v212, v212 op_sel_hi:[0,0,0]
	s_waitcnt vmcnt(0)
	s_waitcnt vmcnt(0)
	s_barrier
	ds_read_b128 v[28:31], v0
	ds_read_b128 v[32:35], v18
	ds_read_b128 v[42:45], v19 offset:32768
	ds_read_b128 v[46:49], v20 offset:32768
	ds_read_b128 v[50:53], v19 offset:34816
	ds_read_b128 v[54:57], v20 offset:34816
	ds_read_b128 v[58:61], v19 offset:36864
	ds_read_b128 v[62:65], v20 offset:36864
	ds_read_b128 v[66:69], v19 offset:38912
	ds_read_b128 v[70:73], v20 offset:38912
	v_lshl_add_u64 v[2:3], v[2:3], 0, s[64:65]
	s_mov_b32 m0, s9
	s_nop 0
	global_load_lds_dwordx4 v[2:3], off
	s_waitcnt lgkmcnt(0)
	v_mfma_scale_f32_16x16x128_f8f6f4 v[202:205], v[28:35], v[42:49], v[202:205], v212, v212 op_sel_hi:[0,0,0]
	ds_read_b128 v[74:77], v0 offset:2048
	ds_read_b128 v[78:81], v18 offset:2048
	v_lshl_add_u64 v[4:5], v[4:5], 0, s[64:65]
	s_mov_b32 m0, s4
	s_nop 0
	global_load_lds_dwordx4 v[4:5], off
	v_mfma_scale_f32_16x16x128_f8f6f4 v[82:85], v[28:35], v[50:57], v[82:85], v212, v212 op_sel_hi:[0,0,0]
	v_mfma_scale_f32_16x16x128_f8f6f4 v[86:89], v[28:35], v[58:65], v[86:89], v212, v212 op_sel_hi:[0,0,0]
	v_lshl_add_u64 v[6:7], v[6:7], 0, s[64:65]
	s_mov_b32 m0, s5
	s_nop 0
	global_load_lds_dwordx4 v[6:7], off
	v_mfma_scale_f32_16x16x128_f8f6f4 v[90:93], v[28:35], v[66:73], v[90:93], v212, v212 op_sel_hi:[0,0,0]
	s_waitcnt lgkmcnt(0)
	v_mfma_scale_f32_16x16x128_f8f6f4 v[94:97], v[74:81], v[42:49], v[94:97], v212, v212 op_sel_hi:[0,0,0]
	ds_read_b128 v[28:31], v0 offset:4096
	ds_read_b128 v[32:35], v18 offset:4096
	v_lshl_add_u64 v[8:9], v[8:9], 0, s[64:65]
	s_mov_b32 m0, s6
	s_nop 0
	global_load_lds_dwordx4 v[8:9], off
	v_mfma_scale_f32_16x16x128_f8f6f4 v[98:101], v[74:81], v[50:57], v[98:101], v212, v212 op_sel_hi:[0,0,0]
	v_mfma_scale_f32_16x16x128_f8f6f4 v[102:105], v[74:81], v[58:65], v[102:105], v212, v212 op_sel_hi:[0,0,0]
	v_lshl_add_u64 v[10:11], v[10:11], 0, s[64:65]
	s_mov_b32 m0, s7
	s_nop 0
	global_load_lds_dwordx4 v[10:11], off
	v_mfma_scale_f32_16x16x128_f8f6f4 v[106:109], v[74:81], v[66:73], v[106:109], v212, v212 op_sel_hi:[0,0,0]
	s_waitcnt lgkmcnt(0)
	v_mfma_scale_f32_16x16x128_f8f6f4 v[110:113], v[28:35], v[42:49], v[110:113], v212, v212 op_sel_hi:[0,0,0]
	ds_read_b128 v[74:77], v0 offset:6144
	ds_read_b128 v[78:81], v18 offset:6144
	v_lshl_add_u64 v[12:13], v[12:13], 0, s[64:65]
	s_mov_b32 m0, s8
	s_nop 0
	global_load_lds_dwordx4 v[12:13], off
	v_mfma_scale_f32_16x16x128_f8f6f4 v[114:117], v[28:35], v[50:57], v[114:117], v212, v212 op_sel_hi:[0,0,0]
	v_mfma_scale_f32_16x16x128_f8f6f4 v[118:121], v[28:35], v[58:65], v[118:121], v212, v212 op_sel_hi:[0,0,0]
	v_lshl_add_u64 v[14:15], v[14:15], 0, s[64:65]
	s_mov_b32 m0, s23
	s_nop 0
	global_load_lds_dwordx4 v[14:15], off
	v_mfma_scale_f32_16x16x128_f8f6f4 v[122:125], v[28:35], v[66:73], v[122:125], v212, v212 op_sel_hi:[0,0,0]
	s_waitcnt lgkmcnt(0)
; #define WAIT_V0() asm volatile("s_waitcnt vmcnt(0)" ::: "memory")
; DI void gemm_core_q(const int tid, const u8* __restrict__ Wb, const u8* __restrict__ Xb, f32x4 (&acc)[8][4]) {
;     ...
;   auto stage = [&](int buf, int kt) {
; #pragma unroll
;     for (int i = 0; i < 4; ++i) {
;       __builtin_amdgcn_global_load_lds((const unsigned*)(Wb + off[i] + kt * 128), (unsigned*)(shm + buf * STAGE_B + wid * 1024 + i * 8192), 16, 0, 0);
;       __builtin_amdgcn_global_load_lds((const unsigned*)(Xb + off[i] + kt * 128), (unsigned*)(shm + buf * STAGE_B + TILE_B + wid * 1024 + i * 8192), 16, 0, 0);
;     }
;   };
;   stage(0, 0); WAIT_V0(); __syncthreads();
;   for (int t = 0; t < 8; ++t) {
;     const int cur = t & 1;
;     if (t + 1 < 8) stage(cur ^ 1, t + 1);
;     i32x8 At[8], Bf[4];
;     const int qb = lds_byte_q(wc * 64 + fr, fq * 2), qa = lds_byte_q(wr * 128 + fr, fq * 2);
;     const char* pb = shm + cur * STAGE_B + TILE_B + qb;
;     const char* pb2 = shm + cur * STAGE_B + TILE_B + (qb ^ 16);
;     const char* pa = shm + cur * STAGE_B + qa;
;     const char* pa2 = shm + cur * STAGE_B + (qa ^ 16);
; #pragma unroll
;     for (int n = 0; n < 4; ++n) {
;       const i32x4 lo = *(const i32x4*)(pb + n * 2048);
;       const i32x4 hi = *(const i32x4*)(pb2 + n * 2048);
;       Bf[n] = __builtin_shufflevector(lo, hi, 0, 1, 2, 3, 4, 5, 6, 7);
;     }
; #pragma unroll
;     for (int m = 0; m < 8; ++m) {
;       const i32x4 lo = *(const i32x4*)(pa + m * 2048);
;       const i32x4 hi = *(const i32x4*)(pa2 + m * 2048);
;       At[m] = __builtin_shufflevector(lo, hi, 0, 1, 2, 3, 4, 5, 6, 7);
;     }
; #pragma unroll
;     for (int m = 0; m < 8; ++m)
; #pragma unroll
;       for (int n = 0; n < 4; ++n)
;         acc[m][n] = __builtin_amdgcn_mfma_scale_f32_16x16x128_f8f6f4(At[m], Bf[n], acc[m][n], 0, 0, 0, 0x7F7F7F7F, 0, 0x7F7F7F7F);
;     __builtin_amdgcn_sched_group_barrier(0x100, 10, 0);
; #pragma unroll
;     for (int m = 0; m < 8; ++m) {
;       __builtin_amdgcn_sched_group_barrier(0x008, 1, 0);
;       if (m < 7) __builtin_amdgcn_sched_group_barrier(0x100, 2, 0);
;       __builtin_amdgcn_sched_group_barrier(0x008, 3, 0);
;     }
;     __builtin_amdgcn_sched_barrier(0);
;     WAIT_V0(); __syncthreads();
	v_mfma_scale_f32_16x16x128_f8f6f4 v[126:129], v[74:81], v[42:49], v[126:129], v212, v212 op_sel_hi:[0,0,0]
	ds_read_b128 v[28:31], v0 offset:8192
	ds_read_b128 v[32:35], v18 offset:8192
	v_lshl_add_u64 v[16:17], v[16:17], 0, s[64:65]
	s_mov_b32 m0, s25
	s_nop 0
	global_load_lds_dwordx4 v[16:17], off
	v_mfma_scale_f32_16x16x128_f8f6f4 v[130:133], v[74:81], v[50:57], v[130:133], v212, v212 op_sel_hi:[0,0,0]
	v_mfma_scale_f32_16x16x128_f8f6f4 v[134:137], v[74:81], v[58:65], v[134:137], v212, v212 op_sel_hi:[0,0,0]
	v_mfma_scale_f32_16x16x128_f8f6f4 v[138:141], v[74:81], v[66:73], v[138:141], v212, v212 op_sel_hi:[0,0,0]
	s_waitcnt lgkmcnt(0)
	v_mfma_scale_f32_16x16x128_f8f6f4 v[142:145], v[28:35], v[42:49], v[142:145], v212, v212 op_sel_hi:[0,0,0]
	ds_read_b128 v[74:77], v0 offset:10240
	ds_read_b128 v[78:81], v18 offset:10240
	v_mfma_scale_f32_16x16x128_f8f6f4 v[146:149], v[28:35], v[50:57], v[146:149], v212, v212 op_sel_hi:[0,0,0]
	v_mfma_scale_f32_16x16x128_f8f6f4 v[150:153], v[28:35], v[58:65], v[150:153], v212, v212 op_sel_hi:[0,0,0]
	v_mfma_scale_f32_16x16x128_f8f6f4 v[154:157], v[28:35], v[66:73], v[154:157], v212, v212 op_sel_hi:[0,0,0]
	s_waitcnt lgkmcnt(0)
	v_mfma_scale_f32_16x16x128_f8f6f4 v[158:161], v[74:81], v[42:49], v[158:161], v212, v212 op_sel_hi:[0,0,0]
	ds_read_b128 v[28:31], v0 offset:12288
	ds_read_b128 v[32:35], v18 offset:12288
	v_mfma_scale_f32_16x16x128_f8f6f4 v[162:165], v[74:81], v[50:57], v[162:165], v212, v212 op_sel_hi:[0,0,0]
	v_mfma_scale_f32_16x16x128_f8f6f4 v[166:169], v[74:81], v[58:65], v[166:169], v212, v212 op_sel_hi:[0,0,0]
	v_mfma_scale_f32_16x16x128_f8f6f4 v[170:173], v[74:81], v[66:73], v[170:173], v212, v212 op_sel_hi:[0,0,0]
	s_waitcnt lgkmcnt(0)
	v_mfma_scale_f32_16x16x128_f8f6f4 v[174:177], v[28:35], v[42:49], v[174:177], v212, v212 op_sel_hi:[0,0,0]
	ds_read_b128 v[74:77], v0 offset:14336
	ds_read_b128 v[78:81], v18 offset:14336
	v_mfma_scale_f32_16x16x128_f8f6f4 v[22:25], v[28:35], v[66:73], v[22:25], v212, v212 op_sel_hi:[0,0,0]
	v_mfma_scale_f32_16x16x128_f8f6f4 v[178:181], v[28:35], v[50:57], v[178:181], v212, v212 op_sel_hi:[0,0,0]
	v_mfma_scale_f32_16x16x128_f8f6f4 v[182:185], v[28:35], v[58:65], v[182:185], v212, v212 op_sel_hi:[0,0,0]
	s_waitcnt lgkmcnt(0)
	v_mfma_scale_f32_16x16x128_f8f6f4 v[186:189], v[74:81], v[42:49], v[186:189], v212, v212 op_sel_hi:[0,0,0]
	v_mfma_scale_f32_16x16x128_f8f6f4 v[190:193], v[74:81], v[50:57], v[190:193], v212, v212 op_sel_hi:[0,0,0]
	v_mfma_scale_f32_16x16x128_f8f6f4 v[194:197], v[74:81], v[58:65], v[194:197], v212, v212 op_sel_hi:[0,0,0]
	v_mfma_scale_f32_16x16x128_f8f6f4 v[198:201], v[74:81], v[66:73], v[198:201], v212, v212 op_sel_hi:[0,0,0]
	s_waitcnt vmcnt(0)
	s_waitcnt vmcnt(0)
	s_barrier
	ds_read_b128 v[28:31], v38
	ds_read_b128 v[32:35], v41
	ds_read_b128 v[42:45], v39
	ds_read_b128 v[46:49], v40
	ds_read_b128 v[50:53], v26
	ds_read_b128 v[54:57], v40 offset:2048
	ds_read_b128 v[58:61], v21
	ds_read_b128 v[62:65], v40 offset:4096
	ds_read_b128 v[66:69], v27
	ds_read_b128 v[70:73], v40 offset:6144
	v_lshl_add_u64 v[2:3], v[2:3], 0, s[64:65]
	s_mov_b32 m0, s26
	s_nop 0
	global_load_lds_dwordx4 v[2:3], off
	s_waitcnt lgkmcnt(0)
	v_mfma_scale_f32_16x16x128_f8f6f4 v[202:205], v[28:35], v[42:49], v[202:205], v212, v212 op_sel_hi:[0,0,0]
	ds_read_b128 v[74:77], v38 offset:2048
	ds_read_b128 v[78:81], v41 offset:2048
	v_lshl_add_u64 v[4:5], v[4:5], 0, s[64:65]
	s_mov_b32 m0, s54
	s_nop 0
	global_load_lds_dwordx4 v[4:5], off
	v_mfma_scale_f32_16x16x128_f8f6f4 v[232:235], v[28:35], v[50:57], v[82:85], v212, v212 op_sel_hi:[0,0,0]
	v_mfma_scale_f32_16x16x128_f8f6f4 v[86:89], v[28:35], v[58:65], v[86:89], v212, v212 op_sel_hi:[0,0,0]
	v_lshl_add_u64 v[6:7], v[6:7], 0, s[64:65]
	s_mov_b32 m0, s29
	s_nop 0
	global_load_lds_dwordx4 v[6:7], off
	v_mfma_scale_f32_16x16x128_f8f6f4 v[236:239], v[28:35], v[66:73], v[90:93], v212, v212 op_sel_hi:[0,0,0]
	s_waitcnt lgkmcnt(0)
	v_mfma_scale_f32_16x16x128_f8f6f4 v[94:97], v[74:81], v[42:49], v[94:97], v212, v212 op_sel_hi:[0,0,0]
	ds_read_b128 v[28:31], v38 offset:4096
	ds_read_b128 v[32:35], v41 offset:4096
	v_lshl_add_u64 v[8:9], v[8:9], 0, s[64:65]
	s_mov_b32 m0, s72
	s_nop 0
	global_load_lds_dwordx4 v[8:9], off
	v_mfma_scale_f32_16x16x128_f8f6f4 v[98:101], v[74:81], v[50:57], v[98:101], v212, v212 op_sel_hi:[0,0,0]
	v_mfma_scale_f32_16x16x128_f8f6f4 v[102:105], v[74:81], v[58:65], v[102:105], v212, v212 op_sel_hi:[0,0,0]
	v_lshl_add_u64 v[10:11], v[10:11], 0, s[64:65]
	s_mov_b32 m0, s28
	s_nop 0
	global_load_lds_dwordx4 v[10:11], off
	v_mfma_scale_f32_16x16x128_f8f6f4 v[106:109], v[74:81], v[66:73], v[106:109], v212, v212 op_sel_hi:[0,0,0]
	s_waitcnt lgkmcnt(0)
	v_mfma_scale_f32_16x16x128_f8f6f4 v[110:113], v[28:35], v[42:49], v[110:113], v212, v212 op_sel_hi:[0,0,0]
	ds_read_b128 v[74:77], v38 offset:6144
	ds_read_b128 v[78:81], v41 offset:6144
	v_lshl_add_u64 v[12:13], v[12:13], 0, s[64:65]
	s_mov_b32 m0, s73
	s_nop 0
	global_load_lds_dwordx4 v[12:13], off
	v_mfma_scale_f32_16x16x128_f8f6f4 v[114:117], v[28:35], v[50:57], v[114:117], v212, v212 op_sel_hi:[0,0,0]
	v_mfma_scale_f32_16x16x128_f8f6f4 v[118:121], v[28:35], v[58:65], v[118:121], v212, v212 op_sel_hi:[0,0,0]
	v_lshl_add_u64 v[14:15], v[14:15], 0, s[64:65]
	s_mov_b32 m0, s27
	s_nop 0
	global_load_lds_dwordx4 v[14:15], off
	v_mfma_scale_f32_16x16x128_f8f6f4 v[240:243], v[28:35], v[66:73], v[122:125], v212, v212 op_sel_hi:[0,0,0]
	s_waitcnt lgkmcnt(0)
; #define WAIT_V0() asm volatile("s_waitcnt vmcnt(0)" ::: "memory")
; DI void gemm_core_q(const int tid, const u8* __restrict__ Wb, const u8* __restrict__ Xb, f32x4 (&acc)[8][4]) {
;     ...
;   auto stage = [&](int buf, int kt) {
; #pragma unroll
;     for (int i = 0; i < 4; ++i) {
;       __builtin_amdgcn_global_load_lds((const unsigned*)(Wb + off[i] + kt * 128), (unsigned*)(shm + buf * STAGE_B + wid * 1024 + i * 8192), 16, 0, 0);
;       __builtin_amdgcn_global_load_lds((const unsigned*)(Xb + off[i] + kt * 128), (unsigned*)(shm + buf * STAGE_B + TILE_B + wid * 1024 + i * 8192), 16, 0, 0);
;     }
;   };
;   stage(0, 0); WAIT_V0(); __syncthreads();
;   for (int t = 0; t < 8; ++t) {
;     const int cur = t & 1;
;     if (t + 1 < 8) stage(cur ^ 1, t + 1);
;     i32x8 At[8], Bf[4];
;     const int qb = lds_byte_q(wc * 64 + fr, fq * 2), qa = lds_byte_q(wr * 128 + fr, fq * 2);
;     const char* pb = shm + cur * STAGE_B + TILE_B + qb;
;     const char* pb2 = shm + cur * STAGE_B + TILE_B + (qb ^ 16);
;     const char* pa = shm + cur * STAGE_B + qa;
;     const char* pa2 = shm + cur * STAGE_B + (qa ^ 16);
; #pragma unroll
;     for (int n = 0; n < 4; ++n) {
;       const i32x4 lo = *(const i32x4*)(pb + n * 2048);
;       const i32x4 hi = *(const i32x4*)(pb2 + n * 2048);
;       Bf[n] = __builtin_shufflevector(lo, hi, 0, 1, 2, 3, 4, 5, 6, 7);
;     }
; #pragma unroll
;     for (int m = 0; m < 8; ++m) {
;       const i32x4 lo = *(const i32x4*)(pa + m * 2048);
;       const i32x4 hi = *(const i32x4*)(pa2 + m * 2048);
;       At[m] = __builtin_shufflevector(lo, hi, 0, 1, 2, 3, 4, 5, 6, 7);
;     }
; #pragma unroll
;     for (int m = 0; m < 8; ++m)
; #pragma unroll
;       for (int n = 0; n < 4; ++n)
;         acc[m][n] = __builtin_amdgcn_mfma_scale_f32_16x16x128_f8f6f4(At[m], Bf[n], acc[m][n], 0, 0, 0, 0x7F7F7F7F, 0, 0x7F7F7F7F);
	v_mfma_scale_f32_16x16x128_f8f6f4 v[244:247], v[74:81], v[42:49], v[126:129], v212, v212 op_sel_hi:[0,0,0]
	ds_read_b128 v[28:31], v38 offset:8192
	ds_read_b128 v[32:35], v41 offset:8192
	v_lshl_add_u64 v[16:17], v[16:17], 0, s[64:65]
	s_mov_b32 m0, s74
	s_nop 0
	global_load_lds_dwordx4 v[16:17], off
	v_mfma_scale_f32_16x16x128_f8f6f4 v[248:251], v[74:81], v[50:57], v[130:133], v212, v212 op_sel_hi:[0,0,0]
	v_mfma_scale_f32_16x16x128_f8f6f4 v[206:209], v[74:81], v[58:65], v[134:137], v212, v212 op_sel_hi:[0,0,0]
	v_mfma_scale_f32_16x16x128_f8f6f4 v[222:225], v[74:81], v[66:73], v[138:141], v212, v212 op_sel_hi:[0,0,0]
	s_waitcnt lgkmcnt(0)
	v_mfma_scale_f32_16x16x128_f8f6f4 v[142:145], v[28:35], v[42:49], v[142:145], v212, v212 op_sel_hi:[0,0,0]
	ds_read_b128 v[74:77], v38 offset:10240
	ds_read_b128 v[78:81], v41 offset:10240
	v_mfma_scale_f32_16x16x128_f8f6f4 v[216:219], v[28:35], v[50:57], v[146:149], v212, v212 op_sel_hi:[0,0,0]
	v_mfma_scale_f32_16x16x128_f8f6f4 v[226:229], v[28:35], v[58:65], v[150:153], v212, v212 op_sel_hi:[0,0,0]
	v_mfma_scale_f32_16x16x128_f8f6f4 v[154:157], v[28:35], v[66:73], v[154:157], v212, v212 op_sel_hi:[0,0,0]
	s_waitcnt lgkmcnt(0)
	v_mfma_scale_f32_16x16x128_f8f6f4 v[158:161], v[74:81], v[42:49], v[158:161], v212, v212 op_sel_hi:[0,0,0]
	ds_read_b128 v[28:31], v38 offset:12288
	ds_read_b128 v[32:35], v41 offset:12288
	v_mfma_scale_f32_16x16x128_f8f6f4 v[162:165], v[74:81], v[50:57], v[162:165], v212, v212 op_sel_hi:[0,0,0]
	v_mfma_scale_f32_16x16x128_f8f6f4 v[166:169], v[74:81], v[58:65], v[166:169], v212, v212 op_sel_hi:[0,0,0]
	v_mfma_scale_f32_16x16x128_f8f6f4 v[170:173], v[74:81], v[66:73], v[170:173], v212, v212 op_sel_hi:[0,0,0]
	s_waitcnt lgkmcnt(0)
	v_mfma_scale_f32_16x16x128_f8f6f4 v[174:177], v[28:35], v[42:49], v[174:177], v212, v212 op_sel_hi:[0,0,0]
	ds_read_b128 v[74:77], v38 offset:14336
	ds_read_b128 v[78:81], v41 offset:14336
	v_mfma_scale_f32_16x16x128_f8f6f4 v[178:181], v[28:35], v[50:57], v[178:181], v212, v212 op_sel_hi:[0,0,0]
	v_mfma_scale_f32_16x16x128_f8f6f4 v[182:185], v[28:35], v[58:65], v[182:185], v212, v212 op_sel_hi:[0,0,0]
	v_mfma_scale_f32_16x16x128_f8f6f4 v[22:25], v[28:35], v[66:73], v[22:25], v212, v212 op_sel_hi:[0,0,0]
	s_waitcnt lgkmcnt(0)
	v_mfma_scale_f32_16x16x128_f8f6f4 v[186:189], v[74:81], v[42:49], v[186:189], v212, v212 op_sel_hi:[0,0,0]
	v_mfma_scale_f32_16x16x128_f8f6f4 v[58:61], v[74:81], v[58:65], v[194:197], v212, v212 op_sel_hi:[0,0,0]
	v_mfma_scale_f32_16x16x128_f8f6f4 v[190:193], v[74:81], v[50:57], v[190:193], v212, v212 op_sel_hi:[0,0,0]
	v_mfma_scale_f32_16x16x128_f8f6f4 v[194:197], v[74:81], v[66:73], v[198:201], v212, v212 op_sel_hi:[0,0,0]
	s_mov_b32 m0, s9
	v_lshl_add_u64 v[2:3], v[2:3], 0, s[64:65]
	s_waitcnt vmcnt(0)
	s_waitcnt vmcnt(0)
	s_barrier
	global_load_lds_dwordx4 v[2:3], off
	v_lshl_add_u64 v[2:3], v[4:5], 0, s[64:65]
	s_mov_b32 m0, s4
	s_nop 0
	global_load_lds_dwordx4 v[2:3], off
	v_lshl_add_u64 v[2:3], v[6:7], 0, s[64:65]
	s_mov_b32 m0, s5
	s_nop 0
	global_load_lds_dwordx4 v[2:3], off
	v_lshl_add_u64 v[2:3], v[8:9], 0, s[64:65]
	s_mov_b32 m0, s6
	s_nop 0
	global_load_lds_dwordx4 v[2:3], off
	v_lshl_add_u64 v[2:3], v[10:11], 0, s[64:65]
	s_mov_b32 m0, s7
	s_nop 0
	global_load_lds_dwordx4 v[2:3], off
	v_lshl_add_u64 v[2:3], v[12:13], 0, s[64:65]
	s_mov_b32 m0, s8
	s_nop 0
	global_load_lds_dwordx4 v[2:3], off
	v_lshl_add_u64 v[2:3], v[14:15], 0, s[64:65]
	s_mov_b32 m0, s23
	s_nop 0
	global_load_lds_dwordx4 v[2:3], off
	v_lshl_add_u64 v[2:3], v[16:17], 0, s[64:65]
	s_mov_b32 m0, s25
	s_nop 0
	global_load_lds_dwordx4 v[2:3], off
	ds_read_b128 v[2:5], v0
	ds_read_b128 v[6:9], v18
	ds_read_b128 v[10:13], v19 offset:32768
	ds_read_b128 v[14:17], v20 offset:32768
	ds_read_b128 v[28:31], v19 offset:34816
	ds_read_b128 v[32:35], v20 offset:34816
	ds_read_b128 v[50:53], v19 offset:36864
	ds_read_b128 v[54:57], v20 offset:36864
	ds_read_b128 v[70:73], v19 offset:38912
	ds_read_b128 v[74:77], v20 offset:38912
	s_waitcnt lgkmcnt(0)
	v_mfma_scale_f32_16x16x128_f8f6f4 v[122:125], v[2:9], v[10:17], v[202:205], v212, v212 op_sel_hi:[0,0,0]
	ds_read_b128 v[78:81], v0 offset:2048
	ds_read_b128 v[82:85], v18 offset:2048
	v_mfma_scale_f32_16x16x128_f8f6f4 v[90:93], v[2:9], v[28:35], v[232:235], v212, v212 op_sel_hi:[0,0,0]
	v_mfma_scale_f32_16x16x128_f8f6f4 v[62:65], v[2:9], v[50:57], v[86:89], v212, v212 op_sel_hi:[0,0,0]
	v_mfma_scale_f32_16x16x128_f8f6f4 v[42:45], v[2:9], v[70:77], v[236:239], v212, v212 op_sel_hi:[0,0,0]
	s_waitcnt lgkmcnt(0)
	v_mfma_scale_f32_16x16x128_f8f6f4 v[126:129], v[78:85], v[10:17], v[94:97], v212, v212 op_sel_hi:[0,0,0]
	ds_read_b128 v[2:5], v0 offset:4096
	ds_read_b128 v[6:9], v18 offset:4096
	v_mfma_scale_f32_16x16x128_f8f6f4 v[94:97], v[78:85], v[28:35], v[98:101], v212, v212 op_sel_hi:[0,0,0]
	v_mfma_scale_f32_16x16x128_f8f6f4 v[66:69], v[78:85], v[50:57], v[102:105], v212, v212 op_sel_hi:[0,0,0]
	v_mfma_scale_f32_16x16x128_f8f6f4 v[46:49], v[78:85], v[70:77], v[106:109], v212, v212 op_sel_hi:[0,0,0]
	s_waitcnt lgkmcnt(0)
	v_mfma_scale_f32_16x16x128_f8f6f4 v[130:133], v[2:9], v[10:17], v[110:113], v212, v212 op_sel_hi:[0,0,0]
	ds_read_b128 v[78:81], v0 offset:6144
	ds_read_b128 v[82:85], v18 offset:6144
	v_mfma_scale_f32_16x16x128_f8f6f4 v[134:137], v[2:9], v[28:35], v[114:117], v212, v212 op_sel_hi:[0,0,0]
	v_mfma_scale_f32_16x16x128_f8f6f4 v[98:101], v[2:9], v[50:57], v[118:121], v212, v212 op_sel_hi:[0,0,0]
	v_mfma_scale_f32_16x16x128_f8f6f4 v[102:105], v[2:9], v[70:77], v[240:243], v212, v212 op_sel_hi:[0,0,0]
	s_waitcnt lgkmcnt(0)
; #define WAIT_V0() asm volatile("s_waitcnt vmcnt(0)" ::: "memory")
; DI void gemm_core_q(const int tid, const u8* __restrict__ Wb, const u8* __restrict__ Xb, f32x4 (&acc)[8][4]) {
;     ...
;     for (int m = 0; m < 8; ++m) {
;       const i32x4 lo = *(const i32x4*)(pa + m * 2048);
;       const i32x4 hi = *(const i32x4*)(pa2 + m * 2048);
;       At[m] = __builtin_shufflevector(lo, hi, 0, 1, 2, 3, 4, 5, 6, 7);
;     }
; #pragma unroll
;     for (int m = 0; m < 8; ++m)
; #pragma unroll
;       for (int n = 0; n < 4; ++n)
;         acc[m][n] = __builtin_amdgcn_mfma_scale_f32_16x16x128_f8f6f4(At[m], Bf[n], acc[m][n], 0, 0, 0, 0x7F7F7F7F, 0, 0x7F7F7F7F);
;     __builtin_amdgcn_sched_group_barrier(0x100, 10, 0);
; #pragma unroll
;     for (int m = 0; m < 8; ++m) {
;       __builtin_amdgcn_sched_group_barrier(0x008, 1, 0);
;       if (m < 7) __builtin_amdgcn_sched_group_barrier(0x100, 2, 0);
;       __builtin_amdgcn_sched_group_barrier(0x008, 3, 0);
;     }
;     __builtin_amdgcn_sched_barrier(0);
;     WAIT_V0(); __syncthreads();
	v_mfma_scale_f32_16x16x128_f8f6f4 v[146:149], v[78:85], v[10:17], v[244:247], v212, v212 op_sel_hi:[0,0,0]
	ds_read_b128 v[2:5], v0 offset:8192
	ds_read_b128 v[6:9], v18 offset:8192
	v_mfma_scale_f32_16x16x128_f8f6f4 v[138:141], v[78:85], v[28:35], v[248:251], v212, v212 op_sel_hi:[0,0,0]
	v_mfma_scale_f32_16x16x128_f8f6f4 v[202:205], v[78:85], v[50:57], v[206:209], v212, v212 op_sel_hi:[0,0,0]
	v_mfma_scale_f32_16x16x128_f8f6f4 v[206:209], v[78:85], v[70:77], v[222:225], v212, v212 op_sel_hi:[0,0,0]
	s_waitcnt lgkmcnt(0)
	v_mfma_scale_f32_16x16x128_f8f6f4 v[150:153], v[2:9], v[10:17], v[142:145], v212, v212 op_sel_hi:[0,0,0]
	ds_read_b128 v[78:81], v0 offset:10240
	ds_read_b128 v[82:85], v18 offset:10240
	v_mfma_scale_f32_16x16x128_f8f6f4 v[110:113], v[2:9], v[28:35], v[216:219], v212, v212 op_sel_hi:[0,0,0]
	v_mfma_scale_f32_16x16x128_f8f6f4 v[142:145], v[2:9], v[50:57], v[226:229], v212, v212 op_sel_hi:[0,0,0]
	v_mfma_scale_f32_16x16x128_f8f6f4 v[86:89], v[2:9], v[70:77], v[154:157], v212, v212 op_sel_hi:[0,0,0]
	s_waitcnt lgkmcnt(0)
	v_mfma_scale_f32_16x16x128_f8f6f4 v[114:117], v[78:85], v[10:17], v[158:161], v212, v212 op_sel_hi:[0,0,0]
	ds_read_b128 v[2:5], v0 offset:12288
	ds_read_b128 v[6:9], v18 offset:12288
	v_mfma_scale_f32_16x16x128_f8f6f4 v[216:219], v[78:85], v[28:35], v[162:165], v212, v212 op_sel_hi:[0,0,0]
	v_mfma_scale_f32_16x16x128_f8f6f4 v[106:109], v[78:85], v[50:57], v[166:169], v212, v212 op_sel_hi:[0,0,0]
	v_mfma_scale_f32_16x16x128_f8f6f4 v[118:121], v[78:85], v[70:77], v[170:173], v212, v212 op_sel_hi:[0,0,0]
	s_waitcnt lgkmcnt(0)
	v_mfma_scale_f32_16x16x128_f8f6f4 v[222:225], v[2:9], v[10:17], v[174:177], v212, v212 op_sel_hi:[0,0,0]
	ds_read_b128 v[78:81], v0 offset:14336
	ds_read_b128 v[82:85], v18 offset:14336
	v_mfma_scale_f32_16x16x128_f8f6f4 v[226:229], v[2:9], v[28:35], v[178:181], v212, v212 op_sel_hi:[0,0,0]
	v_mfma_scale_f32_16x16x128_f8f6f4 v[178:181], v[2:9], v[50:57], v[182:185], v212, v212 op_sel_hi:[0,0,0]
	v_mfma_scale_f32_16x16x128_f8f6f4 v[198:201], v[2:9], v[70:77], v[22:25], v212, v212 op_sel_hi:[0,0,0]
	s_waitcnt lgkmcnt(0)
	v_mfma_scale_f32_16x16x128_f8f6f4 v[240:243], v[78:85], v[10:17], v[186:189], v212, v212 op_sel_hi:[0,0,0]
	v_mfma_scale_f32_16x16x128_f8f6f4 v[28:31], v[78:85], v[28:35], v[190:193], v212, v212 op_sel_hi:[0,0,0]
	v_mfma_scale_f32_16x16x128_f8f6f4 v[22:25], v[78:85], v[50:57], v[58:61], v212, v212 op_sel_hi:[0,0,0]
	v_mfma_scale_f32_16x16x128_f8f6f4 v[34:37], v[78:85], v[70:77], v[194:197], v212, v212 op_sel_hi:[0,0,0]
	s_waitcnt vmcnt(0)
	s_waitcnt vmcnt(0)
	s_barrier
; #define WAIT_V0() asm volatile("s_waitcnt vmcnt(0)" ::: "memory")
; DI void gemm_core_q(const int tid, const u8* __restrict__ Wb, const u8* __restrict__ Xb, f32x4 (&acc)[8][4]) {
;     ...
; #pragma unroll
;     for (int n = 0; n < 4; ++n) {
;       const i32x4 lo = *(const i32x4*)(pb + n * 2048);
;       const i32x4 hi = *(const i32x4*)(pb2 + n * 2048);
;       Bf[n] = __builtin_shufflevector(lo, hi, 0, 1, 2, 3, 4, 5, 6, 7);
;     }
; #pragma unroll
;     for (int m = 0; m < 8; ++m) {
;       const i32x4 lo = *(const i32x4*)(pa + m * 2048);
;       const i32x4 hi = *(const i32x4*)(pa2 + m * 2048);
;       At[m] = __builtin_shufflevector(lo, hi, 0, 1, 2, 3, 4, 5, 6, 7);
;     }
; #pragma unroll
;     for (int m = 0; m < 8; ++m)
; #pragma unroll
;       for (int n = 0; n < 4; ++n)
;         acc[m][n] = __builtin_amdgcn_mfma_scale_f32_16x16x128_f8f6f4(At[m], Bf[n], acc[m][n], 0, 0, 0, 0x7F7F7F7F, 0, 0x7F7F7F7F);
;     __builtin_amdgcn_sched_group_barrier(0x100, 10, 0);
; #pragma unroll
;     for (int m = 0; m < 8; ++m) {
;       __builtin_amdgcn_sched_group_barrier(0x008, 1, 0);
;       if (m < 7) __builtin_amdgcn_sched_group_barrier(0x100, 2, 0);
;       __builtin_amdgcn_sched_group_barrier(0x008, 3, 0);
;     }
;     __builtin_amdgcn_sched_barrier(0);
;     WAIT_V0(); __syncthreads();
; template <int CT>
; DI void phase_g1(int c, int l) {
;     ...
;     if (pn == 18 || pn == 19 || pn == 23 || pn == 24) {
;       u16* gdst = pn >= 23 ? WSU(BG) : WSU(AG);
	ds_read_b128 v[54:57], v41 offset:14336
	ds_read_b128 v[50:53], v38 offset:14336
	ds_read_b128 v[74:77], v41 offset:12288
	ds_read_b128 v[70:73], v38 offset:12288
	ds_read_b128 v[158:161], v41 offset:10240
	ds_read_b128 v[154:157], v38 offset:10240
	ds_read_b128 v[6:9], v41 offset:8192
	ds_read_b128 v[2:5], v38 offset:8192
	ds_read_b128 v[166:169], v41 offset:6144
	ds_read_b128 v[162:165], v38 offset:6144
	ds_read_b128 v[14:17], v40 offset:4096
	ds_read_b128 v[10:13], v21
	s_waitcnt lgkmcnt(0)
	v_mfma_scale_f32_16x16x128_f8f6f4 v[18:21], v[50:57], v[10:17], v[22:25], v212, v212 op_sel_hi:[0,0,0]
	v_mfma_scale_f32_16x16x128_f8f6f4 v[22:25], v[70:77], v[10:17], v[178:181], v212, v212 op_sel_hi:[0,0,0]
	ds_read_b128 v[182:185], v40 offset:2048
	s_nop 5
	ds_read_b128 v[178:181], v26
	s_waitcnt lgkmcnt(0)
	v_mfma_scale_f32_16x16x128_f8f6f4 v[110:113], v[2:9], v[178:185], v[110:113], v212, v212 op_sel_hi:[0,0,0]
	v_mfma_scale_f32_16x16x128_f8f6f4 v[58:61], v[154:161], v[10:17], v[106:109], v212, v212 op_sel_hi:[0,0,0]
	ds_read_b128 v[174:177], v41 offset:4096
	ds_read_b128 v[170:173], v38 offset:4096
	v_mfma_scale_f32_16x16x128_f8f6f4 v[78:81], v[50:57], v[178:185], v[28:31], v212, v212 op_sel_hi:[0,0,0]
	ds_read_b128 v[190:193], v40 offset:6144
	ds_read_b128 v[186:189], v27
	s_waitcnt lgkmcnt(0)
	v_mfma_scale_f32_16x16x128_f8f6f4 v[30:33], v[70:77], v[186:193], v[198:201], v212, v212 op_sel_hi:[0,0,0]
	v_mfma_scale_f32_16x16x128_f8f6f4 v[26:29], v[50:57], v[186:193], v[34:37], v212, v212 op_sel_hi:[0,0,0]
	s_nop 5
	ds_read_b128 v[198:201], v41 offset:2048
	ds_read_b128 v[194:197], v38 offset:2048
	ds_read_b128 v[236:239], v40
	ds_read_b128 v[232:235], v39
	s_waitcnt lgkmcnt(0)
	v_mfma_scale_f32_16x16x128_f8f6f4 v[106:109], v[50:57], v[232:239], v[240:243], v212, v212 op_sel_hi:[0,0,0]
	v_mfma_scale_f32_16x16x128_f8f6f4 v[50:53], v[194:201], v[186:193], v[46:49], v212, v212 op_sel_hi:[0,0,0]
	ds_read_b128 v[244:247], v41
	s_nop 4
	ds_read_b128 v[240:243], v38
	v_mfma_scale_f32_16x16x128_f8f6f4 v[46:49], v[170:177], v[186:193], v[102:105], v212, v212 op_sel_hi:[0,0,0]
	s_waitcnt lgkmcnt(0)
	v_mfma_scale_f32_16x16x128_f8f6f4 v[102:105], v[240:247], v[178:185], v[90:93], v212, v212 op_sel_hi:[0,0,0]
	v_mfma_scale_f32_16x16x128_f8f6f4 v[90:93], v[162:169], v[178:185], v[138:141], v212, v212 op_sel_hi:[0,0,0]
	v_mfma_scale_f32_16x16x128_f8f6f4 v[138:141], v[240:247], v[232:239], v[122:125], v212, v212 op_sel_hi:[0,0,0]
	v_mfma_scale_f32_16x16x128_f8f6f4 v[122:125], v[2:9], v[232:239], v[150:153], v212, v212 op_sel_hi:[0,0,0]
	v_mfma_scale_f32_16x16x128_f8f6f4 v[130:133], v[170:177], v[232:239], v[130:133], v212, v212 op_sel_hi:[0,0,0]
	v_mfma_scale_f32_16x16x128_f8f6f4 v[82:85], v[70:77], v[178:185], v[226:229], v212, v212 op_sel_hi:[0,0,0]
	v_mfma_scale_f32_16x16x128_f8f6f4 v[34:37], v[154:161], v[186:193], v[118:121], v212, v212 op_sel_hi:[0,0,0]
	v_mfma_scale_f32_16x16x128_f8f6f4 v[118:121], v[154:161], v[232:239], v[114:117], v212, v212 op_sel_hi:[0,0,0]
	v_mfma_scale_f32_16x16x128_f8f6f4 v[114:117], v[70:77], v[232:239], v[222:225], v212, v212 op_sel_hi:[0,0,0]
	v_mfma_scale_f32_16x16x128_f8f6f4 v[70:73], v[194:201], v[10:17], v[66:69], v212, v212 op_sel_hi:[0,0,0]
	v_mfma_scale_f32_16x16x128_f8f6f4 v[66:69], v[170:177], v[10:17], v[98:101], v212, v212 op_sel_hi:[0,0,0]
	v_mfma_scale_f32_16x16x128_f8f6f4 v[98:101], v[194:201], v[178:185], v[94:97], v212, v212 op_sel_hi:[0,0,0]
	v_mfma_scale_f32_16x16x128_f8f6f4 v[94:97], v[170:177], v[178:185], v[134:137], v212, v212 op_sel_hi:[0,0,0]
	v_mfma_scale_f32_16x16x128_f8f6f4 v[134:137], v[194:201], v[232:239], v[126:129], v212, v212 op_sel_hi:[0,0,0]
	v_mfma_scale_f32_16x16x128_f8f6f4 v[126:129], v[162:169], v[232:239], v[146:149], v212, v212 op_sel_hi:[0,0,0]
	v_mfma_scale_f32_16x16x128_f8f6f4 v[74:77], v[240:247], v[10:17], v[62:65], v212, v212 op_sel_hi:[0,0,0]
	v_mfma_scale_f32_16x16x128_f8f6f4 v[62:65], v[162:169], v[10:17], v[202:205], v212, v212 op_sel_hi:[0,0,0]
	v_mfma_scale_f32_16x16x128_f8f6f4 v[38:41], v[2:9], v[186:193], v[86:89], v212, v212 op_sel_hi:[0,0,0]
	v_mfma_scale_f32_16x16x128_f8f6f4 v[86:89], v[154:161], v[178:185], v[216:219], v212, v212 op_sel_hi:[0,0,0]
	v_mfma_scale_f32_16x16x128_f8f6f4 v[54:57], v[240:247], v[186:193], v[42:45], v212, v212 op_sel_hi:[0,0,0]
	v_mfma_scale_f32_16x16x128_f8f6f4 v[42:45], v[162:169], v[186:193], v[206:209], v212, v212 op_sel_hi:[0,0,0]
	v_mfma_scale_f32_16x16x128_f8f6f4 v[2:5], v[2:9], v[10:17], v[142:145], v212, v212 op_sel_hi:[0,0,0]
	s_waitcnt vmcnt(0)
	v_mov_b32_e32 v14, v210
	s_barrier
	s_cmp_lt_i32 s84, 23
	v_readfirstlane_b32 s23, v14
	s_cbranch_scc1 .LBB0_498
	s_cmp_gt_i32 s84, 24
	s_mov_b64 s[4:5], -1
	s_cselect_b64 s[6:7], -1, 0
	s_cbranch_execz .LBB0_499
	s_branch .LBB0_500

; #define LOAD_PARAMS() KParams kq_ = (KParams)__builtin_amdgcn_kernarg_segment_ptr(); asm volatile("" : "+s"(kq_)); const Params p = *kq_
; template <int CT>
; __global__ void __launch_bounds__(NTHREADS) mega_kernel(Params p) {
;     ...
;   for (int ph = 0; ph < nph; ++ph) {
;     run_phase<CT>(ph);
;     if (ph + 1 < nph) {
;       LOAD_PARAMS();
;       xcd_barrier((unsigned*)(p.ws + WS<CT>::bar), x, nloc, nx, k);
;       ++k;
;     }
;   }
.LBB0_726:
	s_endpgm
	s_nop 0
	s_nop 0
	s_nop 0
	s_nop 0
	s_nop 0
	s_nop 0
	s_nop 0
	s_nop 0
	s_nop 0
	s_nop 0
	s_nop 0
	s_nop 0
	s_nop 0
	s_nop 0
	s_endpgm
